# k-loops: the duplicate s_waitcnt lgkmcnt(0) right behind each barrier (already waited in front of it) removed, 52 sites
# baseline (speedup 1.0000x reference)
; #define PG8_STAGE(bufoff, gbase, voff) do { _Pragma("unroll") for (int _i = 0; _i < 2; ++_i) \
;         __builtin_amdgcn_global_load_lds((const unsigned*)((const char*)(gbase) + (voff)[_i]), (PG8_LAS unsigned*)(lds + (bufoff) + ldsw + _i * 8192), 16, 0, 0); } while (0)
; #define PG8_LDA(dst, b, h) do { _Pragma("unroll") for (int m = 0; m < 4; ++m) _Pragma("unroll") for (int k = 0; k < 2; ++k) dst[m][k] = *(const PG8_LAS bf16x8*)(lds + PG8_SA(b, h) + aoff + m * 2048 + k * 1024); } while (0)
; #define PG8_LDB(dst, b, h) do { _Pragma("unroll") for (int n = 0; n < 2; ++n) _Pragma("unroll") for (int k = 0; k < 2; ++k) dst[n][k] = *(const PG8_LAS bf16x8*)(lds + PG8_SB(b, h) + boff + n * 2048 + k * 1024); } while (0)
; #define PG8_MMA(ai, bj, At, Bt) do { __builtin_amdgcn_s_setprio(1); _Pragma("unroll") for (int m = 0; m < 4; ++m) _Pragma("unroll") for (int n = 0; n < 2; ++n) _Pragma("unroll") for (int k = 0; k < 2; ++k) \
;         acc[ai][bj][m][n] = __builtin_amdgcn_mfma_f32_16x16x32_bf16(Bt[n][k], At[m][k], acc[ai][bj][m][n], 0, 0, 0); __builtin_amdgcn_s_setprio(0); } while (0)
; #define PG8_WAIT_V(n) asm volatile("s_waitcnt vmcnt(" #n ")" ::: "memory")
; #define PG8_BAR __builtin_amdgcn_s_barrier()
; template <class Epi, class Sched, bool ALIGN_EPI = false, bool SP2 = false>
; __device__ __forceinline__ void gemm_phase(PG8_LAS unsigned char* lds, const Gemm g, const Sched& S, const Epi& E) {
;     ...
;         for (int t = 0; t < nt; t += 2) {
;             const bool last = (t == nt - 2);
;             const char* a1 = cA + (size_t)(t + 1) * kstep;
;             const char* a2 = last ? nA : cA + (size_t)(t + 2) * kstep; const char* b2 = last ? nB : cB + (size_t)(t + 2) * kstep;
;             const char* a3 = a2 + kstep; const char* b3 = b2 + kstep;
;             if (last && has_next) S.a_ready(nxt);
;             if constexpr (SP2) {
;             PG8_LDB(B0, 0, 0); PG8_LDB(B1, 0, 1); PG8_SCHED; PG8_LDA(At, 0, 0); PG8_STAGE(PG8_SA(1, 1), a1 + hstep, voffA);
;             PG8_WAIT_V(8); PG8_WAIT_L(0); PG8_BAR; PG8_MMA(0, 0, At, B0); PG8_MMA(0, 1, At, B1); PG8_BAR; PG8_SCHED;
;             PG8_LDA(At, 0, 1); PG8_STAGE(PG8_SB(0, 0), b2, voffB); PG8_STAGE(PG8_SB(0, 1), b2 + hstep, voffB); PG8_STAGE(PG8_SA(0, 0), a2, voffA);
;             PG8_WAIT_V(8); PG8_WAIT_L(0); PG8_BAR; PG8_MMA(1, 0, At, B0); PG8_MMA(1, 1, At, B1); PG8_BAR; PG8_SCHED;
.LBB0_218:
	ds_read_b128 v[148:151], v157
	ds_read_b128 v[166:169], v157 offset:1024
	ds_read_b128 v[172:175], v157 offset:2048
	ds_read_b128 v[176:179], v157 offset:3072
	ds_read_b128 v[180:183], v158
	ds_read_b128 v[184:187], v158 offset:1024
	ds_read_b128 v[188:191], v158 offset:2048
	ds_read_b128 v[196:199], v158 offset:3072
	s_add_u32 s6, s52, 0xfffc0080
	s_addc_u32 s7, s53, -1
	s_cmp_eq_u32 s72, 12
	s_cselect_b32 s57, s4, s7
	s_cselect_b32 s56, s41, s6
	s_cselect_b32 s55, s39, s33
	s_cselect_b32 s54, s78, s79
	s_add_i32 m0, s37, 0xc000
	ds_read_b128 v[200:203], v159
	ds_read_b128 v[204:207], v159 offset:1024
	ds_read_b128 v[208:211], v159 offset:2048
	ds_read_b128 v[212:215], v159 offset:3072
	ds_read_b128 v[216:219], v159 offset:4096
	ds_read_b128 v[220:223], v159 offset:5120
	ds_read_b128 v[224:227], v159 offset:6144
	ds_read_b128 v[228:231], v159 offset:7168
	global_load_lds_dwordx4 v140, s[52:53]
	s_add_i32 m0, s37, 0xe000
	s_nop 0
	global_load_lds_dwordx4 v142, s[52:53]
	s_waitcnt vmcnt(8)
	s_waitcnt lgkmcnt(0)
	s_barrier
	v_mfma_f32_16x16x32_bf16 v[124:127], v[148:151], v[200:203], v[124:127]
	v_mfma_f32_16x16x32_bf16 v[116:119], v[172:175], v[200:203], v[116:119]
	v_mfma_f32_16x16x32_bf16 v[108:111], v[148:151], v[208:211], v[108:111]
	v_mfma_f32_16x16x32_bf16 v[100:103], v[172:175], v[208:211], v[100:103]
	v_mfma_f32_16x16x32_bf16 v[92:95], v[148:151], v[216:219], v[92:95]
	v_mfma_f32_16x16x32_bf16 v[84:87], v[172:175], v[216:219], v[84:87]
	v_mfma_f32_16x16x32_bf16 v[76:79], v[148:151], v[224:227], v[76:79]
	v_mfma_f32_16x16x32_bf16 v[68:71], v[172:175], v[224:227], v[68:71]
	v_mfma_f32_16x16x32_bf16 v[124:127], v[166:169], v[204:207], v[124:127]
	v_mfma_f32_16x16x32_bf16 v[116:119], v[176:179], v[204:207], v[116:119]
	v_mfma_f32_16x16x32_bf16 v[108:111], v[166:169], v[212:215], v[108:111]
	v_mfma_f32_16x16x32_bf16 v[100:103], v[176:179], v[212:215], v[100:103]
	v_mfma_f32_16x16x32_bf16 v[92:95], v[166:169], v[220:223], v[92:95]
	v_mfma_f32_16x16x32_bf16 v[84:87], v[176:179], v[220:223], v[84:87]
	v_mfma_f32_16x16x32_bf16 v[76:79], v[166:169], v[228:231], v[76:79]
	v_mfma_f32_16x16x32_bf16 v[68:71], v[176:179], v[228:231], v[68:71]
	v_mfma_f32_16x16x32_bf16 v[120:123], v[180:183], v[200:203], v[120:123]
	v_mfma_f32_16x16x32_bf16 v[112:115], v[188:191], v[200:203], v[112:115]
	v_mfma_f32_16x16x32_bf16 v[104:107], v[180:183], v[208:211], v[104:107]
	v_mfma_f32_16x16x32_bf16 v[96:99], v[188:191], v[208:211], v[96:99]
	v_mfma_f32_16x16x32_bf16 v[88:91], v[180:183], v[216:219], v[88:91]
	v_mfma_f32_16x16x32_bf16 v[80:83], v[188:191], v[216:219], v[80:83]
	v_mfma_f32_16x16x32_bf16 v[72:75], v[180:183], v[224:227], v[72:75]
	v_mfma_f32_16x16x32_bf16 v[64:67], v[188:191], v[224:227], v[64:67]
	v_mfma_f32_16x16x32_bf16 v[120:123], v[184:187], v[204:207], v[120:123]
	v_mfma_f32_16x16x32_bf16 v[112:115], v[196:199], v[204:207], v[112:115]
	v_mfma_f32_16x16x32_bf16 v[104:107], v[184:187], v[212:215], v[104:107]
	v_mfma_f32_16x16x32_bf16 v[96:99], v[196:199], v[212:215], v[96:99]
	v_mfma_f32_16x16x32_bf16 v[88:91], v[184:187], v[220:223], v[88:91]
	v_mfma_f32_16x16x32_bf16 v[80:83], v[196:199], v[220:223], v[80:83]
	v_mfma_f32_16x16x32_bf16 v[72:75], v[184:187], v[228:231], v[72:75]
	v_mfma_f32_16x16x32_bf16 v[64:67], v[196:199], v[228:231], v[64:67]
	s_barrier
	s_add_i32 s6, s69, s36
	s_mov_b32 m0, s6
	ds_read_b128 v[200:203], v159 offset:16384
	ds_read_b128 v[204:207], v159 offset:17408
	ds_read_b128 v[208:211], v159 offset:18432
	ds_read_b128 v[212:215], v159 offset:19456
	ds_read_b128 v[216:219], v159 offset:20480
	ds_read_b128 v[220:223], v159 offset:21504
	ds_read_b128 v[224:227], v159 offset:22528
	ds_read_b128 v[228:231], v159 offset:23552
	global_load_lds_dwordx4 v136, s[54:55]
	s_add_i32 m0, s6, 0x2000
	s_add_u32 s6, s54, 0x40000
	s_addc_u32 s7, s55, 0
	s_add_i32 s73, s74, s36
	global_load_lds_dwordx4 v132, s[54:55]
	s_mov_b32 m0, s73
	s_nop 0
	global_load_lds_dwordx4 v136, s[6:7]
	s_add_i32 m0, s73, 0x2000
	s_nop 0
	global_load_lds_dwordx4 v132, s[6:7]
	s_mov_b32 m0, s37
	s_nop 0
	global_load_lds_dwordx4 v138, s[56:57]
	s_mov_b32 m0, s59
	s_nop 0
	global_load_lds_dwordx4 v134, s[56:57]
	s_waitcnt vmcnt(8)
	s_waitcnt lgkmcnt(0)
	s_barrier
	v_mfma_f32_16x16x32_bf16 v[60:63], v[148:151], v[200:203], v[60:63]
	v_mfma_f32_16x16x32_bf16 v[52:55], v[172:175], v[200:203], v[52:55]
	v_mfma_f32_16x16x32_bf16 v[44:47], v[148:151], v[208:211], v[44:47]
	v_mfma_f32_16x16x32_bf16 v[36:39], v[172:175], v[208:211], v[36:39]
	v_mfma_f32_16x16x32_bf16 v[28:31], v[148:151], v[216:219], v[28:31]
	v_mfma_f32_16x16x32_bf16 v[20:23], v[172:175], v[216:219], v[20:23]
	v_mfma_f32_16x16x32_bf16 v[12:15], v[148:151], v[224:227], v[12:15]
	v_mfma_f32_16x16x32_bf16 v[4:7], v[172:175], v[224:227], v[4:7]
	v_mfma_f32_16x16x32_bf16 v[60:63], v[166:169], v[204:207], v[60:63]
	v_mfma_f32_16x16x32_bf16 v[52:55], v[176:179], v[204:207], v[52:55]
	v_mfma_f32_16x16x32_bf16 v[44:47], v[166:169], v[212:215], v[44:47]
	v_mfma_f32_16x16x32_bf16 v[36:39], v[176:179], v[212:215], v[36:39]
	v_mfma_f32_16x16x32_bf16 v[28:31], v[166:169], v[220:223], v[28:31]
	v_mfma_f32_16x16x32_bf16 v[20:23], v[176:179], v[220:223], v[20:23]
	v_mfma_f32_16x16x32_bf16 v[12:15], v[166:169], v[228:231], v[12:15]
	v_mfma_f32_16x16x32_bf16 v[4:7], v[176:179], v[228:231], v[4:7]
	v_mfma_f32_16x16x32_bf16 v[56:59], v[180:183], v[200:203], v[56:59]
	v_mfma_f32_16x16x32_bf16 v[48:51], v[188:191], v[200:203], v[48:51]
	v_mfma_f32_16x16x32_bf16 v[40:43], v[180:183], v[208:211], v[40:43]
	v_mfma_f32_16x16x32_bf16 v[32:35], v[188:191], v[208:211], v[32:35]
	v_mfma_f32_16x16x32_bf16 v[24:27], v[180:183], v[216:219], v[24:27]
	v_mfma_f32_16x16x32_bf16 v[16:19], v[188:191], v[216:219], v[16:19]
	v_mfma_f32_16x16x32_bf16 v[8:11], v[180:183], v[224:227], v[8:11]
	v_mfma_f32_16x16x32_bf16 v[0:3], v[188:191], v[224:227], v[0:3]
	v_mfma_f32_16x16x32_bf16 v[56:59], v[184:187], v[204:207], v[56:59]
	v_mfma_f32_16x16x32_bf16 v[48:51], v[196:199], v[204:207], v[48:51]
	v_mfma_f32_16x16x32_bf16 v[40:43], v[184:187], v[212:215], v[40:43]
	v_mfma_f32_16x16x32_bf16 v[32:35], v[196:199], v[212:215], v[32:35]
	v_mfma_f32_16x16x32_bf16 v[24:27], v[184:187], v[220:223], v[24:27]
	v_mfma_f32_16x16x32_bf16 v[16:19], v[196:199], v[220:223], v[16:19]
	v_mfma_f32_16x16x32_bf16 v[8:11], v[184:187], v[228:231], v[8:11]
	v_mfma_f32_16x16x32_bf16 v[0:3], v[196:199], v[228:231], v[0:3]
	s_barrier
; #define PG8_STAGE(bufoff, gbase, voff) do { _Pragma("unroll") for (int _i = 0; _i < 2; ++_i) \
;         __builtin_amdgcn_global_load_lds((const unsigned*)((const char*)(gbase) + (voff)[_i]), (PG8_LAS unsigned*)(lds + (bufoff) + ldsw + _i * 8192), 16, 0, 0); } while (0)
; #define PG8_LDA(dst, b, h) do { _Pragma("unroll") for (int m = 0; m < 4; ++m) _Pragma("unroll") for (int k = 0; k < 2; ++k) dst[m][k] = *(const PG8_LAS bf16x8*)(lds + PG8_SA(b, h) + aoff + m * 2048 + k * 1024); } while (0)
; #define PG8_LDB(dst, b, h) do { _Pragma("unroll") for (int n = 0; n < 2; ++n) _Pragma("unroll") for (int k = 0; k < 2; ++k) dst[n][k] = *(const PG8_LAS bf16x8*)(lds + PG8_SB(b, h) + boff + n * 2048 + k * 1024); } while (0)
; #define PG8_MMA(ai, bj, At, Bt) do { __builtin_amdgcn_s_setprio(1); _Pragma("unroll") for (int m = 0; m < 4; ++m) _Pragma("unroll") for (int n = 0; n < 2; ++n) _Pragma("unroll") for (int k = 0; k < 2; ++k) \
;         acc[ai][bj][m][n] = __builtin_amdgcn_mfma_f32_16x16x32_bf16(Bt[n][k], At[m][k], acc[ai][bj][m][n], 0, 0, 0); __builtin_amdgcn_s_setprio(0); } while (0)
; #define PG8_WAIT_V(n) asm volatile("s_waitcnt vmcnt(" #n ")" ::: "memory")
; #define PG8_WAIT_L(n) asm volatile("s_waitcnt lgkmcnt(" #n ")" ::: "memory")
; #define PG8_BAR __builtin_amdgcn_s_barrier()
; #define PG8_SCHED __builtin_amdgcn_sched_barrier(0)
; template <class Epi, class Sched, bool ALIGN_EPI = false, bool SP2 = false>
; __device__ __forceinline__ void gemm_phase(PG8_LAS unsigned char* lds, const Gemm g, const Sched& S, const Epi& E) {
;     ...
;             PG8_LDB(B0, 1, 0); PG8_LDB(B1, 1, 1); PG8_SCHED; PG8_LDA(At, 1, 0); PG8_STAGE(PG8_SA(0, 1), a2 + hstep, voffA);
;             PG8_WAIT_V(8); PG8_WAIT_L(0); PG8_BAR; PG8_MMA(0, 0, At, B0); PG8_MMA(0, 1, At, B1); PG8_BAR; PG8_SCHED;
;             PG8_LDA(At, 1, 1); PG8_STAGE(PG8_SB(1, 0), b3, voffB); PG8_STAGE(PG8_SB(1, 1), b3 + hstep, voffB); PG8_STAGE(PG8_SA(1, 0), a3, voffA);
;             PG8_WAIT_V(8); PG8_WAIT_L(0); PG8_BAR; PG8_MMA(1, 0, At, B0); PG8_MMA(1, 1, At, B1); PG8_BAR; PG8_SCHED;
	s_add_i32 s73, 0, 0x18000
	v_add_u32_e32 v161, s73, v154
	s_add_i32 s80, 0, 0x1c000
	ds_read_b128 v[148:151], v161
	ds_read_b128 v[166:169], v161 offset:1024
	ds_read_b128 v[172:175], v161 offset:2048
	ds_read_b128 v[176:179], v161 offset:3072
	v_add_u32_e32 v161, s80, v154
	ds_read_b128 v[180:183], v161
	ds_read_b128 v[184:187], v161 offset:1024
	ds_read_b128 v[188:191], v161 offset:2048
	ds_read_b128 v[196:199], v161 offset:3072
	s_add_u32 s6, s56, 0x40000
	s_addc_u32 s7, s57, 0
	s_mov_b32 m0, s60
	ds_read_b128 v[200:203], v159 offset:32768
	ds_read_b128 v[204:207], v159 offset:33792
	ds_read_b128 v[208:211], v159 offset:34816
	ds_read_b128 v[212:215], v159 offset:35840
	ds_read_b128 v[216:219], v159 offset:36864
	ds_read_b128 v[220:223], v159 offset:37888
	ds_read_b128 v[224:227], v159 offset:38912
	ds_read_b128 v[228:231], v159 offset:39936
	global_load_lds_dwordx4 v138, s[6:7]
	s_mov_b32 m0, s61
	s_nop 0
	global_load_lds_dwordx4 v134, s[6:7]
	s_waitcnt vmcnt(8)
	s_waitcnt lgkmcnt(0)
	s_barrier
	v_mfma_f32_16x16x32_bf16 v[124:127], v[148:151], v[200:203], v[124:127]
	v_mfma_f32_16x16x32_bf16 v[116:119], v[172:175], v[200:203], v[116:119]
	v_mfma_f32_16x16x32_bf16 v[108:111], v[148:151], v[208:211], v[108:111]
	v_mfma_f32_16x16x32_bf16 v[100:103], v[172:175], v[208:211], v[100:103]
	v_mfma_f32_16x16x32_bf16 v[92:95], v[148:151], v[216:219], v[92:95]
	v_mfma_f32_16x16x32_bf16 v[84:87], v[172:175], v[216:219], v[84:87]
	v_mfma_f32_16x16x32_bf16 v[76:79], v[148:151], v[224:227], v[76:79]
	v_mfma_f32_16x16x32_bf16 v[68:71], v[172:175], v[224:227], v[68:71]
	v_mfma_f32_16x16x32_bf16 v[124:127], v[166:169], v[204:207], v[124:127]
	v_mfma_f32_16x16x32_bf16 v[116:119], v[176:179], v[204:207], v[116:119]
	v_mfma_f32_16x16x32_bf16 v[108:111], v[166:169], v[212:215], v[108:111]
	v_mfma_f32_16x16x32_bf16 v[100:103], v[176:179], v[212:215], v[100:103]
	v_mfma_f32_16x16x32_bf16 v[92:95], v[166:169], v[220:223], v[92:95]
	v_mfma_f32_16x16x32_bf16 v[84:87], v[176:179], v[220:223], v[84:87]
	v_mfma_f32_16x16x32_bf16 v[76:79], v[166:169], v[228:231], v[76:79]
	v_mfma_f32_16x16x32_bf16 v[68:71], v[176:179], v[228:231], v[68:71]
	v_mfma_f32_16x16x32_bf16 v[120:123], v[180:183], v[200:203], v[120:123]
	v_mfma_f32_16x16x32_bf16 v[112:115], v[188:191], v[200:203], v[112:115]
	v_mfma_f32_16x16x32_bf16 v[104:107], v[180:183], v[208:211], v[104:107]
	v_mfma_f32_16x16x32_bf16 v[96:99], v[188:191], v[208:211], v[96:99]
	v_mfma_f32_16x16x32_bf16 v[88:91], v[180:183], v[216:219], v[88:91]
	v_mfma_f32_16x16x32_bf16 v[80:83], v[188:191], v[216:219], v[80:83]
	v_mfma_f32_16x16x32_bf16 v[72:75], v[180:183], v[224:227], v[72:75]
	v_mfma_f32_16x16x32_bf16 v[64:67], v[188:191], v[224:227], v[64:67]
	v_mfma_f32_16x16x32_bf16 v[120:123], v[184:187], v[204:207], v[120:123]
	v_mfma_f32_16x16x32_bf16 v[112:115], v[196:199], v[204:207], v[112:115]
	v_mfma_f32_16x16x32_bf16 v[104:107], v[184:187], v[212:215], v[104:107]
	v_mfma_f32_16x16x32_bf16 v[96:99], v[196:199], v[212:215], v[96:99]
	v_mfma_f32_16x16x32_bf16 v[88:91], v[184:187], v[220:223], v[88:91]
	v_mfma_f32_16x16x32_bf16 v[80:83], v[196:199], v[220:223], v[80:83]
	v_mfma_f32_16x16x32_bf16 v[72:75], v[184:187], v[228:231], v[72:75]
	v_mfma_f32_16x16x32_bf16 v[64:67], v[196:199], v[228:231], v[64:67]
	s_barrier
	s_add_i32 s6, s73, s36
	s_add_u32 s98, s54, 0x80
	s_addc_u32 s99, s55, 0
	s_add_u32 s100, s56, 0x80
	s_addc_u32 s101, s57, 0
	s_mov_b32 m0, s6
	ds_read_b128 v[200:203], v159 offset:49152
	ds_read_b128 v[204:207], v159 offset:50176
	ds_read_b128 v[208:211], v159 offset:51200
	ds_read_b128 v[212:215], v159 offset:52224
	ds_read_b128 v[216:219], v159 offset:53248
	ds_read_b128 v[220:223], v159 offset:54272
	ds_read_b128 v[224:227], v159 offset:55296
	ds_read_b128 v[228:231], v159 offset:56320
	global_load_lds_dwordx4 v136, s[98:99]
	s_add_i32 m0, s6, 0x2000
	s_add_u32 s6, s54, 0x40080
	s_addc_u32 s7, s55, 0
	s_add_i32 s54, s80, s36
	global_load_lds_dwordx4 v132, s[98:99]
	s_mov_b32 m0, s54
	s_nop 0
	global_load_lds_dwordx4 v136, s[6:7]
	s_add_i32 m0, s54, 0x2000
	s_nop 0
	global_load_lds_dwordx4 v132, s[6:7]
	s_mov_b32 m0, s67
	s_nop 0
	global_load_lds_dwordx4 v138, s[100:101]
	s_mov_b32 m0, s68
	s_nop 0
	global_load_lds_dwordx4 v134, s[100:101]
	s_waitcnt vmcnt(8)
	s_waitcnt lgkmcnt(0)
	s_barrier
	v_mfma_f32_16x16x32_bf16 v[60:63], v[148:151], v[200:203], v[60:63]
	v_mfma_f32_16x16x32_bf16 v[52:55], v[172:175], v[200:203], v[52:55]
	v_mfma_f32_16x16x32_bf16 v[44:47], v[148:151], v[208:211], v[44:47]
	v_mfma_f32_16x16x32_bf16 v[36:39], v[172:175], v[208:211], v[36:39]
	v_mfma_f32_16x16x32_bf16 v[28:31], v[148:151], v[216:219], v[28:31]
	v_mfma_f32_16x16x32_bf16 v[20:23], v[172:175], v[216:219], v[20:23]
	v_mfma_f32_16x16x32_bf16 v[12:15], v[148:151], v[224:227], v[12:15]
	v_mfma_f32_16x16x32_bf16 v[4:7], v[172:175], v[224:227], v[4:7]
	v_mfma_f32_16x16x32_bf16 v[60:63], v[166:169], v[204:207], v[60:63]
	v_mfma_f32_16x16x32_bf16 v[52:55], v[176:179], v[204:207], v[52:55]
	v_mfma_f32_16x16x32_bf16 v[44:47], v[166:169], v[212:215], v[44:47]
	v_mfma_f32_16x16x32_bf16 v[36:39], v[176:179], v[212:215], v[36:39]
	v_mfma_f32_16x16x32_bf16 v[28:31], v[166:169], v[220:223], v[28:31]
	v_mfma_f32_16x16x32_bf16 v[20:23], v[176:179], v[220:223], v[20:23]
	v_mfma_f32_16x16x32_bf16 v[12:15], v[166:169], v[228:231], v[12:15]
	v_mfma_f32_16x16x32_bf16 v[4:7], v[176:179], v[228:231], v[4:7]
	v_mfma_f32_16x16x32_bf16 v[56:59], v[180:183], v[200:203], v[56:59]
	v_mfma_f32_16x16x32_bf16 v[48:51], v[188:191], v[200:203], v[48:51]
	v_mfma_f32_16x16x32_bf16 v[40:43], v[180:183], v[208:211], v[40:43]
	v_mfma_f32_16x16x32_bf16 v[32:35], v[188:191], v[208:211], v[32:35]
	v_mfma_f32_16x16x32_bf16 v[24:27], v[180:183], v[216:219], v[24:27]
	v_mfma_f32_16x16x32_bf16 v[16:19], v[188:191], v[216:219], v[16:19]
	v_mfma_f32_16x16x32_bf16 v[8:11], v[180:183], v[224:227], v[8:11]
	v_mfma_f32_16x16x32_bf16 v[0:3], v[188:191], v[224:227], v[0:3]
	v_mfma_f32_16x16x32_bf16 v[56:59], v[184:187], v[204:207], v[56:59]
	v_mfma_f32_16x16x32_bf16 v[48:51], v[196:199], v[204:207], v[48:51]
	v_mfma_f32_16x16x32_bf16 v[40:43], v[184:187], v[212:215], v[40:43]
	v_mfma_f32_16x16x32_bf16 v[32:35], v[196:199], v[212:215], v[32:35]
	v_mfma_f32_16x16x32_bf16 v[24:27], v[184:187], v[220:223], v[24:27]
	v_mfma_f32_16x16x32_bf16 v[16:19], v[196:199], v[220:223], v[16:19]
	v_mfma_f32_16x16x32_bf16 v[8:11], v[184:187], v[228:231], v[8:11]
	v_mfma_f32_16x16x32_bf16 v[0:3], v[196:199], v[228:231], v[0:3]
	s_barrier
	s_add_i32 s72, s72, 2
	s_add_u32 s52, s52, 0x100
	s_addc_u32 s53, s53, 0
	s_add_u32 s79, s79, 0x100
	s_addc_u32 s33, s33, 0
	s_cmp_gt_u32 s72, 13
	s_cbranch_scc0 .LBB0_218
	s_and_b64 vcc, exec, s[34:35]
	s_cbranch_vccz .LBB0_221
	s_barrier

; #define PG8_STAGE(bufoff, gbase, voff) do { _Pragma("unroll") for (int _i = 0; _i < 2; ++_i) \
;         __builtin_amdgcn_global_load_lds((const unsigned*)((const char*)(gbase) + (voff)[_i]), (PG8_LAS unsigned*)(lds + (bufoff) + ldsw + _i * 8192), 16, 0, 0); } while (0)
; #define PG8_LDA(dst, b, h) do { _Pragma("unroll") for (int m = 0; m < 4; ++m) _Pragma("unroll") for (int k = 0; k < 2; ++k) dst[m][k] = *(const PG8_LAS bf16x8*)(lds + PG8_SA(b, h) + aoff + m * 2048 + k * 1024); } while (0)
; #define PG8_LDB(dst, b, h) do { _Pragma("unroll") for (int n = 0; n < 2; ++n) _Pragma("unroll") for (int k = 0; k < 2; ++k) dst[n][k] = *(const PG8_LAS bf16x8*)(lds + PG8_SB(b, h) + boff + n * 2048 + k * 1024); } while (0)
; #define PG8_MMA(ai, bj, At, Bt) do { __builtin_amdgcn_s_setprio(1); _Pragma("unroll") for (int m = 0; m < 4; ++m) _Pragma("unroll") for (int n = 0; n < 2; ++n) _Pragma("unroll") for (int k = 0; k < 2; ++k) \
;         acc[ai][bj][m][n] = __builtin_amdgcn_mfma_f32_16x16x32_bf16(Bt[n][k], At[m][k], acc[ai][bj][m][n], 0, 0, 0); __builtin_amdgcn_s_setprio(0); } while (0)
; #define PG8_WAIT_V(n) asm volatile("s_waitcnt vmcnt(" #n ")" ::: "memory")
; #define PG8_BAR __builtin_amdgcn_s_barrier()
; template <class Epi, class Sched, bool ALIGN_EPI = false, bool SP2 = false>
; __device__ __forceinline__ void gemm_phase(PG8_LAS unsigned char* lds, const Gemm g, const Sched& S, const Epi& E) {
;     ...
;         for (int t = 0; t < nt; t += 2) {
;             const bool last = (t == nt - 2);
;             const char* a1 = cA + (size_t)(t + 1) * kstep;
;             const char* a2 = last ? nA : cA + (size_t)(t + 2) * kstep; const char* b2 = last ? nB : cB + (size_t)(t + 2) * kstep;
;             const char* a3 = a2 + kstep; const char* b3 = b2 + kstep;
;             if (last && has_next) S.a_ready(nxt);
;             if constexpr (SP2) {
;             PG8_LDB(B0, 0, 0); PG8_LDB(B1, 0, 1); PG8_SCHED; PG8_LDA(At, 0, 0); PG8_STAGE(PG8_SA(1, 1), a1 + hstep, voffA);
;             PG8_WAIT_V(8); PG8_WAIT_L(0); PG8_BAR; PG8_MMA(0, 0, At, B0); PG8_MMA(0, 1, At, B1); PG8_BAR; PG8_SCHED;
;             PG8_LDA(At, 0, 1); PG8_STAGE(PG8_SB(0, 0), b2, voffB); PG8_STAGE(PG8_SB(0, 1), b2 + hstep, voffB); PG8_STAGE(PG8_SA(0, 0), a2, voffA);
;             PG8_WAIT_V(8); PG8_WAIT_L(0); PG8_BAR; PG8_MMA(1, 0, At, B0); PG8_MMA(1, 1, At, B1); PG8_BAR; PG8_SCHED;
.LBB0_323:
	ds_read_b128 v[148:151], v156
	ds_read_b128 v[166:169], v156 offset:1024
	ds_read_b128 v[172:175], v156 offset:2048
	ds_read_b128 v[176:179], v156 offset:3072
	ds_read_b128 v[180:183], v157
	ds_read_b128 v[184:187], v157 offset:1024
	ds_read_b128 v[188:191], v157 offset:2048
	ds_read_b128 v[196:199], v157 offset:3072
	s_add_u32 s56, s54, 0x100
	s_addc_u32 s57, s55, 0
	s_cmp_eq_u32 s69, 40
	s_cselect_b32 s61, s51, s57
	s_cselect_b32 s60, s50, s56
	s_cselect_b32 s59, s53, s33
	s_cselect_b32 s58, s52, s4
	s_add_i32 m0, s37, 0xc000
	ds_read_b128 v[200:203], v158
	ds_read_b128 v[204:207], v158 offset:1024
	ds_read_b128 v[208:211], v158 offset:2048
	ds_read_b128 v[212:215], v158 offset:3072
	ds_read_b128 v[216:219], v158 offset:4096
	ds_read_b128 v[220:223], v158 offset:5120
	ds_read_b128 v[224:227], v158 offset:6144
	ds_read_b128 v[228:231], v158 offset:7168
	global_load_lds_dwordx4 v140, s[54:55]
	s_add_i32 m0, s37, 0xe000
	s_nop 0
	global_load_lds_dwordx4 v142, s[54:55]
	s_waitcnt vmcnt(8)
	s_waitcnt lgkmcnt(0)
	s_barrier
	v_mfma_f32_16x16x32_bf16 v[124:127], v[148:151], v[200:203], v[124:127]
	v_mfma_f32_16x16x32_bf16 v[120:123], v[172:175], v[200:203], v[120:123]
	v_mfma_f32_16x16x32_bf16 v[108:111], v[148:151], v[208:211], v[108:111]
	v_mfma_f32_16x16x32_bf16 v[104:107], v[172:175], v[208:211], v[104:107]
	v_mfma_f32_16x16x32_bf16 v[92:95], v[148:151], v[216:219], v[92:95]
	v_mfma_f32_16x16x32_bf16 v[88:91], v[172:175], v[216:219], v[88:91]
	v_mfma_f32_16x16x32_bf16 v[76:79], v[148:151], v[224:227], v[76:79]
	v_mfma_f32_16x16x32_bf16 v[72:75], v[172:175], v[224:227], v[72:75]
	v_mfma_f32_16x16x32_bf16 v[124:127], v[166:169], v[204:207], v[124:127]
	v_mfma_f32_16x16x32_bf16 v[120:123], v[176:179], v[204:207], v[120:123]
	v_mfma_f32_16x16x32_bf16 v[108:111], v[166:169], v[212:215], v[108:111]
	v_mfma_f32_16x16x32_bf16 v[104:107], v[176:179], v[212:215], v[104:107]
	v_mfma_f32_16x16x32_bf16 v[92:95], v[166:169], v[220:223], v[92:95]
	v_mfma_f32_16x16x32_bf16 v[88:91], v[176:179], v[220:223], v[88:91]
	v_mfma_f32_16x16x32_bf16 v[76:79], v[166:169], v[228:231], v[76:79]
	v_mfma_f32_16x16x32_bf16 v[72:75], v[176:179], v[228:231], v[72:75]
	v_mfma_f32_16x16x32_bf16 v[116:119], v[180:183], v[200:203], v[116:119]
	v_mfma_f32_16x16x32_bf16 v[112:115], v[188:191], v[200:203], v[112:115]
	v_mfma_f32_16x16x32_bf16 v[100:103], v[180:183], v[208:211], v[100:103]
	v_mfma_f32_16x16x32_bf16 v[96:99], v[188:191], v[208:211], v[96:99]
	v_mfma_f32_16x16x32_bf16 v[84:87], v[180:183], v[216:219], v[84:87]
	v_mfma_f32_16x16x32_bf16 v[80:83], v[188:191], v[216:219], v[80:83]
	v_mfma_f32_16x16x32_bf16 v[68:71], v[180:183], v[224:227], v[68:71]
	v_mfma_f32_16x16x32_bf16 v[64:67], v[188:191], v[224:227], v[64:67]
	v_mfma_f32_16x16x32_bf16 v[116:119], v[184:187], v[204:207], v[116:119]
	v_mfma_f32_16x16x32_bf16 v[112:115], v[196:199], v[204:207], v[112:115]
	v_mfma_f32_16x16x32_bf16 v[100:103], v[184:187], v[212:215], v[100:103]
	v_mfma_f32_16x16x32_bf16 v[96:99], v[196:199], v[212:215], v[96:99]
	v_mfma_f32_16x16x32_bf16 v[84:87], v[184:187], v[220:223], v[84:87]
	v_mfma_f32_16x16x32_bf16 v[80:83], v[196:199], v[220:223], v[80:83]
	v_mfma_f32_16x16x32_bf16 v[68:71], v[184:187], v[228:231], v[68:71]
	v_mfma_f32_16x16x32_bf16 v[64:67], v[196:199], v[228:231], v[64:67]
	s_barrier
	s_add_i32 s6, s74, s36
	s_mov_b32 m0, s6
	ds_read_b128 v[200:203], v158 offset:16384
	ds_read_b128 v[204:207], v158 offset:17408
	ds_read_b128 v[208:211], v158 offset:18432
	ds_read_b128 v[212:215], v158 offset:19456
	ds_read_b128 v[216:219], v158 offset:20480
	ds_read_b128 v[220:223], v158 offset:21504
	ds_read_b128 v[224:227], v158 offset:22528
	ds_read_b128 v[228:231], v158 offset:23552
	global_load_lds_dwordx4 v134, s[58:59]
	s_add_i32 m0, s6, 0x2000
	s_add_u32 s54, s58, 0xb0000
	s_addc_u32 s55, s59, 0
	s_add_i32 s6, s75, s36
	global_load_lds_dwordx4 v138, s[58:59]
	s_mov_b32 m0, s6
	s_nop 0
	global_load_lds_dwordx4 v134, s[54:55]
	s_add_i32 m0, s6, 0x2000
	s_nop 0
	global_load_lds_dwordx4 v138, s[54:55]
	s_mov_b32 m0, s37
	s_nop 0
	global_load_lds_dwordx4 v132, s[60:61]
	s_mov_b32 m0, s30
	s_nop 0
	global_load_lds_dwordx4 v136, s[60:61]
	s_waitcnt vmcnt(8)
	s_waitcnt lgkmcnt(0)
	s_barrier
	v_mfma_f32_16x16x32_bf16 v[60:63], v[148:151], v[200:203], v[60:63]
	v_mfma_f32_16x16x32_bf16 v[56:59], v[172:175], v[200:203], v[56:59]
	v_mfma_f32_16x16x32_bf16 v[44:47], v[148:151], v[208:211], v[44:47]
	v_mfma_f32_16x16x32_bf16 v[40:43], v[172:175], v[208:211], v[40:43]
	v_mfma_f32_16x16x32_bf16 v[28:31], v[148:151], v[216:219], v[28:31]
	v_mfma_f32_16x16x32_bf16 v[24:27], v[172:175], v[216:219], v[24:27]
	v_mfma_f32_16x16x32_bf16 v[12:15], v[148:151], v[224:227], v[12:15]
	v_mfma_f32_16x16x32_bf16 v[8:11], v[172:175], v[224:227], v[8:11]
	v_mfma_f32_16x16x32_bf16 v[60:63], v[166:169], v[204:207], v[60:63]
	v_mfma_f32_16x16x32_bf16 v[56:59], v[176:179], v[204:207], v[56:59]
	v_mfma_f32_16x16x32_bf16 v[44:47], v[166:169], v[212:215], v[44:47]
	v_mfma_f32_16x16x32_bf16 v[40:43], v[176:179], v[212:215], v[40:43]
	v_mfma_f32_16x16x32_bf16 v[28:31], v[166:169], v[220:223], v[28:31]
	v_mfma_f32_16x16x32_bf16 v[24:27], v[176:179], v[220:223], v[24:27]
	v_mfma_f32_16x16x32_bf16 v[12:15], v[166:169], v[228:231], v[12:15]
	v_mfma_f32_16x16x32_bf16 v[8:11], v[176:179], v[228:231], v[8:11]
	v_mfma_f32_16x16x32_bf16 v[52:55], v[180:183], v[200:203], v[52:55]
	v_mfma_f32_16x16x32_bf16 v[48:51], v[188:191], v[200:203], v[48:51]
	v_mfma_f32_16x16x32_bf16 v[36:39], v[180:183], v[208:211], v[36:39]
	v_mfma_f32_16x16x32_bf16 v[32:35], v[188:191], v[208:211], v[32:35]
	v_mfma_f32_16x16x32_bf16 v[20:23], v[180:183], v[216:219], v[20:23]
	v_mfma_f32_16x16x32_bf16 v[16:19], v[188:191], v[216:219], v[16:19]
	v_mfma_f32_16x16x32_bf16 v[4:7], v[180:183], v[224:227], v[4:7]
	v_mfma_f32_16x16x32_bf16 v[0:3], v[188:191], v[224:227], v[0:3]
	v_mfma_f32_16x16x32_bf16 v[52:55], v[184:187], v[204:207], v[52:55]
	v_mfma_f32_16x16x32_bf16 v[48:51], v[196:199], v[204:207], v[48:51]
	v_mfma_f32_16x16x32_bf16 v[36:39], v[184:187], v[212:215], v[36:39]
	v_mfma_f32_16x16x32_bf16 v[32:35], v[196:199], v[212:215], v[32:35]
	v_mfma_f32_16x16x32_bf16 v[20:23], v[184:187], v[220:223], v[20:23]
	v_mfma_f32_16x16x32_bf16 v[16:19], v[196:199], v[220:223], v[16:19]
	v_mfma_f32_16x16x32_bf16 v[4:7], v[184:187], v[228:231], v[4:7]
	v_mfma_f32_16x16x32_bf16 v[0:3], v[196:199], v[228:231], v[0:3]
	s_barrier
; #define PG8_STAGE(bufoff, gbase, voff) do { _Pragma("unroll") for (int _i = 0; _i < 2; ++_i) \
;         __builtin_amdgcn_global_load_lds((const unsigned*)((const char*)(gbase) + (voff)[_i]), (PG8_LAS unsigned*)(lds + (bufoff) + ldsw + _i * 8192), 16, 0, 0); } while (0)
; #define PG8_LDA(dst, b, h) do { _Pragma("unroll") for (int m = 0; m < 4; ++m) _Pragma("unroll") for (int k = 0; k < 2; ++k) dst[m][k] = *(const PG8_LAS bf16x8*)(lds + PG8_SA(b, h) + aoff + m * 2048 + k * 1024); } while (0)
; #define PG8_LDB(dst, b, h) do { _Pragma("unroll") for (int n = 0; n < 2; ++n) _Pragma("unroll") for (int k = 0; k < 2; ++k) dst[n][k] = *(const PG8_LAS bf16x8*)(lds + PG8_SB(b, h) + boff + n * 2048 + k * 1024); } while (0)
; #define PG8_MMA(ai, bj, At, Bt) do { __builtin_amdgcn_s_setprio(1); _Pragma("unroll") for (int m = 0; m < 4; ++m) _Pragma("unroll") for (int n = 0; n < 2; ++n) _Pragma("unroll") for (int k = 0; k < 2; ++k) \
;         acc[ai][bj][m][n] = __builtin_amdgcn_mfma_f32_16x16x32_bf16(Bt[n][k], At[m][k], acc[ai][bj][m][n], 0, 0, 0); __builtin_amdgcn_s_setprio(0); } while (0)
; #define PG8_WAIT_V(n) asm volatile("s_waitcnt vmcnt(" #n ")" ::: "memory")
; #define PG8_WAIT_L(n) asm volatile("s_waitcnt lgkmcnt(" #n ")" ::: "memory")
; #define PG8_BAR __builtin_amdgcn_s_barrier()
; #define PG8_SCHED __builtin_amdgcn_sched_barrier(0)
; template <class Epi, class Sched, bool ALIGN_EPI = false, bool SP2 = false>
; __device__ __forceinline__ void gemm_phase(PG8_LAS unsigned char* lds, const Gemm g, const Sched& S, const Epi& E) {
;     ...
;             PG8_LDB(B0, 1, 0); PG8_LDB(B1, 1, 1); PG8_SCHED; PG8_LDA(At, 1, 0); PG8_STAGE(PG8_SA(0, 1), a2 + hstep, voffA);
;             PG8_WAIT_V(8); PG8_WAIT_L(0); PG8_BAR; PG8_MMA(0, 0, At, B0); PG8_MMA(0, 1, At, B1); PG8_BAR; PG8_SCHED;
;             PG8_LDA(At, 1, 1); PG8_STAGE(PG8_SB(1, 0), b3, voffB); PG8_STAGE(PG8_SB(1, 1), b3 + hstep, voffB); PG8_STAGE(PG8_SA(1, 0), a3, voffA);
;             PG8_WAIT_V(8); PG8_WAIT_L(0); PG8_BAR; PG8_MMA(1, 0, At, B0); PG8_MMA(1, 1, At, B1); PG8_BAR; PG8_SCHED;
	s_add_i32 s6, 0, 0x18000
	v_add_u32_e32 v161, s6, v154
	s_add_i32 s7, 0, 0x1c000
	ds_read_b128 v[148:151], v161
	ds_read_b128 v[166:169], v161 offset:1024
	ds_read_b128 v[172:175], v161 offset:2048
	ds_read_b128 v[176:179], v161 offset:3072
	v_add_u32_e32 v161, s7, v154
	ds_read_b128 v[180:183], v161
	ds_read_b128 v[184:187], v161 offset:1024
	ds_read_b128 v[188:191], v161 offset:2048
	ds_read_b128 v[196:199], v161 offset:3072
	s_add_u32 s54, s60, 0xb0000
	s_addc_u32 s55, s61, 0
	s_mov_b32 m0, s31
	ds_read_b128 v[200:203], v158 offset:32768
	ds_read_b128 v[204:207], v158 offset:33792
	ds_read_b128 v[208:211], v158 offset:34816
	ds_read_b128 v[212:215], v158 offset:35840
	ds_read_b128 v[216:219], v158 offset:36864
	ds_read_b128 v[220:223], v158 offset:37888
	ds_read_b128 v[224:227], v158 offset:38912
	ds_read_b128 v[228:231], v158 offset:39936
	global_load_lds_dwordx4 v132, s[54:55]
	s_mov_b32 m0, s76
	s_nop 0
	global_load_lds_dwordx4 v136, s[54:55]
	s_waitcnt vmcnt(8)
	s_waitcnt lgkmcnt(0)
	s_barrier
	v_mfma_f32_16x16x32_bf16 v[124:127], v[148:151], v[200:203], v[124:127]
	v_mfma_f32_16x16x32_bf16 v[120:123], v[172:175], v[200:203], v[120:123]
	v_mfma_f32_16x16x32_bf16 v[108:111], v[148:151], v[208:211], v[108:111]
	v_mfma_f32_16x16x32_bf16 v[104:107], v[172:175], v[208:211], v[104:107]
	v_mfma_f32_16x16x32_bf16 v[92:95], v[148:151], v[216:219], v[92:95]
	v_mfma_f32_16x16x32_bf16 v[88:91], v[172:175], v[216:219], v[88:91]
	v_mfma_f32_16x16x32_bf16 v[76:79], v[148:151], v[224:227], v[76:79]
	v_mfma_f32_16x16x32_bf16 v[72:75], v[172:175], v[224:227], v[72:75]
	v_mfma_f32_16x16x32_bf16 v[124:127], v[166:169], v[204:207], v[124:127]
	v_mfma_f32_16x16x32_bf16 v[120:123], v[176:179], v[204:207], v[120:123]
	v_mfma_f32_16x16x32_bf16 v[108:111], v[166:169], v[212:215], v[108:111]
	v_mfma_f32_16x16x32_bf16 v[104:107], v[176:179], v[212:215], v[104:107]
	v_mfma_f32_16x16x32_bf16 v[92:95], v[166:169], v[220:223], v[92:95]
	v_mfma_f32_16x16x32_bf16 v[88:91], v[176:179], v[220:223], v[88:91]
	v_mfma_f32_16x16x32_bf16 v[76:79], v[166:169], v[228:231], v[76:79]
	v_mfma_f32_16x16x32_bf16 v[72:75], v[176:179], v[228:231], v[72:75]
	v_mfma_f32_16x16x32_bf16 v[116:119], v[180:183], v[200:203], v[116:119]
	v_mfma_f32_16x16x32_bf16 v[112:115], v[188:191], v[200:203], v[112:115]
	v_mfma_f32_16x16x32_bf16 v[100:103], v[180:183], v[208:211], v[100:103]
	v_mfma_f32_16x16x32_bf16 v[96:99], v[188:191], v[208:211], v[96:99]
	v_mfma_f32_16x16x32_bf16 v[84:87], v[180:183], v[216:219], v[84:87]
	v_mfma_f32_16x16x32_bf16 v[80:83], v[188:191], v[216:219], v[80:83]
	v_mfma_f32_16x16x32_bf16 v[68:71], v[180:183], v[224:227], v[68:71]
	v_mfma_f32_16x16x32_bf16 v[64:67], v[188:191], v[224:227], v[64:67]
	v_mfma_f32_16x16x32_bf16 v[116:119], v[184:187], v[204:207], v[116:119]
	v_mfma_f32_16x16x32_bf16 v[112:115], v[196:199], v[204:207], v[112:115]
	v_mfma_f32_16x16x32_bf16 v[100:103], v[184:187], v[212:215], v[100:103]
	v_mfma_f32_16x16x32_bf16 v[96:99], v[196:199], v[212:215], v[96:99]
	v_mfma_f32_16x16x32_bf16 v[84:87], v[184:187], v[220:223], v[84:87]
	v_mfma_f32_16x16x32_bf16 v[80:83], v[196:199], v[220:223], v[80:83]
	v_mfma_f32_16x16x32_bf16 v[68:71], v[184:187], v[228:231], v[68:71]
	v_mfma_f32_16x16x32_bf16 v[64:67], v[196:199], v[228:231], v[64:67]
	s_barrier
	s_add_i32 s6, s6, s36
	s_add_u32 s98, s58, 0x80
	s_addc_u32 s99, s59, 0
	s_add_u32 s100, s60, 0x80
	s_addc_u32 s101, s61, 0
	s_mov_b32 m0, s6
	ds_read_b128 v[200:203], v158 offset:49152
	ds_read_b128 v[204:207], v158 offset:50176
	ds_read_b128 v[208:211], v158 offset:51200
	ds_read_b128 v[212:215], v158 offset:52224
	ds_read_b128 v[216:219], v158 offset:53248
	ds_read_b128 v[220:223], v158 offset:54272
	ds_read_b128 v[224:227], v158 offset:55296
	ds_read_b128 v[228:231], v158 offset:56320
	global_load_lds_dwordx4 v134, s[98:99]
	s_add_i32 m0, s6, 0x2000
	s_add_u32 s54, s58, 0xb0080
	s_addc_u32 s55, s59, 0
	s_add_i32 s6, s7, s36
	global_load_lds_dwordx4 v138, s[98:99]
	s_mov_b32 m0, s6
	s_nop 0
	global_load_lds_dwordx4 v134, s[54:55]
	s_add_i32 m0, s6, 0x2000
	s_nop 0
	global_load_lds_dwordx4 v138, s[54:55]
	s_mov_b32 m0, s78
	s_nop 0
	global_load_lds_dwordx4 v132, s[100:101]
	s_mov_b32 m0, s79
	s_nop 0
	global_load_lds_dwordx4 v136, s[100:101]
	s_waitcnt vmcnt(8)
	s_waitcnt lgkmcnt(0)
	s_barrier
	v_mfma_f32_16x16x32_bf16 v[60:63], v[148:151], v[200:203], v[60:63]
	v_mfma_f32_16x16x32_bf16 v[56:59], v[172:175], v[200:203], v[56:59]
	v_mfma_f32_16x16x32_bf16 v[44:47], v[148:151], v[208:211], v[44:47]
	v_mfma_f32_16x16x32_bf16 v[40:43], v[172:175], v[208:211], v[40:43]
	v_mfma_f32_16x16x32_bf16 v[28:31], v[148:151], v[216:219], v[28:31]
	v_mfma_f32_16x16x32_bf16 v[24:27], v[172:175], v[216:219], v[24:27]
	v_mfma_f32_16x16x32_bf16 v[12:15], v[148:151], v[224:227], v[12:15]
	v_mfma_f32_16x16x32_bf16 v[8:11], v[172:175], v[224:227], v[8:11]
	v_mfma_f32_16x16x32_bf16 v[60:63], v[166:169], v[204:207], v[60:63]
	v_mfma_f32_16x16x32_bf16 v[56:59], v[176:179], v[204:207], v[56:59]
	v_mfma_f32_16x16x32_bf16 v[44:47], v[166:169], v[212:215], v[44:47]
	v_mfma_f32_16x16x32_bf16 v[40:43], v[176:179], v[212:215], v[40:43]
	v_mfma_f32_16x16x32_bf16 v[28:31], v[166:169], v[220:223], v[28:31]
	v_mfma_f32_16x16x32_bf16 v[24:27], v[176:179], v[220:223], v[24:27]
	v_mfma_f32_16x16x32_bf16 v[12:15], v[166:169], v[228:231], v[12:15]
	v_mfma_f32_16x16x32_bf16 v[8:11], v[176:179], v[228:231], v[8:11]
	v_mfma_f32_16x16x32_bf16 v[52:55], v[180:183], v[200:203], v[52:55]
	v_mfma_f32_16x16x32_bf16 v[48:51], v[188:191], v[200:203], v[48:51]
	v_mfma_f32_16x16x32_bf16 v[36:39], v[180:183], v[208:211], v[36:39]
	v_mfma_f32_16x16x32_bf16 v[32:35], v[188:191], v[208:211], v[32:35]
	v_mfma_f32_16x16x32_bf16 v[20:23], v[180:183], v[216:219], v[20:23]
	v_mfma_f32_16x16x32_bf16 v[16:19], v[188:191], v[216:219], v[16:19]
	v_mfma_f32_16x16x32_bf16 v[4:7], v[180:183], v[224:227], v[4:7]
	v_mfma_f32_16x16x32_bf16 v[0:3], v[188:191], v[224:227], v[0:3]
	v_mfma_f32_16x16x32_bf16 v[52:55], v[184:187], v[204:207], v[52:55]
	v_mfma_f32_16x16x32_bf16 v[48:51], v[196:199], v[204:207], v[48:51]
	v_mfma_f32_16x16x32_bf16 v[36:39], v[184:187], v[212:215], v[36:39]
	v_mfma_f32_16x16x32_bf16 v[32:35], v[196:199], v[212:215], v[32:35]
	v_mfma_f32_16x16x32_bf16 v[20:23], v[184:187], v[220:223], v[20:23]
	v_mfma_f32_16x16x32_bf16 v[16:19], v[196:199], v[220:223], v[16:19]
	v_mfma_f32_16x16x32_bf16 v[4:7], v[184:187], v[228:231], v[4:7]
	v_mfma_f32_16x16x32_bf16 v[0:3], v[196:199], v[228:231], v[0:3]
	s_barrier
	s_add_i32 s69, s69, 2
	s_add_u32 s4, s4, 0x100
	s_addc_u32 s33, s33, 0
	s_cmp_gt_u32 s69, 41
	s_mov_b64 s[54:55], s[56:57]
	s_cbranch_scc0 .LBB0_323
	s_and_b64 vcc, exec, s[40:41]
	s_cbranch_vccz .LBB0_326
	s_barrier

; #define PG8_STAGE(bufoff, gbase, voff) do { _Pragma("unroll") for (int _i = 0; _i < 2; ++_i) \
;         __builtin_amdgcn_global_load_lds((const unsigned*)((const char*)(gbase) + (voff)[_i]), (PG8_LAS unsigned*)(lds + (bufoff) + ldsw + _i * 8192), 16, 0, 0); } while (0)
; #define PG8_LDA(dst, b, h) do { _Pragma("unroll") for (int m = 0; m < 4; ++m) _Pragma("unroll") for (int k = 0; k < 2; ++k) dst[m][k] = *(const PG8_LAS bf16x8*)(lds + PG8_SA(b, h) + aoff + m * 2048 + k * 1024); } while (0)
; #define PG8_LDB(dst, b, h) do { _Pragma("unroll") for (int n = 0; n < 2; ++n) _Pragma("unroll") for (int k = 0; k < 2; ++k) dst[n][k] = *(const PG8_LAS bf16x8*)(lds + PG8_SB(b, h) + boff + n * 2048 + k * 1024); } while (0)
; #define PG8_MMA(ai, bj, At, Bt) do { __builtin_amdgcn_s_setprio(1); _Pragma("unroll") for (int m = 0; m < 4; ++m) _Pragma("unroll") for (int n = 0; n < 2; ++n) _Pragma("unroll") for (int k = 0; k < 2; ++k) \
;         acc[ai][bj][m][n] = __builtin_amdgcn_mfma_f32_16x16x32_bf16(Bt[n][k], At[m][k], acc[ai][bj][m][n], 0, 0, 0); __builtin_amdgcn_s_setprio(0); } while (0)
; #define PG8_WAIT_V(n) asm volatile("s_waitcnt vmcnt(" #n ")" ::: "memory")
; #define PG8_BAR __builtin_amdgcn_s_barrier()
; template <class Epi, class Sched, bool ALIGN_EPI = false, bool SP2 = false>
; __device__ __forceinline__ void gemm_phase(PG8_LAS unsigned char* lds, const Gemm g, const Sched& S, const Epi& E) {
;     ...
;         for (int t = 0; t < nt; t += 2) {
;             const bool last = (t == nt - 2);
;             const char* a1 = cA + (size_t)(t + 1) * kstep;
;             const char* a2 = last ? nA : cA + (size_t)(t + 2) * kstep; const char* b2 = last ? nB : cB + (size_t)(t + 2) * kstep;
;             const char* a3 = a2 + kstep; const char* b3 = b2 + kstep;
;             if (last && has_next) S.a_ready(nxt);
;             if constexpr (SP2) {
;             PG8_LDB(B0, 0, 0); PG8_LDB(B1, 0, 1); PG8_SCHED; PG8_LDA(At, 0, 0); PG8_STAGE(PG8_SA(1, 1), a1 + hstep, voffA);
;             PG8_WAIT_V(8); PG8_WAIT_L(0); PG8_BAR; PG8_MMA(0, 0, At, B0); PG8_MMA(0, 1, At, B1); PG8_BAR; PG8_SCHED;
;             PG8_LDA(At, 0, 1); PG8_STAGE(PG8_SB(0, 0), b2, voffB); PG8_STAGE(PG8_SB(0, 1), b2 + hstep, voffB); PG8_STAGE(PG8_SA(0, 0), a2, voffA);
;             PG8_WAIT_V(8); PG8_WAIT_L(0); PG8_BAR; PG8_MMA(1, 0, At, B0); PG8_MMA(1, 1, At, B1); PG8_BAR; PG8_SCHED;
.LBB0_463:
	ds_read_b128 v[152:155], v172
	ds_read_b128 v[156:159], v172 offset:1024
	ds_read_b128 v[166:169], v172 offset:2048
	ds_read_b128 v[176:179], v172 offset:3072
	ds_read_b128 v[180:183], v173
	ds_read_b128 v[184:187], v173 offset:1024
	ds_read_b128 v[188:191], v173 offset:2048
	ds_read_b128 v[196:199], v173 offset:3072
	s_add_u32 s6, s60, 0xfffc0080
	s_addc_u32 s7, s61, -1
	s_cmp_eq_u32 s72, 12
	s_cselect_b32 s81, s49, s7
	s_cselect_b32 s80, s55, s6
	s_cselect_b32 s79, s53, s33
	s_cselect_b32 s78, vcc_lo, vcc_hi
	s_add_i32 m0, s31, 0xc000
	ds_read_b128 v[200:203], v174
	ds_read_b128 v[204:207], v174 offset:1024
	ds_read_b128 v[208:211], v174 offset:2048
	ds_read_b128 v[212:215], v174 offset:3072
	ds_read_b128 v[216:219], v174 offset:4096
	ds_read_b128 v[220:223], v174 offset:5120
	ds_read_b128 v[224:227], v174 offset:6144
	ds_read_b128 v[228:231], v174 offset:7168
	global_load_lds_dwordx4 v144, s[60:61]
	s_add_i32 m0, s31, 0xe000
	s_nop 0
	global_load_lds_dwordx4 v146, s[60:61]
	s_waitcnt vmcnt(8)
	s_waitcnt lgkmcnt(0)
	s_barrier
	v_mfma_f32_16x16x32_bf16 v[124:127], v[152:155], v[200:203], v[124:127]
	v_mfma_f32_16x16x32_bf16 v[120:123], v[166:169], v[200:203], v[120:123]
	v_mfma_f32_16x16x32_bf16 v[108:111], v[152:155], v[208:211], v[108:111]
	v_mfma_f32_16x16x32_bf16 v[104:107], v[166:169], v[208:211], v[104:107]
	v_mfma_f32_16x16x32_bf16 v[92:95], v[152:155], v[216:219], v[92:95]
	v_mfma_f32_16x16x32_bf16 v[88:91], v[166:169], v[216:219], v[88:91]
	v_mfma_f32_16x16x32_bf16 v[76:79], v[152:155], v[224:227], v[76:79]
	v_mfma_f32_16x16x32_bf16 v[72:75], v[166:169], v[224:227], v[72:75]
	v_mfma_f32_16x16x32_bf16 v[124:127], v[156:159], v[204:207], v[124:127]
	v_mfma_f32_16x16x32_bf16 v[120:123], v[176:179], v[204:207], v[120:123]
	v_mfma_f32_16x16x32_bf16 v[108:111], v[156:159], v[212:215], v[108:111]
	v_mfma_f32_16x16x32_bf16 v[104:107], v[176:179], v[212:215], v[104:107]
	v_mfma_f32_16x16x32_bf16 v[92:95], v[156:159], v[220:223], v[92:95]
	v_mfma_f32_16x16x32_bf16 v[88:91], v[176:179], v[220:223], v[88:91]
	v_mfma_f32_16x16x32_bf16 v[76:79], v[156:159], v[228:231], v[76:79]
	v_mfma_f32_16x16x32_bf16 v[72:75], v[176:179], v[228:231], v[72:75]
	v_mfma_f32_16x16x32_bf16 v[116:119], v[180:183], v[200:203], v[116:119]
	v_mfma_f32_16x16x32_bf16 v[112:115], v[188:191], v[200:203], v[112:115]
	v_mfma_f32_16x16x32_bf16 v[100:103], v[180:183], v[208:211], v[100:103]
	v_mfma_f32_16x16x32_bf16 v[96:99], v[188:191], v[208:211], v[96:99]
	v_mfma_f32_16x16x32_bf16 v[84:87], v[180:183], v[216:219], v[84:87]
	v_mfma_f32_16x16x32_bf16 v[80:83], v[188:191], v[216:219], v[80:83]
	v_mfma_f32_16x16x32_bf16 v[68:71], v[180:183], v[224:227], v[68:71]
	v_mfma_f32_16x16x32_bf16 v[64:67], v[188:191], v[224:227], v[64:67]
	v_mfma_f32_16x16x32_bf16 v[116:119], v[184:187], v[204:207], v[116:119]
	v_mfma_f32_16x16x32_bf16 v[112:115], v[196:199], v[204:207], v[112:115]
	v_mfma_f32_16x16x32_bf16 v[100:103], v[184:187], v[212:215], v[100:103]
	v_mfma_f32_16x16x32_bf16 v[96:99], v[196:199], v[212:215], v[96:99]
	v_mfma_f32_16x16x32_bf16 v[84:87], v[184:187], v[220:223], v[84:87]
	v_mfma_f32_16x16x32_bf16 v[80:83], v[196:199], v[220:223], v[80:83]
	v_mfma_f32_16x16x32_bf16 v[68:71], v[184:187], v[228:231], v[68:71]
	v_mfma_f32_16x16x32_bf16 v[64:67], v[196:199], v[228:231], v[64:67]
	s_barrier
	s_add_i32 s6, s69, s30
	s_mov_b32 m0, s6
	ds_read_b128 v[200:203], v174 offset:16384
	ds_read_b128 v[204:207], v174 offset:17408
	ds_read_b128 v[208:211], v174 offset:18432
	ds_read_b128 v[212:215], v174 offset:19456
	ds_read_b128 v[216:219], v174 offset:20480
	ds_read_b128 v[220:223], v174 offset:21504
	ds_read_b128 v[224:227], v174 offset:22528
	ds_read_b128 v[228:231], v174 offset:23552
	global_load_lds_dwordx4 v134, s[78:79]
	s_add_i32 m0, s6, 0x2000
	s_add_u32 s6, s78, 0x40000
	s_addc_u32 s7, s79, 0
	s_add_i32 s73, s74, s30
	global_load_lds_dwordx4 v138, s[78:79]
	s_mov_b32 m0, s73
	s_nop 0
	global_load_lds_dwordx4 v134, s[6:7]
	s_add_i32 m0, s73, 0x2000
	s_nop 0
	global_load_lds_dwordx4 v138, s[6:7]
	s_mov_b32 m0, s31
	s_nop 0
	global_load_lds_dwordx4 v132, s[80:81]
	s_mov_b32 m0, s36
	s_nop 0
	global_load_lds_dwordx4 v136, s[80:81]
	s_waitcnt vmcnt(8)
	s_waitcnt lgkmcnt(0)
	s_barrier
	v_mfma_f32_16x16x32_bf16 v[60:63], v[152:155], v[200:203], v[60:63]
	v_mfma_f32_16x16x32_bf16 v[56:59], v[166:169], v[200:203], v[56:59]
	v_mfma_f32_16x16x32_bf16 v[44:47], v[152:155], v[208:211], v[44:47]
	v_mfma_f32_16x16x32_bf16 v[40:43], v[166:169], v[208:211], v[40:43]
	v_mfma_f32_16x16x32_bf16 v[28:31], v[152:155], v[216:219], v[28:31]
	v_mfma_f32_16x16x32_bf16 v[24:27], v[166:169], v[216:219], v[24:27]
	v_mfma_f32_16x16x32_bf16 v[12:15], v[152:155], v[224:227], v[12:15]
	v_mfma_f32_16x16x32_bf16 v[8:11], v[166:169], v[224:227], v[8:11]
	v_mfma_f32_16x16x32_bf16 v[60:63], v[156:159], v[204:207], v[60:63]
	v_mfma_f32_16x16x32_bf16 v[56:59], v[176:179], v[204:207], v[56:59]
	v_mfma_f32_16x16x32_bf16 v[44:47], v[156:159], v[212:215], v[44:47]
	v_mfma_f32_16x16x32_bf16 v[40:43], v[176:179], v[212:215], v[40:43]
	v_mfma_f32_16x16x32_bf16 v[28:31], v[156:159], v[220:223], v[28:31]
	v_mfma_f32_16x16x32_bf16 v[24:27], v[176:179], v[220:223], v[24:27]
	v_mfma_f32_16x16x32_bf16 v[12:15], v[156:159], v[228:231], v[12:15]
	v_mfma_f32_16x16x32_bf16 v[8:11], v[176:179], v[228:231], v[8:11]
	v_mfma_f32_16x16x32_bf16 v[52:55], v[180:183], v[200:203], v[52:55]
	v_mfma_f32_16x16x32_bf16 v[48:51], v[188:191], v[200:203], v[48:51]
	v_mfma_f32_16x16x32_bf16 v[36:39], v[180:183], v[208:211], v[36:39]
	v_mfma_f32_16x16x32_bf16 v[32:35], v[188:191], v[208:211], v[32:35]
	v_mfma_f32_16x16x32_bf16 v[20:23], v[180:183], v[216:219], v[20:23]
	v_mfma_f32_16x16x32_bf16 v[16:19], v[188:191], v[216:219], v[16:19]
	v_mfma_f32_16x16x32_bf16 v[4:7], v[180:183], v[224:227], v[4:7]
	v_mfma_f32_16x16x32_bf16 v[0:3], v[188:191], v[224:227], v[0:3]
	v_mfma_f32_16x16x32_bf16 v[52:55], v[184:187], v[204:207], v[52:55]
	v_mfma_f32_16x16x32_bf16 v[48:51], v[196:199], v[204:207], v[48:51]
	v_mfma_f32_16x16x32_bf16 v[36:39], v[184:187], v[212:215], v[36:39]
	v_mfma_f32_16x16x32_bf16 v[32:35], v[196:199], v[212:215], v[32:35]
	v_mfma_f32_16x16x32_bf16 v[20:23], v[184:187], v[220:223], v[20:23]
	v_mfma_f32_16x16x32_bf16 v[16:19], v[196:199], v[220:223], v[16:19]
	v_mfma_f32_16x16x32_bf16 v[4:7], v[184:187], v[228:231], v[4:7]
	v_mfma_f32_16x16x32_bf16 v[0:3], v[196:199], v[228:231], v[0:3]
	s_barrier
; #define PG8_STAGE(bufoff, gbase, voff) do { _Pragma("unroll") for (int _i = 0; _i < 2; ++_i) \
;         __builtin_amdgcn_global_load_lds((const unsigned*)((const char*)(gbase) + (voff)[_i]), (PG8_LAS unsigned*)(lds + (bufoff) + ldsw + _i * 8192), 16, 0, 0); } while (0)
; #define PG8_LDA(dst, b, h) do { _Pragma("unroll") for (int m = 0; m < 4; ++m) _Pragma("unroll") for (int k = 0; k < 2; ++k) dst[m][k] = *(const PG8_LAS bf16x8*)(lds + PG8_SA(b, h) + aoff + m * 2048 + k * 1024); } while (0)
; #define PG8_LDB(dst, b, h) do { _Pragma("unroll") for (int n = 0; n < 2; ++n) _Pragma("unroll") for (int k = 0; k < 2; ++k) dst[n][k] = *(const PG8_LAS bf16x8*)(lds + PG8_SB(b, h) + boff + n * 2048 + k * 1024); } while (0)
; #define PG8_MMA(ai, bj, At, Bt) do { __builtin_amdgcn_s_setprio(1); _Pragma("unroll") for (int m = 0; m < 4; ++m) _Pragma("unroll") for (int n = 0; n < 2; ++n) _Pragma("unroll") for (int k = 0; k < 2; ++k) \
;         acc[ai][bj][m][n] = __builtin_amdgcn_mfma_f32_16x16x32_bf16(Bt[n][k], At[m][k], acc[ai][bj][m][n], 0, 0, 0); __builtin_amdgcn_s_setprio(0); } while (0)
; #define PG8_WAIT_V(n) asm volatile("s_waitcnt vmcnt(" #n ")" ::: "memory")
; #define PG8_WAIT_L(n) asm volatile("s_waitcnt lgkmcnt(" #n ")" ::: "memory")
; #define PG8_BAR __builtin_amdgcn_s_barrier()
; #define PG8_SCHED __builtin_amdgcn_sched_barrier(0)
; template <class Epi, class Sched, bool ALIGN_EPI = false, bool SP2 = false>
; __device__ __forceinline__ void gemm_phase(PG8_LAS unsigned char* lds, const Gemm g, const Sched& S, const Epi& E) {
;     ...
;             PG8_LDB(B0, 1, 0); PG8_LDB(B1, 1, 1); PG8_SCHED; PG8_LDA(At, 1, 0); PG8_STAGE(PG8_SA(0, 1), a2 + hstep, voffA);
;             PG8_WAIT_V(8); PG8_WAIT_L(0); PG8_BAR; PG8_MMA(0, 0, At, B0); PG8_MMA(0, 1, At, B1); PG8_BAR; PG8_SCHED;
;             PG8_LDA(At, 1, 1); PG8_STAGE(PG8_SB(1, 0), b3, voffB); PG8_STAGE(PG8_SB(1, 1), b3 + hstep, voffB); PG8_STAGE(PG8_SA(1, 0), a3, voffA);
;             PG8_WAIT_V(8); PG8_WAIT_L(0); PG8_BAR; PG8_MMA(1, 0, At, B0); PG8_MMA(1, 1, At, B1); PG8_BAR; PG8_SCHED;
	s_add_i32 s73, 0, 0x18000
	v_add_u32_e32 v175, s73, v143
	s_add_i32 s82, 0, 0x1c000
	ds_read_b128 v[152:155], v175
	ds_read_b128 v[156:159], v175 offset:1024
	ds_read_b128 v[166:169], v175 offset:2048
	ds_read_b128 v[176:179], v175 offset:3072
	v_add_u32_e32 v175, s82, v143
	ds_read_b128 v[180:183], v175
	ds_read_b128 v[184:187], v175 offset:1024
	ds_read_b128 v[188:191], v175 offset:2048
	ds_read_b128 v[196:199], v175 offset:3072
	s_add_u32 s6, s80, 0x40000
	s_addc_u32 s7, s81, 0
	s_mov_b32 m0, s37
	ds_read_b128 v[200:203], v174 offset:32768
	ds_read_b128 v[204:207], v174 offset:33792
	ds_read_b128 v[208:211], v174 offset:34816
	ds_read_b128 v[212:215], v174 offset:35840
	ds_read_b128 v[216:219], v174 offset:36864
	ds_read_b128 v[220:223], v174 offset:37888
	ds_read_b128 v[224:227], v174 offset:38912
	ds_read_b128 v[228:231], v174 offset:39936
	global_load_lds_dwordx4 v132, s[6:7]
	s_mov_b32 m0, s42
	s_nop 0
	global_load_lds_dwordx4 v136, s[6:7]
	s_waitcnt vmcnt(8)
	s_waitcnt lgkmcnt(0)
	s_barrier
	v_mfma_f32_16x16x32_bf16 v[124:127], v[152:155], v[200:203], v[124:127]
	v_mfma_f32_16x16x32_bf16 v[120:123], v[166:169], v[200:203], v[120:123]
	v_mfma_f32_16x16x32_bf16 v[108:111], v[152:155], v[208:211], v[108:111]
	v_mfma_f32_16x16x32_bf16 v[104:107], v[166:169], v[208:211], v[104:107]
	v_mfma_f32_16x16x32_bf16 v[92:95], v[152:155], v[216:219], v[92:95]
	v_mfma_f32_16x16x32_bf16 v[88:91], v[166:169], v[216:219], v[88:91]
	v_mfma_f32_16x16x32_bf16 v[76:79], v[152:155], v[224:227], v[76:79]
	v_mfma_f32_16x16x32_bf16 v[72:75], v[166:169], v[224:227], v[72:75]
	v_mfma_f32_16x16x32_bf16 v[124:127], v[156:159], v[204:207], v[124:127]
	v_mfma_f32_16x16x32_bf16 v[120:123], v[176:179], v[204:207], v[120:123]
	v_mfma_f32_16x16x32_bf16 v[108:111], v[156:159], v[212:215], v[108:111]
	v_mfma_f32_16x16x32_bf16 v[104:107], v[176:179], v[212:215], v[104:107]
	v_mfma_f32_16x16x32_bf16 v[92:95], v[156:159], v[220:223], v[92:95]
	v_mfma_f32_16x16x32_bf16 v[88:91], v[176:179], v[220:223], v[88:91]
	v_mfma_f32_16x16x32_bf16 v[76:79], v[156:159], v[228:231], v[76:79]
	v_mfma_f32_16x16x32_bf16 v[72:75], v[176:179], v[228:231], v[72:75]
	v_mfma_f32_16x16x32_bf16 v[116:119], v[180:183], v[200:203], v[116:119]
	v_mfma_f32_16x16x32_bf16 v[112:115], v[188:191], v[200:203], v[112:115]
	v_mfma_f32_16x16x32_bf16 v[100:103], v[180:183], v[208:211], v[100:103]
	v_mfma_f32_16x16x32_bf16 v[96:99], v[188:191], v[208:211], v[96:99]
	v_mfma_f32_16x16x32_bf16 v[84:87], v[180:183], v[216:219], v[84:87]
	v_mfma_f32_16x16x32_bf16 v[80:83], v[188:191], v[216:219], v[80:83]
	v_mfma_f32_16x16x32_bf16 v[68:71], v[180:183], v[224:227], v[68:71]
	v_mfma_f32_16x16x32_bf16 v[64:67], v[188:191], v[224:227], v[64:67]
	v_mfma_f32_16x16x32_bf16 v[116:119], v[184:187], v[204:207], v[116:119]
	v_mfma_f32_16x16x32_bf16 v[112:115], v[196:199], v[204:207], v[112:115]
	v_mfma_f32_16x16x32_bf16 v[100:103], v[184:187], v[212:215], v[100:103]
	v_mfma_f32_16x16x32_bf16 v[96:99], v[196:199], v[212:215], v[96:99]
	v_mfma_f32_16x16x32_bf16 v[84:87], v[184:187], v[220:223], v[84:87]
	v_mfma_f32_16x16x32_bf16 v[80:83], v[196:199], v[220:223], v[80:83]
	v_mfma_f32_16x16x32_bf16 v[68:71], v[184:187], v[228:231], v[68:71]
	v_mfma_f32_16x16x32_bf16 v[64:67], v[196:199], v[228:231], v[64:67]
	s_barrier
	s_add_i32 s6, s73, s30
	s_add_u32 s98, s78, 0x80
	s_addc_u32 s99, s79, 0
	s_add_u32 s100, s80, 0x80
	s_addc_u32 s101, s81, 0
	s_mov_b32 m0, s6
	ds_read_b128 v[200:203], v174 offset:49152
	ds_read_b128 v[204:207], v174 offset:50176
	ds_read_b128 v[208:211], v174 offset:51200
	ds_read_b128 v[212:215], v174 offset:52224
	ds_read_b128 v[216:219], v174 offset:53248
	ds_read_b128 v[220:223], v174 offset:54272
	ds_read_b128 v[224:227], v174 offset:55296
	ds_read_b128 v[228:231], v174 offset:56320
	global_load_lds_dwordx4 v134, s[98:99]
	s_add_i32 m0, s6, 0x2000
	s_add_u32 s6, s78, 0x40080
	s_addc_u32 s7, s79, 0
	s_add_i32 s73, s82, s30
	global_load_lds_dwordx4 v138, s[98:99]
	s_mov_b32 m0, s73
	s_nop 0
	global_load_lds_dwordx4 v134, s[6:7]
	s_add_i32 m0, s73, 0x2000
	s_nop 0
	global_load_lds_dwordx4 v138, s[6:7]
	s_mov_b32 m0, s67
	s_nop 0
	global_load_lds_dwordx4 v132, s[100:101]
	s_mov_b32 m0, s68
	s_nop 0
	global_load_lds_dwordx4 v136, s[100:101]
	s_waitcnt vmcnt(8)
	s_waitcnt lgkmcnt(0)
	s_barrier
	v_mfma_f32_16x16x32_bf16 v[60:63], v[152:155], v[200:203], v[60:63]
	v_mfma_f32_16x16x32_bf16 v[56:59], v[166:169], v[200:203], v[56:59]
	v_mfma_f32_16x16x32_bf16 v[44:47], v[152:155], v[208:211], v[44:47]
	v_mfma_f32_16x16x32_bf16 v[40:43], v[166:169], v[208:211], v[40:43]
	v_mfma_f32_16x16x32_bf16 v[28:31], v[152:155], v[216:219], v[28:31]
	v_mfma_f32_16x16x32_bf16 v[24:27], v[166:169], v[216:219], v[24:27]
	v_mfma_f32_16x16x32_bf16 v[12:15], v[152:155], v[224:227], v[12:15]
	v_mfma_f32_16x16x32_bf16 v[8:11], v[166:169], v[224:227], v[8:11]
	v_mfma_f32_16x16x32_bf16 v[60:63], v[156:159], v[204:207], v[60:63]
	v_mfma_f32_16x16x32_bf16 v[56:59], v[176:179], v[204:207], v[56:59]
	v_mfma_f32_16x16x32_bf16 v[44:47], v[156:159], v[212:215], v[44:47]
	v_mfma_f32_16x16x32_bf16 v[40:43], v[176:179], v[212:215], v[40:43]
	v_mfma_f32_16x16x32_bf16 v[28:31], v[156:159], v[220:223], v[28:31]
	v_mfma_f32_16x16x32_bf16 v[24:27], v[176:179], v[220:223], v[24:27]
	v_mfma_f32_16x16x32_bf16 v[12:15], v[156:159], v[228:231], v[12:15]
	v_mfma_f32_16x16x32_bf16 v[8:11], v[176:179], v[228:231], v[8:11]
	v_mfma_f32_16x16x32_bf16 v[52:55], v[180:183], v[200:203], v[52:55]
	v_mfma_f32_16x16x32_bf16 v[48:51], v[188:191], v[200:203], v[48:51]
	v_mfma_f32_16x16x32_bf16 v[36:39], v[180:183], v[208:211], v[36:39]
	v_mfma_f32_16x16x32_bf16 v[32:35], v[188:191], v[208:211], v[32:35]
	v_mfma_f32_16x16x32_bf16 v[20:23], v[180:183], v[216:219], v[20:23]
	v_mfma_f32_16x16x32_bf16 v[16:19], v[188:191], v[216:219], v[16:19]
	v_mfma_f32_16x16x32_bf16 v[4:7], v[180:183], v[224:227], v[4:7]
	v_mfma_f32_16x16x32_bf16 v[0:3], v[188:191], v[224:227], v[0:3]
	v_mfma_f32_16x16x32_bf16 v[52:55], v[184:187], v[204:207], v[52:55]
	v_mfma_f32_16x16x32_bf16 v[48:51], v[196:199], v[204:207], v[48:51]
	v_mfma_f32_16x16x32_bf16 v[36:39], v[184:187], v[212:215], v[36:39]
	v_mfma_f32_16x16x32_bf16 v[32:35], v[196:199], v[212:215], v[32:35]
	v_mfma_f32_16x16x32_bf16 v[20:23], v[184:187], v[220:223], v[20:23]
	v_mfma_f32_16x16x32_bf16 v[16:19], v[196:199], v[220:223], v[16:19]
	v_mfma_f32_16x16x32_bf16 v[4:7], v[184:187], v[228:231], v[4:7]
	v_mfma_f32_16x16x32_bf16 v[0:3], v[196:199], v[228:231], v[0:3]
	s_barrier
	s_add_i32 s72, s72, 2
	s_add_u32 s60, s60, 0x100
	s_addc_u32 s61, s61, 0
	s_add_u32 vcc_hi, vcc_hi, 0x100
	s_addc_u32 s33, s33, 0
	s_cmp_gt_u32 s72, 13
	s_cbranch_scc0 .LBB0_463
	s_and_b64 vcc, exec, s[50:51]
	s_cbranch_vccz .LBB0_466
	s_barrier

; #define PG8_STAGE(bufoff, gbase, voff) do { _Pragma("unroll") for (int _i = 0; _i < 2; ++_i) \
;         __builtin_amdgcn_global_load_lds((const unsigned*)((const char*)(gbase) + (voff)[_i]), (PG8_LAS unsigned*)(lds + (bufoff) + ldsw + _i * 8192), 16, 0, 0); } while (0)
; #define PG8_LDA(dst, b, h) do { _Pragma("unroll") for (int m = 0; m < 4; ++m) _Pragma("unroll") for (int k = 0; k < 2; ++k) dst[m][k] = *(const PG8_LAS bf16x8*)(lds + PG8_SA(b, h) + aoff + m * 2048 + k * 1024); } while (0)
; #define PG8_LDB(dst, b, h) do { _Pragma("unroll") for (int n = 0; n < 2; ++n) _Pragma("unroll") for (int k = 0; k < 2; ++k) dst[n][k] = *(const PG8_LAS bf16x8*)(lds + PG8_SB(b, h) + boff + n * 2048 + k * 1024); } while (0)
; #define PG8_MMA(ai, bj, At, Bt) do { __builtin_amdgcn_s_setprio(1); _Pragma("unroll") for (int m = 0; m < 4; ++m) _Pragma("unroll") for (int n = 0; n < 2; ++n) _Pragma("unroll") for (int k = 0; k < 2; ++k) \
;         acc[ai][bj][m][n] = __builtin_amdgcn_mfma_f32_16x16x32_bf16(Bt[n][k], At[m][k], acc[ai][bj][m][n], 0, 0, 0); __builtin_amdgcn_s_setprio(0); } while (0)
; #define PG8_WAIT_V(n) asm volatile("s_waitcnt vmcnt(" #n ")" ::: "memory")
; #define PG8_BAR __builtin_amdgcn_s_barrier()
; template <class Epi, class Sched, bool ALIGN_EPI = false, bool SP2 = false>
; __device__ __forceinline__ void gemm_phase(PG8_LAS unsigned char* lds, const Gemm g, const Sched& S, const Epi& E) {
;     ...
;         for (int t = 0; t < nt; t += 2) {
;             const bool last = (t == nt - 2);
;             const char* a1 = cA + (size_t)(t + 1) * kstep;
;             const char* a2 = last ? nA : cA + (size_t)(t + 2) * kstep; const char* b2 = last ? nB : cB + (size_t)(t + 2) * kstep;
;             const char* a3 = a2 + kstep; const char* b3 = b2 + kstep;
;             if (last && has_next) S.a_ready(nxt);
;             if constexpr (SP2) {
;             PG8_LDB(B0, 0, 0); PG8_LDB(B1, 0, 1); PG8_SCHED; PG8_LDA(At, 0, 0); PG8_STAGE(PG8_SA(1, 1), a1 + hstep, voffA);
;             PG8_WAIT_V(8); PG8_WAIT_L(0); PG8_BAR; PG8_MMA(0, 0, At, B0); PG8_MMA(0, 1, At, B1); PG8_BAR; PG8_SCHED;
;             PG8_LDA(At, 0, 1); PG8_STAGE(PG8_SB(0, 0), b2, voffB); PG8_STAGE(PG8_SB(0, 1), b2 + hstep, voffB); PG8_STAGE(PG8_SA(0, 0), a2, voffA);
;             PG8_WAIT_V(8); PG8_WAIT_L(0); PG8_BAR; PG8_MMA(1, 0, At, B0); PG8_MMA(1, 1, At, B1); PG8_BAR; PG8_SCHED;
.LBB0_777:
	ds_read_b128 v[144:147], v158
	ds_read_b128 v[168:171], v158 offset:1024
	ds_read_b128 v[172:175], v158 offset:2048
	ds_read_b128 v[176:179], v158 offset:3072
	ds_read_b128 v[180:183], v159
	ds_read_b128 v[184:187], v159 offset:1024
	ds_read_b128 v[188:191], v159 offset:2048
	ds_read_b128 v[196:199], v159 offset:3072
	s_add_u32 s60, s58, 0x100
	s_addc_u32 s61, s59, 0
	s_cmp_eq_u32 s72, 8
	s_cselect_b32 s81, s49, s61
	s_cselect_b32 s80, s48, s60
	s_cselect_b32 s79, s57, vcc_lo
	s_cselect_b32 s78, s56, s33
	s_add_i32 m0, s76, 0xc000
	ds_read_b128 v[200:203], v163
	ds_read_b128 v[204:207], v163 offset:1024
	ds_read_b128 v[208:211], v163 offset:2048
	ds_read_b128 v[212:215], v163 offset:3072
	ds_read_b128 v[216:219], v163 offset:4096
	ds_read_b128 v[220:223], v163 offset:5120
	ds_read_b128 v[224:227], v163 offset:6144
	ds_read_b128 v[228:231], v163 offset:7168
	global_load_lds_dwordx4 v136, s[58:59]
	s_add_i32 m0, s76, 0xe000
	s_nop 0
	global_load_lds_dwordx4 v138, s[58:59]
	s_waitcnt vmcnt(8)
	s_waitcnt lgkmcnt(0)
	s_barrier
	v_mfma_f32_16x16x32_bf16 v[124:127], v[144:147], v[200:203], v[124:127]
	v_mfma_f32_16x16x32_bf16 v[120:123], v[172:175], v[200:203], v[120:123]
	v_mfma_f32_16x16x32_bf16 v[108:111], v[144:147], v[208:211], v[108:111]
	v_mfma_f32_16x16x32_bf16 v[104:107], v[172:175], v[208:211], v[104:107]
	v_mfma_f32_16x16x32_bf16 v[92:95], v[144:147], v[216:219], v[92:95]
	v_mfma_f32_16x16x32_bf16 v[88:91], v[172:175], v[216:219], v[88:91]
	v_mfma_f32_16x16x32_bf16 v[76:79], v[144:147], v[224:227], v[76:79]
	v_mfma_f32_16x16x32_bf16 v[72:75], v[172:175], v[224:227], v[72:75]
	v_mfma_f32_16x16x32_bf16 v[124:127], v[168:171], v[204:207], v[124:127]
	v_mfma_f32_16x16x32_bf16 v[120:123], v[176:179], v[204:207], v[120:123]
	v_mfma_f32_16x16x32_bf16 v[108:111], v[168:171], v[212:215], v[108:111]
	v_mfma_f32_16x16x32_bf16 v[104:107], v[176:179], v[212:215], v[104:107]
	v_mfma_f32_16x16x32_bf16 v[92:95], v[168:171], v[220:223], v[92:95]
	v_mfma_f32_16x16x32_bf16 v[88:91], v[176:179], v[220:223], v[88:91]
	v_mfma_f32_16x16x32_bf16 v[76:79], v[168:171], v[228:231], v[76:79]
	v_mfma_f32_16x16x32_bf16 v[72:75], v[176:179], v[228:231], v[72:75]
	v_mfma_f32_16x16x32_bf16 v[116:119], v[180:183], v[200:203], v[116:119]
	v_mfma_f32_16x16x32_bf16 v[112:115], v[188:191], v[200:203], v[112:115]
	v_mfma_f32_16x16x32_bf16 v[100:103], v[180:183], v[208:211], v[100:103]
	v_mfma_f32_16x16x32_bf16 v[96:99], v[188:191], v[208:211], v[96:99]
	v_mfma_f32_16x16x32_bf16 v[84:87], v[180:183], v[216:219], v[84:87]
	v_mfma_f32_16x16x32_bf16 v[80:83], v[188:191], v[216:219], v[80:83]
	v_mfma_f32_16x16x32_bf16 v[68:71], v[180:183], v[224:227], v[68:71]
	v_mfma_f32_16x16x32_bf16 v[64:67], v[188:191], v[224:227], v[64:67]
	v_mfma_f32_16x16x32_bf16 v[116:119], v[184:187], v[204:207], v[116:119]
	v_mfma_f32_16x16x32_bf16 v[112:115], v[196:199], v[204:207], v[112:115]
	v_mfma_f32_16x16x32_bf16 v[100:103], v[184:187], v[212:215], v[100:103]
	v_mfma_f32_16x16x32_bf16 v[96:99], v[196:199], v[212:215], v[96:99]
	v_mfma_f32_16x16x32_bf16 v[84:87], v[184:187], v[220:223], v[84:87]
	v_mfma_f32_16x16x32_bf16 v[80:83], v[196:199], v[220:223], v[80:83]
	v_mfma_f32_16x16x32_bf16 v[68:71], v[184:187], v[228:231], v[68:71]
	v_mfma_f32_16x16x32_bf16 v[64:67], v[196:199], v[228:231], v[64:67]
	s_barrier
	s_add_i32 s6, s26, s67
	s_mov_b32 m0, s6
	ds_read_b128 v[200:203], v163 offset:16384
	ds_read_b128 v[204:207], v163 offset:17408
	ds_read_b128 v[208:211], v163 offset:18432
	ds_read_b128 v[212:215], v163 offset:19456
	ds_read_b128 v[216:219], v163 offset:20480
	ds_read_b128 v[220:223], v163 offset:21504
	ds_read_b128 v[224:227], v163 offset:22528
	ds_read_b128 v[228:231], v163 offset:23552
	global_load_lds_dwordx4 v130, s[78:79]
	s_add_i32 m0, s6, 0x2000
	s_add_u32 s6, s78, 0x30000
	s_addc_u32 s7, s79, 0
	s_add_i32 s58, s74, s67
	global_load_lds_dwordx4 v134, s[78:79]
	s_mov_b32 m0, s58
	s_nop 0
	global_load_lds_dwordx4 v130, s[6:7]
	s_add_i32 m0, s58, 0x2000
	s_nop 0
	global_load_lds_dwordx4 v134, s[6:7]
	s_mov_b32 m0, s76
	s_nop 0
	global_load_lds_dwordx4 v128, s[80:81]
	s_mov_b32 m0, s77
	s_nop 0
	global_load_lds_dwordx4 v132, s[80:81]
	s_waitcnt vmcnt(8)
	s_waitcnt lgkmcnt(0)
	s_barrier
	v_mfma_f32_16x16x32_bf16 v[60:63], v[144:147], v[200:203], v[60:63]
	v_mfma_f32_16x16x32_bf16 v[56:59], v[172:175], v[200:203], v[56:59]
	v_mfma_f32_16x16x32_bf16 v[44:47], v[144:147], v[208:211], v[44:47]
	v_mfma_f32_16x16x32_bf16 v[40:43], v[172:175], v[208:211], v[40:43]
	v_mfma_f32_16x16x32_bf16 v[28:31], v[144:147], v[216:219], v[28:31]
	v_mfma_f32_16x16x32_bf16 v[24:27], v[172:175], v[216:219], v[24:27]
	v_mfma_f32_16x16x32_bf16 v[12:15], v[144:147], v[224:227], v[12:15]
	v_mfma_f32_16x16x32_bf16 v[8:11], v[172:175], v[224:227], v[8:11]
	v_mfma_f32_16x16x32_bf16 v[60:63], v[168:171], v[204:207], v[60:63]
	v_mfma_f32_16x16x32_bf16 v[56:59], v[176:179], v[204:207], v[56:59]
	v_mfma_f32_16x16x32_bf16 v[44:47], v[168:171], v[212:215], v[44:47]
	v_mfma_f32_16x16x32_bf16 v[40:43], v[176:179], v[212:215], v[40:43]
	v_mfma_f32_16x16x32_bf16 v[28:31], v[168:171], v[220:223], v[28:31]
	v_mfma_f32_16x16x32_bf16 v[24:27], v[176:179], v[220:223], v[24:27]
	v_mfma_f32_16x16x32_bf16 v[12:15], v[168:171], v[228:231], v[12:15]
	v_mfma_f32_16x16x32_bf16 v[8:11], v[176:179], v[228:231], v[8:11]
	v_mfma_f32_16x16x32_bf16 v[52:55], v[180:183], v[200:203], v[52:55]
	v_mfma_f32_16x16x32_bf16 v[48:51], v[188:191], v[200:203], v[48:51]
	v_mfma_f32_16x16x32_bf16 v[36:39], v[180:183], v[208:211], v[36:39]
	v_mfma_f32_16x16x32_bf16 v[32:35], v[188:191], v[208:211], v[32:35]
	v_mfma_f32_16x16x32_bf16 v[20:23], v[180:183], v[216:219], v[20:23]
	v_mfma_f32_16x16x32_bf16 v[16:19], v[188:191], v[216:219], v[16:19]
	v_mfma_f32_16x16x32_bf16 v[4:7], v[180:183], v[224:227], v[4:7]
	v_mfma_f32_16x16x32_bf16 v[0:3], v[188:191], v[224:227], v[0:3]
	v_mfma_f32_16x16x32_bf16 v[52:55], v[184:187], v[204:207], v[52:55]
	v_mfma_f32_16x16x32_bf16 v[48:51], v[196:199], v[204:207], v[48:51]
	v_mfma_f32_16x16x32_bf16 v[36:39], v[184:187], v[212:215], v[36:39]
	v_mfma_f32_16x16x32_bf16 v[32:35], v[196:199], v[212:215], v[32:35]
	v_mfma_f32_16x16x32_bf16 v[20:23], v[184:187], v[220:223], v[20:23]
	v_mfma_f32_16x16x32_bf16 v[16:19], v[196:199], v[220:223], v[16:19]
	v_mfma_f32_16x16x32_bf16 v[4:7], v[184:187], v[228:231], v[4:7]
	v_mfma_f32_16x16x32_bf16 v[0:3], v[196:199], v[228:231], v[0:3]
	s_barrier
; #define PG8_STAGE(bufoff, gbase, voff) do { _Pragma("unroll") for (int _i = 0; _i < 2; ++_i) \
;         __builtin_amdgcn_global_load_lds((const unsigned*)((const char*)(gbase) + (voff)[_i]), (PG8_LAS unsigned*)(lds + (bufoff) + ldsw + _i * 8192), 16, 0, 0); } while (0)
; #define PG8_LDA(dst, b, h) do { _Pragma("unroll") for (int m = 0; m < 4; ++m) _Pragma("unroll") for (int k = 0; k < 2; ++k) dst[m][k] = *(const PG8_LAS bf16x8*)(lds + PG8_SA(b, h) + aoff + m * 2048 + k * 1024); } while (0)
; #define PG8_LDB(dst, b, h) do { _Pragma("unroll") for (int n = 0; n < 2; ++n) _Pragma("unroll") for (int k = 0; k < 2; ++k) dst[n][k] = *(const PG8_LAS bf16x8*)(lds + PG8_SB(b, h) + boff + n * 2048 + k * 1024); } while (0)
; #define PG8_MMA(ai, bj, At, Bt) do { __builtin_amdgcn_s_setprio(1); _Pragma("unroll") for (int m = 0; m < 4; ++m) _Pragma("unroll") for (int n = 0; n < 2; ++n) _Pragma("unroll") for (int k = 0; k < 2; ++k) \
;         acc[ai][bj][m][n] = __builtin_amdgcn_mfma_f32_16x16x32_bf16(Bt[n][k], At[m][k], acc[ai][bj][m][n], 0, 0, 0); __builtin_amdgcn_s_setprio(0); } while (0)
; #define PG8_WAIT_V(n) asm volatile("s_waitcnt vmcnt(" #n ")" ::: "memory")
; #define PG8_WAIT_L(n) asm volatile("s_waitcnt lgkmcnt(" #n ")" ::: "memory")
; #define PG8_BAR __builtin_amdgcn_s_barrier()
; #define PG8_SCHED __builtin_amdgcn_sched_barrier(0)
; template <class Epi, class Sched, bool ALIGN_EPI = false, bool SP2 = false>
; __device__ __forceinline__ void gemm_phase(PG8_LAS unsigned char* lds, const Gemm g, const Sched& S, const Epi& E) {
;     ...
;             PG8_LDB(B0, 1, 0); PG8_LDB(B1, 1, 1); PG8_SCHED; PG8_LDA(At, 1, 0); PG8_STAGE(PG8_SA(0, 1), a2 + hstep, voffA);
;             PG8_WAIT_V(8); PG8_WAIT_L(0); PG8_BAR; PG8_MMA(0, 0, At, B0); PG8_MMA(0, 1, At, B1); PG8_BAR; PG8_SCHED;
;             PG8_LDA(At, 1, 1); PG8_STAGE(PG8_SB(1, 0), b3, voffB); PG8_STAGE(PG8_SB(1, 1), b3 + hstep, voffB); PG8_STAGE(PG8_SA(1, 0), a3, voffA);
;             PG8_WAIT_V(8); PG8_WAIT_L(0); PG8_BAR; PG8_MMA(1, 0, At, B0); PG8_MMA(1, 1, At, B1); PG8_BAR; PG8_SCHED;
	s_add_i32 s58, 0, 0x18000
	v_add_u32_e32 v167, s58, v156
	s_add_i32 s59, 0, 0x1c000
	ds_read_b128 v[144:147], v167
	ds_read_b128 v[168:171], v167 offset:1024
	ds_read_b128 v[172:175], v167 offset:2048
	ds_read_b128 v[176:179], v167 offset:3072
	v_add_u32_e32 v167, s59, v156
	ds_read_b128 v[180:183], v167
	ds_read_b128 v[184:187], v167 offset:1024
	ds_read_b128 v[188:191], v167 offset:2048
	ds_read_b128 v[196:199], v167 offset:3072
	s_add_u32 s6, s80, 0x30000
	s_addc_u32 s7, s81, 0
	s_mov_b32 m0, s36
	ds_read_b128 v[200:203], v163 offset:32768
	ds_read_b128 v[204:207], v163 offset:33792
	ds_read_b128 v[208:211], v163 offset:34816
	ds_read_b128 v[212:215], v163 offset:35840
	ds_read_b128 v[216:219], v163 offset:36864
	ds_read_b128 v[220:223], v163 offset:37888
	ds_read_b128 v[224:227], v163 offset:38912
	ds_read_b128 v[228:231], v163 offset:39936
	global_load_lds_dwordx4 v128, s[6:7]
	s_mov_b32 m0, s37
	s_nop 0
	global_load_lds_dwordx4 v132, s[6:7]
	s_waitcnt vmcnt(8)
	s_waitcnt lgkmcnt(0)
	s_barrier
	v_mfma_f32_16x16x32_bf16 v[124:127], v[144:147], v[200:203], v[124:127]
	v_mfma_f32_16x16x32_bf16 v[120:123], v[172:175], v[200:203], v[120:123]
	v_mfma_f32_16x16x32_bf16 v[108:111], v[144:147], v[208:211], v[108:111]
	v_mfma_f32_16x16x32_bf16 v[104:107], v[172:175], v[208:211], v[104:107]
	v_mfma_f32_16x16x32_bf16 v[92:95], v[144:147], v[216:219], v[92:95]
	v_mfma_f32_16x16x32_bf16 v[88:91], v[172:175], v[216:219], v[88:91]
	v_mfma_f32_16x16x32_bf16 v[76:79], v[144:147], v[224:227], v[76:79]
	v_mfma_f32_16x16x32_bf16 v[72:75], v[172:175], v[224:227], v[72:75]
	v_mfma_f32_16x16x32_bf16 v[124:127], v[168:171], v[204:207], v[124:127]
	v_mfma_f32_16x16x32_bf16 v[120:123], v[176:179], v[204:207], v[120:123]
	v_mfma_f32_16x16x32_bf16 v[108:111], v[168:171], v[212:215], v[108:111]
	v_mfma_f32_16x16x32_bf16 v[104:107], v[176:179], v[212:215], v[104:107]
	v_mfma_f32_16x16x32_bf16 v[92:95], v[168:171], v[220:223], v[92:95]
	v_mfma_f32_16x16x32_bf16 v[88:91], v[176:179], v[220:223], v[88:91]
	v_mfma_f32_16x16x32_bf16 v[76:79], v[168:171], v[228:231], v[76:79]
	v_mfma_f32_16x16x32_bf16 v[72:75], v[176:179], v[228:231], v[72:75]
	v_mfma_f32_16x16x32_bf16 v[116:119], v[180:183], v[200:203], v[116:119]
	v_mfma_f32_16x16x32_bf16 v[112:115], v[188:191], v[200:203], v[112:115]
	v_mfma_f32_16x16x32_bf16 v[100:103], v[180:183], v[208:211], v[100:103]
	v_mfma_f32_16x16x32_bf16 v[96:99], v[188:191], v[208:211], v[96:99]
	v_mfma_f32_16x16x32_bf16 v[84:87], v[180:183], v[216:219], v[84:87]
	v_mfma_f32_16x16x32_bf16 v[80:83], v[188:191], v[216:219], v[80:83]
	v_mfma_f32_16x16x32_bf16 v[68:71], v[180:183], v[224:227], v[68:71]
	v_mfma_f32_16x16x32_bf16 v[64:67], v[188:191], v[224:227], v[64:67]
	v_mfma_f32_16x16x32_bf16 v[116:119], v[184:187], v[204:207], v[116:119]
	v_mfma_f32_16x16x32_bf16 v[112:115], v[196:199], v[204:207], v[112:115]
	v_mfma_f32_16x16x32_bf16 v[100:103], v[184:187], v[212:215], v[100:103]
	v_mfma_f32_16x16x32_bf16 v[96:99], v[196:199], v[212:215], v[96:99]
	v_mfma_f32_16x16x32_bf16 v[84:87], v[184:187], v[220:223], v[84:87]
	v_mfma_f32_16x16x32_bf16 v[80:83], v[196:199], v[220:223], v[80:83]
	v_mfma_f32_16x16x32_bf16 v[68:71], v[184:187], v[228:231], v[68:71]
	v_mfma_f32_16x16x32_bf16 v[64:67], v[196:199], v[228:231], v[64:67]
	s_barrier
	s_add_i32 s6, s58, s67
	s_add_u32 s98, s78, 0x80
	s_addc_u32 s99, s79, 0
	s_add_u32 s100, s80, 0x80
	s_addc_u32 s101, s81, 0
	s_mov_b32 m0, s6
	ds_read_b128 v[200:203], v163 offset:49152
	ds_read_b128 v[204:207], v163 offset:50176
	ds_read_b128 v[208:211], v163 offset:51200
	ds_read_b128 v[212:215], v163 offset:52224
	ds_read_b128 v[216:219], v163 offset:53248
	ds_read_b128 v[220:223], v163 offset:54272
	ds_read_b128 v[224:227], v163 offset:55296
	ds_read_b128 v[228:231], v163 offset:56320
	global_load_lds_dwordx4 v130, s[98:99]
	s_add_i32 m0, s6, 0x2000
	s_add_u32 s6, s78, 0x30080
	s_addc_u32 s7, s79, 0
	s_add_i32 s58, s59, s67
	global_load_lds_dwordx4 v134, s[98:99]
	s_mov_b32 m0, s58
	s_nop 0
	global_load_lds_dwordx4 v130, s[6:7]
	s_add_i32 m0, s58, 0x2000
	s_nop 0
	global_load_lds_dwordx4 v134, s[6:7]
	s_mov_b32 m0, s31
	s_nop 0
	global_load_lds_dwordx4 v128, s[100:101]
	s_mov_b32 m0, s4
	s_nop 0
	global_load_lds_dwordx4 v132, s[100:101]
	s_waitcnt vmcnt(8)
	s_waitcnt lgkmcnt(0)
	s_barrier
	v_mfma_f32_16x16x32_bf16 v[60:63], v[144:147], v[200:203], v[60:63]
	v_mfma_f32_16x16x32_bf16 v[56:59], v[172:175], v[200:203], v[56:59]
	v_mfma_f32_16x16x32_bf16 v[44:47], v[144:147], v[208:211], v[44:47]
	v_mfma_f32_16x16x32_bf16 v[40:43], v[172:175], v[208:211], v[40:43]
	v_mfma_f32_16x16x32_bf16 v[28:31], v[144:147], v[216:219], v[28:31]
	v_mfma_f32_16x16x32_bf16 v[24:27], v[172:175], v[216:219], v[24:27]
	v_mfma_f32_16x16x32_bf16 v[12:15], v[144:147], v[224:227], v[12:15]
	v_mfma_f32_16x16x32_bf16 v[8:11], v[172:175], v[224:227], v[8:11]
	v_mfma_f32_16x16x32_bf16 v[60:63], v[168:171], v[204:207], v[60:63]
	v_mfma_f32_16x16x32_bf16 v[56:59], v[176:179], v[204:207], v[56:59]
	v_mfma_f32_16x16x32_bf16 v[44:47], v[168:171], v[212:215], v[44:47]
	v_mfma_f32_16x16x32_bf16 v[40:43], v[176:179], v[212:215], v[40:43]
	v_mfma_f32_16x16x32_bf16 v[28:31], v[168:171], v[220:223], v[28:31]
	v_mfma_f32_16x16x32_bf16 v[24:27], v[176:179], v[220:223], v[24:27]
	v_mfma_f32_16x16x32_bf16 v[12:15], v[168:171], v[228:231], v[12:15]
	v_mfma_f32_16x16x32_bf16 v[8:11], v[176:179], v[228:231], v[8:11]
	v_mfma_f32_16x16x32_bf16 v[52:55], v[180:183], v[200:203], v[52:55]
	v_mfma_f32_16x16x32_bf16 v[48:51], v[188:191], v[200:203], v[48:51]
	v_mfma_f32_16x16x32_bf16 v[36:39], v[180:183], v[208:211], v[36:39]
	v_mfma_f32_16x16x32_bf16 v[32:35], v[188:191], v[208:211], v[32:35]
	v_mfma_f32_16x16x32_bf16 v[20:23], v[180:183], v[216:219], v[20:23]
	v_mfma_f32_16x16x32_bf16 v[16:19], v[188:191], v[216:219], v[16:19]
	v_mfma_f32_16x16x32_bf16 v[4:7], v[180:183], v[224:227], v[4:7]
	v_mfma_f32_16x16x32_bf16 v[0:3], v[188:191], v[224:227], v[0:3]
	v_mfma_f32_16x16x32_bf16 v[52:55], v[184:187], v[204:207], v[52:55]
	v_mfma_f32_16x16x32_bf16 v[48:51], v[196:199], v[204:207], v[48:51]
	v_mfma_f32_16x16x32_bf16 v[36:39], v[184:187], v[212:215], v[36:39]
	v_mfma_f32_16x16x32_bf16 v[32:35], v[196:199], v[212:215], v[32:35]
	v_mfma_f32_16x16x32_bf16 v[20:23], v[184:187], v[220:223], v[20:23]
	v_mfma_f32_16x16x32_bf16 v[16:19], v[196:199], v[220:223], v[16:19]
	v_mfma_f32_16x16x32_bf16 v[4:7], v[184:187], v[228:231], v[4:7]
	v_mfma_f32_16x16x32_bf16 v[0:3], v[196:199], v[228:231], v[0:3]
	s_barrier
	s_add_i32 s72, s72, 2
	s_add_u32 s33, s33, 0x100
	s_addc_u32 vcc_lo, vcc_lo, 0
	s_cmp_gt_u32 s72, 9
	s_mov_b64 s[58:59], s[60:61]
	s_cbranch_scc0 .LBB0_777
	s_and_b64 vcc, exec, s[54:55]
	s_cbranch_vccz .LBB0_780
	s_barrier

; #define PG8_STAGE(bufoff, gbase, voff) do { _Pragma("unroll") for (int _i = 0; _i < 2; ++_i) \
;         __builtin_amdgcn_global_load_lds((const unsigned*)((const char*)(gbase) + (voff)[_i]), (PG8_LAS unsigned*)(lds + (bufoff) + ldsw + _i * 8192), 16, 0, 0); } while (0)
; #define PG8_LDA(dst, b, h) do { _Pragma("unroll") for (int m = 0; m < 4; ++m) _Pragma("unroll") for (int k = 0; k < 2; ++k) dst[m][k] = *(const PG8_LAS bf16x8*)(lds + PG8_SA(b, h) + aoff + m * 2048 + k * 1024); } while (0)
; #define PG8_LDB(dst, b, h) do { _Pragma("unroll") for (int n = 0; n < 2; ++n) _Pragma("unroll") for (int k = 0; k < 2; ++k) dst[n][k] = *(const PG8_LAS bf16x8*)(lds + PG8_SB(b, h) + boff + n * 2048 + k * 1024); } while (0)
; #define PG8_MMA(ai, bj, At, Bt) do { __builtin_amdgcn_s_setprio(1); _Pragma("unroll") for (int m = 0; m < 4; ++m) _Pragma("unroll") for (int n = 0; n < 2; ++n) _Pragma("unroll") for (int k = 0; k < 2; ++k) \
;         acc[ai][bj][m][n] = __builtin_amdgcn_mfma_f32_16x16x32_bf16(Bt[n][k], At[m][k], acc[ai][bj][m][n], 0, 0, 0); __builtin_amdgcn_s_setprio(0); } while (0)
; #define PG8_WAIT_V(n) asm volatile("s_waitcnt vmcnt(" #n ")" ::: "memory")
; #define PG8_BAR __builtin_amdgcn_s_barrier()
; template <class Epi, class Sched, bool ALIGN_EPI = false, bool SP2 = false>
; __device__ __forceinline__ void gemm_phase(PG8_LAS unsigned char* lds, const Gemm g, const Sched& S, const Epi& E) {
;     ...
;         for (int t = 0; t < nt; t += 2) {
;             const bool last = (t == nt - 2);
;             const char* a1 = cA + (size_t)(t + 1) * kstep;
;             const char* a2 = last ? nA : cA + (size_t)(t + 2) * kstep; const char* b2 = last ? nB : cB + (size_t)(t + 2) * kstep;
;             const char* a3 = a2 + kstep; const char* b3 = b2 + kstep;
;             if (last && has_next) S.a_ready(nxt);
;             if constexpr (SP2) {
;             PG8_LDB(B0, 0, 0); PG8_LDB(B1, 0, 1); PG8_SCHED; PG8_LDA(At, 0, 0); PG8_STAGE(PG8_SA(1, 1), a1 + hstep, voffA);
;             PG8_WAIT_V(8); PG8_WAIT_L(0); PG8_BAR; PG8_MMA(0, 0, At, B0); PG8_MMA(0, 1, At, B1); PG8_BAR; PG8_SCHED;
;             PG8_LDA(At, 0, 1); PG8_STAGE(PG8_SB(0, 0), b2, voffB); PG8_STAGE(PG8_SB(0, 1), b2 + hstep, voffB); PG8_STAGE(PG8_SA(0, 0), a2, voffA);
;             PG8_WAIT_V(8); PG8_WAIT_L(0); PG8_BAR; PG8_MMA(1, 0, At, B0); PG8_MMA(1, 1, At, B1); PG8_BAR; PG8_SCHED;
.LBB0_901:
	ds_read_b128 v[144:147], v159
	ds_read_b128 v[168:171], v159 offset:1024
	ds_read_b128 v[172:175], v159 offset:2048
	ds_read_b128 v[176:179], v159 offset:3072
	ds_read_b128 v[180:183], v163
	ds_read_b128 v[184:187], v163 offset:1024
	ds_read_b128 v[188:191], v163 offset:2048
	ds_read_b128 v[196:199], v163 offset:3072
	s_add_u32 s6, s56, 0xfffc0080
	s_addc_u32 s7, s57, -1
	s_cmp_eq_u32 s72, 12
	s_cselect_b32 s61, s49, s7
	s_cselect_b32 s60, s76, s6
	s_cselect_b32 s59, s41, s33
	s_cselect_b32 s58, s77, s78
	s_add_i32 m0, s30, 0xc000
	ds_read_b128 v[200:203], v166
	ds_read_b128 v[204:207], v166 offset:1024
	ds_read_b128 v[208:211], v166 offset:2048
	ds_read_b128 v[212:215], v166 offset:3072
	ds_read_b128 v[216:219], v166 offset:4096
	ds_read_b128 v[220:223], v166 offset:5120
	ds_read_b128 v[224:227], v166 offset:6144
	ds_read_b128 v[228:231], v166 offset:7168
	global_load_lds_dwordx4 v136, s[56:57]
	s_add_i32 m0, s30, 0xe000
	s_nop 0
	global_load_lds_dwordx4 v138, s[56:57]
	s_waitcnt vmcnt(8)
	s_waitcnt lgkmcnt(0)
	s_barrier
	v_mfma_f32_16x16x32_bf16 v[124:127], v[144:147], v[200:203], v[124:127]
	v_mfma_f32_16x16x32_bf16 v[116:119], v[172:175], v[200:203], v[116:119]
	v_mfma_f32_16x16x32_bf16 v[108:111], v[144:147], v[208:211], v[108:111]
	v_mfma_f32_16x16x32_bf16 v[100:103], v[172:175], v[208:211], v[100:103]
	v_mfma_f32_16x16x32_bf16 v[92:95], v[144:147], v[216:219], v[92:95]
	v_mfma_f32_16x16x32_bf16 v[84:87], v[172:175], v[216:219], v[84:87]
	v_mfma_f32_16x16x32_bf16 v[76:79], v[144:147], v[224:227], v[76:79]
	v_mfma_f32_16x16x32_bf16 v[68:71], v[172:175], v[224:227], v[68:71]
	v_mfma_f32_16x16x32_bf16 v[124:127], v[168:171], v[204:207], v[124:127]
	v_mfma_f32_16x16x32_bf16 v[116:119], v[176:179], v[204:207], v[116:119]
	v_mfma_f32_16x16x32_bf16 v[108:111], v[168:171], v[212:215], v[108:111]
	v_mfma_f32_16x16x32_bf16 v[100:103], v[176:179], v[212:215], v[100:103]
	v_mfma_f32_16x16x32_bf16 v[92:95], v[168:171], v[220:223], v[92:95]
	v_mfma_f32_16x16x32_bf16 v[84:87], v[176:179], v[220:223], v[84:87]
	v_mfma_f32_16x16x32_bf16 v[76:79], v[168:171], v[228:231], v[76:79]
	v_mfma_f32_16x16x32_bf16 v[68:71], v[176:179], v[228:231], v[68:71]
	v_mfma_f32_16x16x32_bf16 v[120:123], v[180:183], v[200:203], v[120:123]
	v_mfma_f32_16x16x32_bf16 v[112:115], v[188:191], v[200:203], v[112:115]
	v_mfma_f32_16x16x32_bf16 v[104:107], v[180:183], v[208:211], v[104:107]
	v_mfma_f32_16x16x32_bf16 v[96:99], v[188:191], v[208:211], v[96:99]
	v_mfma_f32_16x16x32_bf16 v[88:91], v[180:183], v[216:219], v[88:91]
	v_mfma_f32_16x16x32_bf16 v[80:83], v[188:191], v[216:219], v[80:83]
	v_mfma_f32_16x16x32_bf16 v[72:75], v[180:183], v[224:227], v[72:75]
	v_mfma_f32_16x16x32_bf16 v[64:67], v[188:191], v[224:227], v[64:67]
	v_mfma_f32_16x16x32_bf16 v[120:123], v[184:187], v[204:207], v[120:123]
	v_mfma_f32_16x16x32_bf16 v[112:115], v[196:199], v[204:207], v[112:115]
	v_mfma_f32_16x16x32_bf16 v[104:107], v[184:187], v[212:215], v[104:107]
	v_mfma_f32_16x16x32_bf16 v[96:99], v[196:199], v[212:215], v[96:99]
	v_mfma_f32_16x16x32_bf16 v[88:91], v[184:187], v[220:223], v[88:91]
	v_mfma_f32_16x16x32_bf16 v[80:83], v[196:199], v[220:223], v[80:83]
	v_mfma_f32_16x16x32_bf16 v[72:75], v[184:187], v[228:231], v[72:75]
	v_mfma_f32_16x16x32_bf16 v[64:67], v[196:199], v[228:231], v[64:67]
	s_barrier
	s_add_i32 s6, s67, s27
	s_mov_b32 m0, s6
	ds_read_b128 v[200:203], v166 offset:16384
	ds_read_b128 v[204:207], v166 offset:17408
	ds_read_b128 v[208:211], v166 offset:18432
	ds_read_b128 v[212:215], v166 offset:19456
	ds_read_b128 v[216:219], v166 offset:20480
	ds_read_b128 v[220:223], v166 offset:21504
	ds_read_b128 v[224:227], v166 offset:22528
	ds_read_b128 v[228:231], v166 offset:23552
	global_load_lds_dwordx4 v132, s[58:59]
	s_add_i32 m0, s6, 0x2000
	s_add_u32 s6, s58, 0x40000
	s_addc_u32 s7, s59, 0
	s_add_i32 s73, s68, s27
	global_load_lds_dwordx4 v128, s[58:59]
	s_mov_b32 m0, s73
	s_nop 0
	global_load_lds_dwordx4 v132, s[6:7]
	s_add_i32 m0, s73, 0x2000
	s_nop 0
	global_load_lds_dwordx4 v128, s[6:7]
	s_mov_b32 m0, s30
	s_nop 0
	global_load_lds_dwordx4 v134, s[60:61]
	s_mov_b32 m0, s31
	s_nop 0
	global_load_lds_dwordx4 v130, s[60:61]
	s_waitcnt vmcnt(8)
	s_waitcnt lgkmcnt(0)
	s_barrier
	v_mfma_f32_16x16x32_bf16 v[60:63], v[144:147], v[200:203], v[60:63]
	v_mfma_f32_16x16x32_bf16 v[52:55], v[172:175], v[200:203], v[52:55]
	v_mfma_f32_16x16x32_bf16 v[44:47], v[144:147], v[208:211], v[44:47]
	v_mfma_f32_16x16x32_bf16 v[36:39], v[172:175], v[208:211], v[36:39]
	v_mfma_f32_16x16x32_bf16 v[28:31], v[144:147], v[216:219], v[28:31]
	v_mfma_f32_16x16x32_bf16 v[20:23], v[172:175], v[216:219], v[20:23]
	v_mfma_f32_16x16x32_bf16 v[12:15], v[144:147], v[224:227], v[12:15]
	v_mfma_f32_16x16x32_bf16 v[4:7], v[172:175], v[224:227], v[4:7]
	v_mfma_f32_16x16x32_bf16 v[60:63], v[168:171], v[204:207], v[60:63]
	v_mfma_f32_16x16x32_bf16 v[52:55], v[176:179], v[204:207], v[52:55]
	v_mfma_f32_16x16x32_bf16 v[44:47], v[168:171], v[212:215], v[44:47]
	v_mfma_f32_16x16x32_bf16 v[36:39], v[176:179], v[212:215], v[36:39]
	v_mfma_f32_16x16x32_bf16 v[28:31], v[168:171], v[220:223], v[28:31]
	v_mfma_f32_16x16x32_bf16 v[20:23], v[176:179], v[220:223], v[20:23]
	v_mfma_f32_16x16x32_bf16 v[12:15], v[168:171], v[228:231], v[12:15]
	v_mfma_f32_16x16x32_bf16 v[4:7], v[176:179], v[228:231], v[4:7]
	v_mfma_f32_16x16x32_bf16 v[56:59], v[180:183], v[200:203], v[56:59]
	v_mfma_f32_16x16x32_bf16 v[48:51], v[188:191], v[200:203], v[48:51]
	v_mfma_f32_16x16x32_bf16 v[40:43], v[180:183], v[208:211], v[40:43]
	v_mfma_f32_16x16x32_bf16 v[32:35], v[188:191], v[208:211], v[32:35]
	v_mfma_f32_16x16x32_bf16 v[24:27], v[180:183], v[216:219], v[24:27]
	v_mfma_f32_16x16x32_bf16 v[16:19], v[188:191], v[216:219], v[16:19]
	v_mfma_f32_16x16x32_bf16 v[8:11], v[180:183], v[224:227], v[8:11]
	v_mfma_f32_16x16x32_bf16 v[0:3], v[188:191], v[224:227], v[0:3]
	v_mfma_f32_16x16x32_bf16 v[56:59], v[184:187], v[204:207], v[56:59]
	v_mfma_f32_16x16x32_bf16 v[48:51], v[196:199], v[204:207], v[48:51]
	v_mfma_f32_16x16x32_bf16 v[40:43], v[184:187], v[212:215], v[40:43]
	v_mfma_f32_16x16x32_bf16 v[32:35], v[196:199], v[212:215], v[32:35]
	v_mfma_f32_16x16x32_bf16 v[24:27], v[184:187], v[220:223], v[24:27]
	v_mfma_f32_16x16x32_bf16 v[16:19], v[196:199], v[220:223], v[16:19]
	v_mfma_f32_16x16x32_bf16 v[8:11], v[184:187], v[228:231], v[8:11]
	v_mfma_f32_16x16x32_bf16 v[0:3], v[196:199], v[228:231], v[0:3]
	s_barrier
; #define PG8_STAGE(bufoff, gbase, voff) do { _Pragma("unroll") for (int _i = 0; _i < 2; ++_i) \
;         __builtin_amdgcn_global_load_lds((const unsigned*)((const char*)(gbase) + (voff)[_i]), (PG8_LAS unsigned*)(lds + (bufoff) + ldsw + _i * 8192), 16, 0, 0); } while (0)
; #define PG8_LDA(dst, b, h) do { _Pragma("unroll") for (int m = 0; m < 4; ++m) _Pragma("unroll") for (int k = 0; k < 2; ++k) dst[m][k] = *(const PG8_LAS bf16x8*)(lds + PG8_SA(b, h) + aoff + m * 2048 + k * 1024); } while (0)
; #define PG8_LDB(dst, b, h) do { _Pragma("unroll") for (int n = 0; n < 2; ++n) _Pragma("unroll") for (int k = 0; k < 2; ++k) dst[n][k] = *(const PG8_LAS bf16x8*)(lds + PG8_SB(b, h) + boff + n * 2048 + k * 1024); } while (0)
; #define PG8_MMA(ai, bj, At, Bt) do { __builtin_amdgcn_s_setprio(1); _Pragma("unroll") for (int m = 0; m < 4; ++m) _Pragma("unroll") for (int n = 0; n < 2; ++n) _Pragma("unroll") for (int k = 0; k < 2; ++k) \
;         acc[ai][bj][m][n] = __builtin_amdgcn_mfma_f32_16x16x32_bf16(Bt[n][k], At[m][k], acc[ai][bj][m][n], 0, 0, 0); __builtin_amdgcn_s_setprio(0); } while (0)
; #define PG8_WAIT_V(n) asm volatile("s_waitcnt vmcnt(" #n ")" ::: "memory")
; #define PG8_WAIT_L(n) asm volatile("s_waitcnt lgkmcnt(" #n ")" ::: "memory")
; #define PG8_BAR __builtin_amdgcn_s_barrier()
; #define PG8_SCHED __builtin_amdgcn_sched_barrier(0)
; template <class Epi, class Sched, bool ALIGN_EPI = false, bool SP2 = false>
; __device__ __forceinline__ void gemm_phase(PG8_LAS unsigned char* lds, const Gemm g, const Sched& S, const Epi& E) {
;     ...
;             PG8_LDB(B0, 1, 0); PG8_LDB(B1, 1, 1); PG8_SCHED; PG8_LDA(At, 1, 0); PG8_STAGE(PG8_SA(0, 1), a2 + hstep, voffA);
;             PG8_WAIT_V(8); PG8_WAIT_L(0); PG8_BAR; PG8_MMA(0, 0, At, B0); PG8_MMA(0, 1, At, B1); PG8_BAR; PG8_SCHED;
;             PG8_LDA(At, 1, 1); PG8_STAGE(PG8_SB(1, 0), b3, voffB); PG8_STAGE(PG8_SB(1, 1), b3 + hstep, voffB); PG8_STAGE(PG8_SA(1, 0), a3, voffA);
;             PG8_WAIT_V(8); PG8_WAIT_L(0); PG8_BAR; PG8_MMA(1, 0, At, B0); PG8_MMA(1, 1, At, B1); PG8_BAR; PG8_SCHED;
;     ...
;         }
;         if constexpr (ALIGN_EPI) { if (wr == 0) PG8_BAR; }
	s_add_i32 s73, 0, 0x18000
	v_add_u32_e32 v167, s73, v156
	s_add_i32 s79, 0, 0x1c000
	ds_read_b128 v[144:147], v167
	ds_read_b128 v[168:171], v167 offset:1024
	ds_read_b128 v[172:175], v167 offset:2048
	ds_read_b128 v[176:179], v167 offset:3072
	v_add_u32_e32 v167, s79, v156
	ds_read_b128 v[180:183], v167
	ds_read_b128 v[184:187], v167 offset:1024
	ds_read_b128 v[188:191], v167 offset:2048
	ds_read_b128 v[196:199], v167 offset:3072
	s_add_u32 s6, s60, 0x40000
	s_addc_u32 s7, s61, 0
	s_mov_b32 m0, s42
	ds_read_b128 v[200:203], v166 offset:32768
	ds_read_b128 v[204:207], v166 offset:33792
	ds_read_b128 v[208:211], v166 offset:34816
	ds_read_b128 v[212:215], v166 offset:35840
	ds_read_b128 v[216:219], v166 offset:36864
	ds_read_b128 v[220:223], v166 offset:37888
	ds_read_b128 v[224:227], v166 offset:38912
	ds_read_b128 v[228:231], v166 offset:39936
	global_load_lds_dwordx4 v134, s[6:7]
	s_mov_b32 m0, s43
	s_nop 0
	global_load_lds_dwordx4 v130, s[6:7]
	s_waitcnt vmcnt(8)
	s_waitcnt lgkmcnt(0)
	s_barrier
	v_mfma_f32_16x16x32_bf16 v[124:127], v[144:147], v[200:203], v[124:127]
	v_mfma_f32_16x16x32_bf16 v[116:119], v[172:175], v[200:203], v[116:119]
	v_mfma_f32_16x16x32_bf16 v[108:111], v[144:147], v[208:211], v[108:111]
	v_mfma_f32_16x16x32_bf16 v[100:103], v[172:175], v[208:211], v[100:103]
	v_mfma_f32_16x16x32_bf16 v[92:95], v[144:147], v[216:219], v[92:95]
	v_mfma_f32_16x16x32_bf16 v[84:87], v[172:175], v[216:219], v[84:87]
	v_mfma_f32_16x16x32_bf16 v[76:79], v[144:147], v[224:227], v[76:79]
	v_mfma_f32_16x16x32_bf16 v[68:71], v[172:175], v[224:227], v[68:71]
	v_mfma_f32_16x16x32_bf16 v[124:127], v[168:171], v[204:207], v[124:127]
	v_mfma_f32_16x16x32_bf16 v[116:119], v[176:179], v[204:207], v[116:119]
	v_mfma_f32_16x16x32_bf16 v[108:111], v[168:171], v[212:215], v[108:111]
	v_mfma_f32_16x16x32_bf16 v[100:103], v[176:179], v[212:215], v[100:103]
	v_mfma_f32_16x16x32_bf16 v[92:95], v[168:171], v[220:223], v[92:95]
	v_mfma_f32_16x16x32_bf16 v[84:87], v[176:179], v[220:223], v[84:87]
	v_mfma_f32_16x16x32_bf16 v[76:79], v[168:171], v[228:231], v[76:79]
	v_mfma_f32_16x16x32_bf16 v[68:71], v[176:179], v[228:231], v[68:71]
	v_mfma_f32_16x16x32_bf16 v[120:123], v[180:183], v[200:203], v[120:123]
	v_mfma_f32_16x16x32_bf16 v[112:115], v[188:191], v[200:203], v[112:115]
	v_mfma_f32_16x16x32_bf16 v[104:107], v[180:183], v[208:211], v[104:107]
	v_mfma_f32_16x16x32_bf16 v[96:99], v[188:191], v[208:211], v[96:99]
	v_mfma_f32_16x16x32_bf16 v[88:91], v[180:183], v[216:219], v[88:91]
	v_mfma_f32_16x16x32_bf16 v[80:83], v[188:191], v[216:219], v[80:83]
	v_mfma_f32_16x16x32_bf16 v[72:75], v[180:183], v[224:227], v[72:75]
	v_mfma_f32_16x16x32_bf16 v[64:67], v[188:191], v[224:227], v[64:67]
	v_mfma_f32_16x16x32_bf16 v[120:123], v[184:187], v[204:207], v[120:123]
	v_mfma_f32_16x16x32_bf16 v[112:115], v[196:199], v[204:207], v[112:115]
	v_mfma_f32_16x16x32_bf16 v[104:107], v[184:187], v[212:215], v[104:107]
	v_mfma_f32_16x16x32_bf16 v[96:99], v[196:199], v[212:215], v[96:99]
	v_mfma_f32_16x16x32_bf16 v[88:91], v[184:187], v[220:223], v[88:91]
	v_mfma_f32_16x16x32_bf16 v[80:83], v[196:199], v[220:223], v[80:83]
	v_mfma_f32_16x16x32_bf16 v[72:75], v[184:187], v[228:231], v[72:75]
	v_mfma_f32_16x16x32_bf16 v[64:67], v[196:199], v[228:231], v[64:67]
	s_barrier
	s_add_i32 s6, s73, s27
	s_add_u32 s98, s58, 0x80
	s_addc_u32 s99, s59, 0
	s_add_u32 s100, s60, 0x80
	s_addc_u32 s101, s61, 0
	s_mov_b32 m0, s6
	ds_read_b128 v[200:203], v166 offset:49152
	ds_read_b128 v[204:207], v166 offset:50176
	ds_read_b128 v[208:211], v166 offset:51200
	ds_read_b128 v[212:215], v166 offset:52224
	ds_read_b128 v[216:219], v166 offset:53248
	ds_read_b128 v[220:223], v166 offset:54272
	ds_read_b128 v[224:227], v166 offset:55296
	ds_read_b128 v[228:231], v166 offset:56320
	global_load_lds_dwordx4 v132, s[98:99]
	s_add_i32 m0, s6, 0x2000
	s_add_u32 s6, s58, 0x40080
	s_addc_u32 s7, s59, 0
	s_add_i32 s58, s79, s27
	global_load_lds_dwordx4 v128, s[98:99]
	s_mov_b32 m0, s58
	s_nop 0
	global_load_lds_dwordx4 v132, s[6:7]
	s_add_i32 m0, s58, 0x2000
	s_nop 0
	global_load_lds_dwordx4 v128, s[6:7]
	s_mov_b32 m0, s44
	s_nop 0
	global_load_lds_dwordx4 v134, s[100:101]
	s_mov_b32 m0, s45
	s_nop 0
	global_load_lds_dwordx4 v130, s[100:101]
	s_waitcnt vmcnt(8)
	s_waitcnt lgkmcnt(0)
	s_barrier
	v_mfma_f32_16x16x32_bf16 v[60:63], v[144:147], v[200:203], v[60:63]
	v_mfma_f32_16x16x32_bf16 v[52:55], v[172:175], v[200:203], v[52:55]
	v_mfma_f32_16x16x32_bf16 v[44:47], v[144:147], v[208:211], v[44:47]
	v_mfma_f32_16x16x32_bf16 v[36:39], v[172:175], v[208:211], v[36:39]
	v_mfma_f32_16x16x32_bf16 v[28:31], v[144:147], v[216:219], v[28:31]
	v_mfma_f32_16x16x32_bf16 v[20:23], v[172:175], v[216:219], v[20:23]
	v_mfma_f32_16x16x32_bf16 v[12:15], v[144:147], v[224:227], v[12:15]
	v_mfma_f32_16x16x32_bf16 v[4:7], v[172:175], v[224:227], v[4:7]
	v_mfma_f32_16x16x32_bf16 v[60:63], v[168:171], v[204:207], v[60:63]
	v_mfma_f32_16x16x32_bf16 v[52:55], v[176:179], v[204:207], v[52:55]
	v_mfma_f32_16x16x32_bf16 v[44:47], v[168:171], v[212:215], v[44:47]
	v_mfma_f32_16x16x32_bf16 v[36:39], v[176:179], v[212:215], v[36:39]
	v_mfma_f32_16x16x32_bf16 v[28:31], v[168:171], v[220:223], v[28:31]
	v_mfma_f32_16x16x32_bf16 v[20:23], v[176:179], v[220:223], v[20:23]
	v_mfma_f32_16x16x32_bf16 v[12:15], v[168:171], v[228:231], v[12:15]
	v_mfma_f32_16x16x32_bf16 v[4:7], v[176:179], v[228:231], v[4:7]
	v_mfma_f32_16x16x32_bf16 v[56:59], v[180:183], v[200:203], v[56:59]
	v_mfma_f32_16x16x32_bf16 v[48:51], v[188:191], v[200:203], v[48:51]
	v_mfma_f32_16x16x32_bf16 v[40:43], v[180:183], v[208:211], v[40:43]
	v_mfma_f32_16x16x32_bf16 v[32:35], v[188:191], v[208:211], v[32:35]
	v_mfma_f32_16x16x32_bf16 v[24:27], v[180:183], v[216:219], v[24:27]
	v_mfma_f32_16x16x32_bf16 v[16:19], v[188:191], v[216:219], v[16:19]
	v_mfma_f32_16x16x32_bf16 v[8:11], v[180:183], v[224:227], v[8:11]
	v_mfma_f32_16x16x32_bf16 v[0:3], v[188:191], v[224:227], v[0:3]
	v_mfma_f32_16x16x32_bf16 v[56:59], v[184:187], v[204:207], v[56:59]
	v_mfma_f32_16x16x32_bf16 v[48:51], v[196:199], v[204:207], v[48:51]
	v_mfma_f32_16x16x32_bf16 v[40:43], v[184:187], v[212:215], v[40:43]
	v_mfma_f32_16x16x32_bf16 v[32:35], v[196:199], v[212:215], v[32:35]
	v_mfma_f32_16x16x32_bf16 v[24:27], v[184:187], v[220:223], v[24:27]
	v_mfma_f32_16x16x32_bf16 v[16:19], v[196:199], v[220:223], v[16:19]
	v_mfma_f32_16x16x32_bf16 v[8:11], v[184:187], v[228:231], v[8:11]
	v_mfma_f32_16x16x32_bf16 v[0:3], v[196:199], v[228:231], v[0:3]
	s_barrier
	s_add_i32 s72, s72, 2
	s_add_u32 s56, s56, 0x100
	s_addc_u32 s57, s57, 0
	s_add_u32 s78, s78, 0x100
	s_addc_u32 s33, s33, 0
	s_cmp_gt_u32 s72, 13
	s_cbranch_scc0 .LBB0_901
	s_and_b64 vcc, exec, s[38:39]
	s_cbranch_vccz .LBB0_904
	s_barrier

; #define PG8_STAGE(bufoff, gbase, voff) do { _Pragma("unroll") for (int _i = 0; _i < 2; ++_i) \
;         __builtin_amdgcn_global_load_lds((const unsigned*)((const char*)(gbase) + (voff)[_i]), (PG8_LAS unsigned*)(lds + (bufoff) + ldsw + _i * 8192), 16, 0, 0); } while (0)
; #define PG8_LDA(dst, b, h) do { _Pragma("unroll") for (int m = 0; m < 4; ++m) _Pragma("unroll") for (int k = 0; k < 2; ++k) dst[m][k] = *(const PG8_LAS bf16x8*)(lds + PG8_SA(b, h) + aoff + m * 2048 + k * 1024); } while (0)
; #define PG8_LDB(dst, b, h) do { _Pragma("unroll") for (int n = 0; n < 2; ++n) _Pragma("unroll") for (int k = 0; k < 2; ++k) dst[n][k] = *(const PG8_LAS bf16x8*)(lds + PG8_SB(b, h) + boff + n * 2048 + k * 1024); } while (0)
; #define PG8_MMA(ai, bj, At, Bt) do { __builtin_amdgcn_s_setprio(1); _Pragma("unroll") for (int m = 0; m < 4; ++m) _Pragma("unroll") for (int n = 0; n < 2; ++n) _Pragma("unroll") for (int k = 0; k < 2; ++k) \
;         acc[ai][bj][m][n] = __builtin_amdgcn_mfma_f32_16x16x32_bf16(Bt[n][k], At[m][k], acc[ai][bj][m][n], 0, 0, 0); __builtin_amdgcn_s_setprio(0); } while (0)
; #define PG8_WAIT_V(n) asm volatile("s_waitcnt vmcnt(" #n ")" ::: "memory")
; #define PG8_WAIT_L(n) asm volatile("s_waitcnt lgkmcnt(" #n ")" ::: "memory")
; template <class Epi, class Sched, bool ALIGN_EPI = false, bool SP2 = false>
; __device__ __forceinline__ void gemm_phase(PG8_LAS unsigned char* lds, const Gemm g, const Sched& S, const Epi& E) {
;     ...
;             const bool last = (t == nt - 2);
;             const char* a1 = cA + (size_t)(t + 1) * kstep;
;             const char* a2 = last ? nA : cA + (size_t)(t + 2) * kstep; const char* b2 = last ? nB : cB + (size_t)(t + 2) * kstep;
;             const char* a3 = a2 + kstep; const char* b3 = b2 + kstep;
;             if (last && has_next) S.a_ready(nxt);
;             if constexpr (SP2) {
;             PG8_LDB(B0, 0, 0); PG8_LDB(B1, 0, 1); PG8_SCHED; PG8_LDA(At, 0, 0); PG8_STAGE(PG8_SA(1, 1), a1 + hstep, voffA);
;             PG8_WAIT_V(8); PG8_WAIT_L(0); PG8_BAR; PG8_MMA(0, 0, At, B0); PG8_MMA(0, 1, At, B1); PG8_BAR; PG8_SCHED;
;             PG8_LDA(At, 0, 1); PG8_STAGE(PG8_SB(0, 0), b2, voffB); PG8_STAGE(PG8_SB(0, 1), b2 + hstep, voffB); PG8_STAGE(PG8_SA(0, 0), a2, voffA);
;             PG8_WAIT_V(8); PG8_WAIT_L(0); PG8_BAR; PG8_MMA(1, 0, At, B0); PG8_MMA(1, 1, At, B1); PG8_BAR; PG8_SCHED;
.LBB0_1014:
	ds_read_b128 v[144:147], v158
	ds_read_b128 v[168:171], v158 offset:1024
	ds_read_b128 v[172:175], v158 offset:2048
	ds_read_b128 v[176:179], v158 offset:3072
	ds_read_b128 v[180:183], v159
	ds_read_b128 v[184:187], v159 offset:1024
	ds_read_b128 v[188:191], v159 offset:2048
	ds_read_b128 v[196:199], v159 offset:3072
	s_add_u32 s58, s56, 0x100
	s_addc_u32 s59, s57, 0
	s_cmp_eq_u32 s72, 40
	s_cselect_b32 s79, s51, s59
	s_cselect_b32 s78, s50, s58
	s_cselect_b32 s61, s55, s80
	s_cselect_b32 s60, s54, s33
	s_add_i32 m0, s45, 0xc000
	ds_read_b128 v[200:203], v163
	ds_read_b128 v[204:207], v163 offset:1024
	ds_read_b128 v[208:211], v163 offset:2048
	ds_read_b128 v[212:215], v163 offset:3072
	ds_read_b128 v[216:219], v163 offset:4096
	ds_read_b128 v[220:223], v163 offset:5120
	ds_read_b128 v[224:227], v163 offset:6144
	ds_read_b128 v[228:231], v163 offset:7168
	global_load_lds_dwordx4 v136, s[56:57]
	s_add_i32 m0, s45, 0xe000
	s_nop 0
	global_load_lds_dwordx4 v138, s[56:57]
	s_waitcnt vmcnt(8)
	s_waitcnt lgkmcnt(0)
	s_barrier
	v_mfma_f32_16x16x32_bf16 v[124:127], v[144:147], v[200:203], v[124:127]
	v_mfma_f32_16x16x32_bf16 v[120:123], v[172:175], v[200:203], v[120:123]
	v_mfma_f32_16x16x32_bf16 v[108:111], v[144:147], v[208:211], v[108:111]
	v_mfma_f32_16x16x32_bf16 v[104:107], v[172:175], v[208:211], v[104:107]
	v_mfma_f32_16x16x32_bf16 v[92:95], v[144:147], v[216:219], v[92:95]
	v_mfma_f32_16x16x32_bf16 v[88:91], v[172:175], v[216:219], v[88:91]
	v_mfma_f32_16x16x32_bf16 v[76:79], v[144:147], v[224:227], v[76:79]
	v_mfma_f32_16x16x32_bf16 v[72:75], v[172:175], v[224:227], v[72:75]
	v_mfma_f32_16x16x32_bf16 v[124:127], v[168:171], v[204:207], v[124:127]
	v_mfma_f32_16x16x32_bf16 v[120:123], v[176:179], v[204:207], v[120:123]
	v_mfma_f32_16x16x32_bf16 v[108:111], v[168:171], v[212:215], v[108:111]
	v_mfma_f32_16x16x32_bf16 v[104:107], v[176:179], v[212:215], v[104:107]
	v_mfma_f32_16x16x32_bf16 v[92:95], v[168:171], v[220:223], v[92:95]
	v_mfma_f32_16x16x32_bf16 v[88:91], v[176:179], v[220:223], v[88:91]
	v_mfma_f32_16x16x32_bf16 v[76:79], v[168:171], v[228:231], v[76:79]
	v_mfma_f32_16x16x32_bf16 v[72:75], v[176:179], v[228:231], v[72:75]
	v_mfma_f32_16x16x32_bf16 v[116:119], v[180:183], v[200:203], v[116:119]
	v_mfma_f32_16x16x32_bf16 v[112:115], v[188:191], v[200:203], v[112:115]
	v_mfma_f32_16x16x32_bf16 v[100:103], v[180:183], v[208:211], v[100:103]
	v_mfma_f32_16x16x32_bf16 v[96:99], v[188:191], v[208:211], v[96:99]
	v_mfma_f32_16x16x32_bf16 v[84:87], v[180:183], v[216:219], v[84:87]
	v_mfma_f32_16x16x32_bf16 v[80:83], v[188:191], v[216:219], v[80:83]
	v_mfma_f32_16x16x32_bf16 v[68:71], v[180:183], v[224:227], v[68:71]
	v_mfma_f32_16x16x32_bf16 v[64:67], v[188:191], v[224:227], v[64:67]
	v_mfma_f32_16x16x32_bf16 v[116:119], v[184:187], v[204:207], v[116:119]
	v_mfma_f32_16x16x32_bf16 v[112:115], v[196:199], v[204:207], v[112:115]
	v_mfma_f32_16x16x32_bf16 v[100:103], v[184:187], v[212:215], v[100:103]
	v_mfma_f32_16x16x32_bf16 v[96:99], v[196:199], v[212:215], v[96:99]
	v_mfma_f32_16x16x32_bf16 v[84:87], v[184:187], v[220:223], v[84:87]
	v_mfma_f32_16x16x32_bf16 v[80:83], v[196:199], v[220:223], v[80:83]
	v_mfma_f32_16x16x32_bf16 v[68:71], v[184:187], v[228:231], v[68:71]
	v_mfma_f32_16x16x32_bf16 v[64:67], v[196:199], v[228:231], v[64:67]
	s_barrier
	s_add_i32 s6, s26, s44
	s_mov_b32 m0, s6
	ds_read_b128 v[200:203], v163 offset:16384
	ds_read_b128 v[204:207], v163 offset:17408
	ds_read_b128 v[208:211], v163 offset:18432
	ds_read_b128 v[212:215], v163 offset:19456
	ds_read_b128 v[216:219], v163 offset:20480
	ds_read_b128 v[220:223], v163 offset:21504
	ds_read_b128 v[224:227], v163 offset:22528
	ds_read_b128 v[228:231], v163 offset:23552
	global_load_lds_dwordx4 v130, s[60:61]
	s_add_i32 m0, s6, 0x2000
	s_add_u32 s6, s60, 0xb0000
	s_addc_u32 s7, s61, 0
	s_add_i32 s56, s74, s44
	global_load_lds_dwordx4 v134, s[60:61]
	s_mov_b32 m0, s56
	s_nop 0
	global_load_lds_dwordx4 v130, s[6:7]
	s_add_i32 m0, s56, 0x2000
	s_nop 0
	global_load_lds_dwordx4 v134, s[6:7]
	s_mov_b32 m0, s45
	s_nop 0
	global_load_lds_dwordx4 v128, s[78:79]
	s_mov_b32 m0, s67
	s_nop 0
	global_load_lds_dwordx4 v132, s[78:79]
	s_waitcnt vmcnt(8)
	s_waitcnt lgkmcnt(0)
	s_barrier
	v_mfma_f32_16x16x32_bf16 v[60:63], v[144:147], v[200:203], v[60:63]
	v_mfma_f32_16x16x32_bf16 v[56:59], v[172:175], v[200:203], v[56:59]
	v_mfma_f32_16x16x32_bf16 v[44:47], v[144:147], v[208:211], v[44:47]
	v_mfma_f32_16x16x32_bf16 v[40:43], v[172:175], v[208:211], v[40:43]
	v_mfma_f32_16x16x32_bf16 v[28:31], v[144:147], v[216:219], v[28:31]
	v_mfma_f32_16x16x32_bf16 v[24:27], v[172:175], v[216:219], v[24:27]
	v_mfma_f32_16x16x32_bf16 v[12:15], v[144:147], v[224:227], v[12:15]
	v_mfma_f32_16x16x32_bf16 v[8:11], v[172:175], v[224:227], v[8:11]
	v_mfma_f32_16x16x32_bf16 v[60:63], v[168:171], v[204:207], v[60:63]
	v_mfma_f32_16x16x32_bf16 v[56:59], v[176:179], v[204:207], v[56:59]
	v_mfma_f32_16x16x32_bf16 v[44:47], v[168:171], v[212:215], v[44:47]
	v_mfma_f32_16x16x32_bf16 v[40:43], v[176:179], v[212:215], v[40:43]
	v_mfma_f32_16x16x32_bf16 v[28:31], v[168:171], v[220:223], v[28:31]
	v_mfma_f32_16x16x32_bf16 v[24:27], v[176:179], v[220:223], v[24:27]
	v_mfma_f32_16x16x32_bf16 v[12:15], v[168:171], v[228:231], v[12:15]
	v_mfma_f32_16x16x32_bf16 v[8:11], v[176:179], v[228:231], v[8:11]
	v_mfma_f32_16x16x32_bf16 v[52:55], v[180:183], v[200:203], v[52:55]
	v_mfma_f32_16x16x32_bf16 v[48:51], v[188:191], v[200:203], v[48:51]
	v_mfma_f32_16x16x32_bf16 v[36:39], v[180:183], v[208:211], v[36:39]
	v_mfma_f32_16x16x32_bf16 v[32:35], v[188:191], v[208:211], v[32:35]
	v_mfma_f32_16x16x32_bf16 v[20:23], v[180:183], v[216:219], v[20:23]
	v_mfma_f32_16x16x32_bf16 v[16:19], v[188:191], v[216:219], v[16:19]
	v_mfma_f32_16x16x32_bf16 v[4:7], v[180:183], v[224:227], v[4:7]
	v_mfma_f32_16x16x32_bf16 v[0:3], v[188:191], v[224:227], v[0:3]
	v_mfma_f32_16x16x32_bf16 v[52:55], v[184:187], v[204:207], v[52:55]
	v_mfma_f32_16x16x32_bf16 v[48:51], v[196:199], v[204:207], v[48:51]
	v_mfma_f32_16x16x32_bf16 v[36:39], v[184:187], v[212:215], v[36:39]
	v_mfma_f32_16x16x32_bf16 v[32:35], v[196:199], v[212:215], v[32:35]
	v_mfma_f32_16x16x32_bf16 v[20:23], v[184:187], v[220:223], v[20:23]
	v_mfma_f32_16x16x32_bf16 v[16:19], v[196:199], v[220:223], v[16:19]
	v_mfma_f32_16x16x32_bf16 v[4:7], v[184:187], v[228:231], v[4:7]
	v_mfma_f32_16x16x32_bf16 v[0:3], v[196:199], v[228:231], v[0:3]
	s_barrier
; #define PG8_STAGE(bufoff, gbase, voff) do { _Pragma("unroll") for (int _i = 0; _i < 2; ++_i) \
;         __builtin_amdgcn_global_load_lds((const unsigned*)((const char*)(gbase) + (voff)[_i]), (PG8_LAS unsigned*)(lds + (bufoff) + ldsw + _i * 8192), 16, 0, 0); } while (0)
; #define PG8_LDA(dst, b, h) do { _Pragma("unroll") for (int m = 0; m < 4; ++m) _Pragma("unroll") for (int k = 0; k < 2; ++k) dst[m][k] = *(const PG8_LAS bf16x8*)(lds + PG8_SA(b, h) + aoff + m * 2048 + k * 1024); } while (0)
; #define PG8_LDB(dst, b, h) do { _Pragma("unroll") for (int n = 0; n < 2; ++n) _Pragma("unroll") for (int k = 0; k < 2; ++k) dst[n][k] = *(const PG8_LAS bf16x8*)(lds + PG8_SB(b, h) + boff + n * 2048 + k * 1024); } while (0)
; #define PG8_MMA(ai, bj, At, Bt) do { __builtin_amdgcn_s_setprio(1); _Pragma("unroll") for (int m = 0; m < 4; ++m) _Pragma("unroll") for (int n = 0; n < 2; ++n) _Pragma("unroll") for (int k = 0; k < 2; ++k) \
;         acc[ai][bj][m][n] = __builtin_amdgcn_mfma_f32_16x16x32_bf16(Bt[n][k], At[m][k], acc[ai][bj][m][n], 0, 0, 0); __builtin_amdgcn_s_setprio(0); } while (0)
; #define PG8_WAIT_V(n) asm volatile("s_waitcnt vmcnt(" #n ")" ::: "memory")
; #define PG8_WAIT_L(n) asm volatile("s_waitcnt lgkmcnt(" #n ")" ::: "memory")
; #define PG8_BAR __builtin_amdgcn_s_barrier()
; #define PG8_SCHED __builtin_amdgcn_sched_barrier(0)
; template <class Epi, class Sched, bool ALIGN_EPI = false, bool SP2 = false>
; __device__ __forceinline__ void gemm_phase(PG8_LAS unsigned char* lds, const Gemm g, const Sched& S, const Epi& E) {
;     ...
;             PG8_LDB(B0, 1, 0); PG8_LDB(B1, 1, 1); PG8_SCHED; PG8_LDA(At, 1, 0); PG8_STAGE(PG8_SA(0, 1), a2 + hstep, voffA);
;             PG8_WAIT_V(8); PG8_WAIT_L(0); PG8_BAR; PG8_MMA(0, 0, At, B0); PG8_MMA(0, 1, At, B1); PG8_BAR; PG8_SCHED;
;             PG8_LDA(At, 1, 1); PG8_STAGE(PG8_SB(1, 0), b3, voffB); PG8_STAGE(PG8_SB(1, 1), b3 + hstep, voffB); PG8_STAGE(PG8_SA(1, 0), a3, voffA);
;             PG8_WAIT_V(8); PG8_WAIT_L(0); PG8_BAR; PG8_MMA(1, 0, At, B0); PG8_MMA(1, 1, At, B1); PG8_BAR; PG8_SCHED;
;     ...
;         }
;         if constexpr (ALIGN_EPI) { if (wr == 0) PG8_BAR; }
	s_add_i32 s56, 0, 0x18000
	v_add_u32_e32 v167, s56, v156
	s_add_i32 s57, 0, 0x1c000
	ds_read_b128 v[144:147], v167
	ds_read_b128 v[168:171], v167 offset:1024
	ds_read_b128 v[172:175], v167 offset:2048
	ds_read_b128 v[176:179], v167 offset:3072
	v_add_u32_e32 v167, s57, v156
	ds_read_b128 v[180:183], v167
	ds_read_b128 v[184:187], v167 offset:1024
	ds_read_b128 v[188:191], v167 offset:2048
	ds_read_b128 v[196:199], v167 offset:3072
	s_add_u32 s6, s78, 0xb0000
	s_addc_u32 s7, s79, 0
	s_mov_b32 m0, s76
	ds_read_b128 v[200:203], v163 offset:32768
	ds_read_b128 v[204:207], v163 offset:33792
	ds_read_b128 v[208:211], v163 offset:34816
	ds_read_b128 v[212:215], v163 offset:35840
	ds_read_b128 v[216:219], v163 offset:36864
	ds_read_b128 v[220:223], v163 offset:37888
	ds_read_b128 v[224:227], v163 offset:38912
	ds_read_b128 v[228:231], v163 offset:39936
	global_load_lds_dwordx4 v128, s[6:7]
	s_mov_b32 m0, s77
	s_nop 0
	global_load_lds_dwordx4 v132, s[6:7]
	s_waitcnt vmcnt(8)
	s_waitcnt lgkmcnt(0)
	s_barrier
	v_mfma_f32_16x16x32_bf16 v[124:127], v[144:147], v[200:203], v[124:127]
	v_mfma_f32_16x16x32_bf16 v[120:123], v[172:175], v[200:203], v[120:123]
	v_mfma_f32_16x16x32_bf16 v[108:111], v[144:147], v[208:211], v[108:111]
	v_mfma_f32_16x16x32_bf16 v[104:107], v[172:175], v[208:211], v[104:107]
	v_mfma_f32_16x16x32_bf16 v[92:95], v[144:147], v[216:219], v[92:95]
	v_mfma_f32_16x16x32_bf16 v[88:91], v[172:175], v[216:219], v[88:91]
	v_mfma_f32_16x16x32_bf16 v[76:79], v[144:147], v[224:227], v[76:79]
	v_mfma_f32_16x16x32_bf16 v[72:75], v[172:175], v[224:227], v[72:75]
	v_mfma_f32_16x16x32_bf16 v[124:127], v[168:171], v[204:207], v[124:127]
	v_mfma_f32_16x16x32_bf16 v[120:123], v[176:179], v[204:207], v[120:123]
	v_mfma_f32_16x16x32_bf16 v[108:111], v[168:171], v[212:215], v[108:111]
	v_mfma_f32_16x16x32_bf16 v[104:107], v[176:179], v[212:215], v[104:107]
	v_mfma_f32_16x16x32_bf16 v[92:95], v[168:171], v[220:223], v[92:95]
	v_mfma_f32_16x16x32_bf16 v[88:91], v[176:179], v[220:223], v[88:91]
	v_mfma_f32_16x16x32_bf16 v[76:79], v[168:171], v[228:231], v[76:79]
	v_mfma_f32_16x16x32_bf16 v[72:75], v[176:179], v[228:231], v[72:75]
	v_mfma_f32_16x16x32_bf16 v[116:119], v[180:183], v[200:203], v[116:119]
	v_mfma_f32_16x16x32_bf16 v[112:115], v[188:191], v[200:203], v[112:115]
	v_mfma_f32_16x16x32_bf16 v[100:103], v[180:183], v[208:211], v[100:103]
	v_mfma_f32_16x16x32_bf16 v[96:99], v[188:191], v[208:211], v[96:99]
	v_mfma_f32_16x16x32_bf16 v[84:87], v[180:183], v[216:219], v[84:87]
	v_mfma_f32_16x16x32_bf16 v[80:83], v[188:191], v[216:219], v[80:83]
	v_mfma_f32_16x16x32_bf16 v[68:71], v[180:183], v[224:227], v[68:71]
	v_mfma_f32_16x16x32_bf16 v[64:67], v[188:191], v[224:227], v[64:67]
	v_mfma_f32_16x16x32_bf16 v[116:119], v[184:187], v[204:207], v[116:119]
	v_mfma_f32_16x16x32_bf16 v[112:115], v[196:199], v[204:207], v[112:115]
	v_mfma_f32_16x16x32_bf16 v[100:103], v[184:187], v[212:215], v[100:103]
	v_mfma_f32_16x16x32_bf16 v[96:99], v[196:199], v[212:215], v[96:99]
	v_mfma_f32_16x16x32_bf16 v[84:87], v[184:187], v[220:223], v[84:87]
	v_mfma_f32_16x16x32_bf16 v[80:83], v[196:199], v[220:223], v[80:83]
	v_mfma_f32_16x16x32_bf16 v[68:71], v[184:187], v[228:231], v[68:71]
	v_mfma_f32_16x16x32_bf16 v[64:67], v[196:199], v[228:231], v[64:67]
	s_barrier
	s_add_i32 s6, s56, s44
	s_add_u32 s98, s60, 0x80
	s_addc_u32 s99, s61, 0
	s_add_u32 s100, s78, 0x80
	s_addc_u32 s101, s79, 0
	s_mov_b32 m0, s6
	ds_read_b128 v[200:203], v163 offset:49152
	ds_read_b128 v[204:207], v163 offset:50176
	ds_read_b128 v[208:211], v163 offset:51200
	ds_read_b128 v[212:215], v163 offset:52224
	ds_read_b128 v[216:219], v163 offset:53248
	ds_read_b128 v[220:223], v163 offset:54272
	ds_read_b128 v[224:227], v163 offset:55296
	ds_read_b128 v[228:231], v163 offset:56320
	global_load_lds_dwordx4 v130, s[98:99]
	s_add_i32 m0, s6, 0x2000
	s_add_u32 s6, s60, 0xb0080
	s_addc_u32 s7, s61, 0
	s_add_i32 s56, s57, s44
	global_load_lds_dwordx4 v134, s[98:99]
	s_mov_b32 m0, s56
	s_nop 0
	global_load_lds_dwordx4 v130, s[6:7]
	s_add_i32 m0, s56, 0x2000
	s_nop 0
	global_load_lds_dwordx4 v134, s[6:7]
	s_mov_b32 m0, s31
	s_nop 0
	global_load_lds_dwordx4 v128, s[100:101]
	s_mov_b32 m0, s4
	s_nop 0
	global_load_lds_dwordx4 v132, s[100:101]
	s_waitcnt vmcnt(8)
	s_waitcnt lgkmcnt(0)
	s_barrier
	v_mfma_f32_16x16x32_bf16 v[60:63], v[144:147], v[200:203], v[60:63]
	v_mfma_f32_16x16x32_bf16 v[56:59], v[172:175], v[200:203], v[56:59]
	v_mfma_f32_16x16x32_bf16 v[44:47], v[144:147], v[208:211], v[44:47]
	v_mfma_f32_16x16x32_bf16 v[40:43], v[172:175], v[208:211], v[40:43]
	v_mfma_f32_16x16x32_bf16 v[28:31], v[144:147], v[216:219], v[28:31]
	v_mfma_f32_16x16x32_bf16 v[24:27], v[172:175], v[216:219], v[24:27]
	v_mfma_f32_16x16x32_bf16 v[12:15], v[144:147], v[224:227], v[12:15]
	v_mfma_f32_16x16x32_bf16 v[8:11], v[172:175], v[224:227], v[8:11]
	v_mfma_f32_16x16x32_bf16 v[60:63], v[168:171], v[204:207], v[60:63]
	v_mfma_f32_16x16x32_bf16 v[56:59], v[176:179], v[204:207], v[56:59]
	v_mfma_f32_16x16x32_bf16 v[44:47], v[168:171], v[212:215], v[44:47]
	v_mfma_f32_16x16x32_bf16 v[40:43], v[176:179], v[212:215], v[40:43]
	v_mfma_f32_16x16x32_bf16 v[28:31], v[168:171], v[220:223], v[28:31]
	v_mfma_f32_16x16x32_bf16 v[24:27], v[176:179], v[220:223], v[24:27]
	v_mfma_f32_16x16x32_bf16 v[12:15], v[168:171], v[228:231], v[12:15]
	v_mfma_f32_16x16x32_bf16 v[8:11], v[176:179], v[228:231], v[8:11]
	v_mfma_f32_16x16x32_bf16 v[52:55], v[180:183], v[200:203], v[52:55]
	v_mfma_f32_16x16x32_bf16 v[48:51], v[188:191], v[200:203], v[48:51]
	v_mfma_f32_16x16x32_bf16 v[36:39], v[180:183], v[208:211], v[36:39]
	v_mfma_f32_16x16x32_bf16 v[32:35], v[188:191], v[208:211], v[32:35]
	v_mfma_f32_16x16x32_bf16 v[20:23], v[180:183], v[216:219], v[20:23]
	v_mfma_f32_16x16x32_bf16 v[16:19], v[188:191], v[216:219], v[16:19]
	v_mfma_f32_16x16x32_bf16 v[4:7], v[180:183], v[224:227], v[4:7]
	v_mfma_f32_16x16x32_bf16 v[0:3], v[188:191], v[224:227], v[0:3]
	v_mfma_f32_16x16x32_bf16 v[52:55], v[184:187], v[204:207], v[52:55]
	v_mfma_f32_16x16x32_bf16 v[48:51], v[196:199], v[204:207], v[48:51]
	v_mfma_f32_16x16x32_bf16 v[36:39], v[184:187], v[212:215], v[36:39]
	v_mfma_f32_16x16x32_bf16 v[32:35], v[196:199], v[212:215], v[32:35]
	v_mfma_f32_16x16x32_bf16 v[20:23], v[184:187], v[220:223], v[20:23]
	v_mfma_f32_16x16x32_bf16 v[16:19], v[196:199], v[220:223], v[16:19]
	v_mfma_f32_16x16x32_bf16 v[4:7], v[184:187], v[228:231], v[4:7]
	v_mfma_f32_16x16x32_bf16 v[0:3], v[196:199], v[228:231], v[0:3]
	s_barrier
	s_add_i32 s72, s72, 2
	s_add_u32 s33, s33, 0x100
	s_addc_u32 s80, s80, 0
	s_cmp_gt_u32 s72, 41
	s_mov_b64 s[56:57], s[58:59]
	s_cbranch_scc0 .LBB0_1014
	s_and_b64 vcc, exec, s[52:53]
	s_cbranch_vccz .LBB0_1017
	s_barrier

; #define PG8_STAGE(bufoff, gbase, voff) do { _Pragma("unroll") for (int _i = 0; _i < 2; ++_i) \
;         __builtin_amdgcn_global_load_lds((const unsigned*)((const char*)(gbase) + (voff)[_i]), (PG8_LAS unsigned*)(lds + (bufoff) + ldsw + _i * 8192), 16, 0, 0); } while (0)
; #define PG8_LDA(dst, b, h) do { _Pragma("unroll") for (int m = 0; m < 4; ++m) _Pragma("unroll") for (int k = 0; k < 2; ++k) dst[m][k] = *(const PG8_LAS bf16x8*)(lds + PG8_SA(b, h) + aoff + m * 2048 + k * 1024); } while (0)
; #define PG8_LDB(dst, b, h) do { _Pragma("unroll") for (int n = 0; n < 2; ++n) _Pragma("unroll") for (int k = 0; k < 2; ++k) dst[n][k] = *(const PG8_LAS bf16x8*)(lds + PG8_SB(b, h) + boff + n * 2048 + k * 1024); } while (0)
; #define PG8_MMA(ai, bj, At, Bt) do { __builtin_amdgcn_s_setprio(1); _Pragma("unroll") for (int m = 0; m < 4; ++m) _Pragma("unroll") for (int n = 0; n < 2; ++n) _Pragma("unroll") for (int k = 0; k < 2; ++k) \
;         acc[ai][bj][m][n] = __builtin_amdgcn_mfma_f32_16x16x32_bf16(Bt[n][k], At[m][k], acc[ai][bj][m][n], 0, 0, 0); __builtin_amdgcn_s_setprio(0); } while (0)
; #define PG8_WAIT_V(n) asm volatile("s_waitcnt vmcnt(" #n ")" ::: "memory")
; #define PG8_WAIT_L(n) asm volatile("s_waitcnt lgkmcnt(" #n ")" ::: "memory")
; template <class Epi, class Sched, bool ALIGN_EPI = false, bool SP2 = false>
; __device__ __forceinline__ void gemm_phase(PG8_LAS unsigned char* lds, const Gemm g, const Sched& S, const Epi& E) {
;     ...
;             const bool last = (t == nt - 2);
;             const char* a1 = cA + (size_t)(t + 1) * kstep;
;             const char* a2 = last ? nA : cA + (size_t)(t + 2) * kstep; const char* b2 = last ? nB : cB + (size_t)(t + 2) * kstep;
;             const char* a3 = a2 + kstep; const char* b3 = b2 + kstep;
;             if (last && has_next) S.a_ready(nxt);
;             if constexpr (SP2) {
;             PG8_LDB(B0, 0, 0); PG8_LDB(B1, 0, 1); PG8_SCHED; PG8_LDA(At, 0, 0); PG8_STAGE(PG8_SA(1, 1), a1 + hstep, voffA);
;             PG8_WAIT_V(8); PG8_WAIT_L(0); PG8_BAR; PG8_MMA(0, 0, At, B0); PG8_MMA(0, 1, At, B1); PG8_BAR; PG8_SCHED;
;             PG8_LDA(At, 0, 1); PG8_STAGE(PG8_SB(0, 0), b2, voffB); PG8_STAGE(PG8_SB(0, 1), b2 + hstep, voffB); PG8_STAGE(PG8_SA(0, 0), a2, voffA);
;             PG8_WAIT_V(8); PG8_WAIT_L(0); PG8_BAR; PG8_MMA(1, 0, At, B0); PG8_MMA(1, 1, At, B1); PG8_BAR; PG8_SCHED;
.LBB0_1392:
	ds_read_b128 v[144:147], v157
	ds_read_b128 v[166:169], v157 offset:1024
	ds_read_b128 v[170:173], v157 offset:2048
	ds_read_b128 v[174:177], v157 offset:3072
	ds_read_b128 v[178:181], v158
	ds_read_b128 v[182:185], v158 offset:1024
	ds_read_b128 v[186:189], v158 offset:2048
	ds_read_b128 v[196:199], v158 offset:3072
	s_add_u32 s6, s58, 0xfffc0080
	s_addc_u32 s7, s59, -1
	s_cmp_eq_u32 s72, 12
	s_cselect_b32 s79, s51, s7
	s_cselect_b32 s78, s75, s6
	s_cselect_b32 s61, s49, s33
	s_cselect_b32 s60, s76, s77
	v_lshl_add_u64 v[190:191], s[58:59], 0, v[136:137]
	s_add_i32 m0, s30, 0xc000
	ds_read_b128 v[200:203], v159
	ds_read_b128 v[204:207], v159 offset:1024
	ds_read_b128 v[208:211], v159 offset:2048
	ds_read_b128 v[212:215], v159 offset:3072
	ds_read_b128 v[216:219], v159 offset:4096
	ds_read_b128 v[220:223], v159 offset:5120
	ds_read_b128 v[224:227], v159 offset:6144
	ds_read_b128 v[228:231], v159 offset:7168
	global_load_lds_dwordx4 v[190:191], off
	v_lshl_add_u64 v[190:191], s[58:59], 0, v[138:139]
	s_add_i32 m0, s30, 0xe000
	s_nop 0
	global_load_lds_dwordx4 v[190:191], off
	s_waitcnt vmcnt(8)
	s_waitcnt lgkmcnt(0)
	s_barrier
	v_mfma_f32_16x16x32_bf16 v[124:127], v[144:147], v[200:203], v[124:127]
	v_mfma_f32_16x16x32_bf16 v[120:123], v[170:173], v[200:203], v[120:123]
	v_mfma_f32_16x16x32_bf16 v[112:115], v[144:147], v[208:211], v[112:115]
	v_mfma_f32_16x16x32_bf16 v[104:107], v[170:173], v[208:211], v[104:107]
	v_mfma_f32_16x16x32_bf16 v[96:99], v[144:147], v[216:219], v[96:99]
	v_mfma_f32_16x16x32_bf16 v[88:91], v[170:173], v[216:219], v[88:91]
	v_mfma_f32_16x16x32_bf16 v[80:83], v[144:147], v[224:227], v[80:83]
	v_mfma_f32_16x16x32_bf16 v[72:75], v[170:173], v[224:227], v[72:75]
	v_mfma_f32_16x16x32_bf16 v[124:127], v[166:169], v[204:207], v[124:127]
	v_mfma_f32_16x16x32_bf16 v[120:123], v[174:177], v[204:207], v[120:123]
	v_mfma_f32_16x16x32_bf16 v[112:115], v[166:169], v[212:215], v[112:115]
	v_mfma_f32_16x16x32_bf16 v[104:107], v[174:177], v[212:215], v[104:107]
	v_mfma_f32_16x16x32_bf16 v[96:99], v[166:169], v[220:223], v[96:99]
	v_mfma_f32_16x16x32_bf16 v[88:91], v[174:177], v[220:223], v[88:91]
	v_mfma_f32_16x16x32_bf16 v[80:83], v[166:169], v[228:231], v[80:83]
	v_mfma_f32_16x16x32_bf16 v[72:75], v[174:177], v[228:231], v[72:75]
	v_mfma_f32_16x16x32_bf16 v[116:119], v[178:181], v[200:203], v[116:119]
	v_mfma_f32_16x16x32_bf16 v[108:111], v[186:189], v[200:203], v[108:111]
	v_mfma_f32_16x16x32_bf16 v[100:103], v[178:181], v[208:211], v[100:103]
	v_mfma_f32_16x16x32_bf16 v[92:95], v[186:189], v[208:211], v[92:95]
	v_mfma_f32_16x16x32_bf16 v[84:87], v[178:181], v[216:219], v[84:87]
	v_mfma_f32_16x16x32_bf16 v[76:79], v[186:189], v[216:219], v[76:79]
	v_mfma_f32_16x16x32_bf16 v[68:71], v[178:181], v[224:227], v[68:71]
	v_mfma_f32_16x16x32_bf16 v[64:67], v[186:189], v[224:227], v[64:67]
	v_mfma_f32_16x16x32_bf16 v[116:119], v[182:185], v[204:207], v[116:119]
	v_mfma_f32_16x16x32_bf16 v[108:111], v[196:199], v[204:207], v[108:111]
	v_mfma_f32_16x16x32_bf16 v[100:103], v[182:185], v[212:215], v[100:103]
	v_mfma_f32_16x16x32_bf16 v[92:95], v[196:199], v[212:215], v[92:95]
	v_mfma_f32_16x16x32_bf16 v[84:87], v[182:185], v[220:223], v[84:87]
	v_mfma_f32_16x16x32_bf16 v[76:79], v[196:199], v[220:223], v[76:79]
	v_mfma_f32_16x16x32_bf16 v[68:71], v[182:185], v[228:231], v[68:71]
	v_mfma_f32_16x16x32_bf16 v[64:67], v[196:199], v[228:231], v[64:67]
	s_barrier
	s_add_i32 s6, s57, s27
	v_lshl_add_u64 v[190:191], s[60:61], 0, v[130:131]
	s_mov_b32 m0, s6
	ds_read_b128 v[200:203], v159 offset:16384
	ds_read_b128 v[204:207], v159 offset:17408
	ds_read_b128 v[208:211], v159 offset:18432
	ds_read_b128 v[212:215], v159 offset:19456
	ds_read_b128 v[216:219], v159 offset:20480
	ds_read_b128 v[220:223], v159 offset:21504
	ds_read_b128 v[224:227], v159 offset:22528
	ds_read_b128 v[228:231], v159 offset:23552
	global_load_lds_dwordx4 v[190:191], off
	s_add_i32 m0, s6, 0x2000
	s_add_u32 s6, s60, 0x40000
	v_lshl_add_u64 v[232:233], s[60:61], 0, v[134:135]
	s_addc_u32 s7, s61, 0
	s_add_i32 s73, s67, s27
	global_load_lds_dwordx4 v[232:233], off
	s_mov_b32 m0, s73
	v_lshl_add_u64 v[236:237], s[78:79], 0, v[132:133]
	global_load_lds_dwordx4 v130, s[6:7]
	s_add_i32 m0, s73, 0x2000
	s_nop 0
	global_load_lds_dwordx4 v134, s[6:7]
	v_lshl_add_u64 v[234:235], s[78:79], 0, v[128:129]
	s_mov_b32 m0, s30
	s_nop 0
	global_load_lds_dwordx4 v[234:235], off
	s_mov_b32 m0, s31
	s_nop 0
	global_load_lds_dwordx4 v[236:237], off
	s_waitcnt vmcnt(8)
	s_waitcnt lgkmcnt(0)
	s_barrier
	v_mfma_f32_16x16x32_bf16 v[60:63], v[144:147], v[200:203], v[60:63]
	v_mfma_f32_16x16x32_bf16 v[56:59], v[170:173], v[200:203], v[56:59]
	v_mfma_f32_16x16x32_bf16 v[52:55], v[144:147], v[208:211], v[52:55]
	v_mfma_f32_16x16x32_bf16 v[40:43], v[170:173], v[208:211], v[40:43]
	v_mfma_f32_16x16x32_bf16 v[36:39], v[144:147], v[216:219], v[36:39]
	v_mfma_f32_16x16x32_bf16 v[24:27], v[170:173], v[216:219], v[24:27]
	v_mfma_f32_16x16x32_bf16 v[20:23], v[144:147], v[224:227], v[20:23]
	v_mfma_f32_16x16x32_bf16 v[8:11], v[170:173], v[224:227], v[8:11]
	v_mfma_f32_16x16x32_bf16 v[60:63], v[166:169], v[204:207], v[60:63]
	v_mfma_f32_16x16x32_bf16 v[56:59], v[174:177], v[204:207], v[56:59]
	v_mfma_f32_16x16x32_bf16 v[52:55], v[166:169], v[212:215], v[52:55]
	v_mfma_f32_16x16x32_bf16 v[40:43], v[174:177], v[212:215], v[40:43]
	v_mfma_f32_16x16x32_bf16 v[36:39], v[166:169], v[220:223], v[36:39]
	v_mfma_f32_16x16x32_bf16 v[24:27], v[174:177], v[220:223], v[24:27]
	v_mfma_f32_16x16x32_bf16 v[20:23], v[166:169], v[228:231], v[20:23]
	v_mfma_f32_16x16x32_bf16 v[8:11], v[174:177], v[228:231], v[8:11]
	v_mfma_f32_16x16x32_bf16 v[48:51], v[178:181], v[200:203], v[48:51]
	v_mfma_f32_16x16x32_bf16 v[44:47], v[186:189], v[200:203], v[44:47]
	v_mfma_f32_16x16x32_bf16 v[32:35], v[178:181], v[208:211], v[32:35]
	v_mfma_f32_16x16x32_bf16 v[28:31], v[186:189], v[208:211], v[28:31]
	v_mfma_f32_16x16x32_bf16 v[16:19], v[178:181], v[216:219], v[16:19]
	v_mfma_f32_16x16x32_bf16 v[12:15], v[186:189], v[216:219], v[12:15]
	v_mfma_f32_16x16x32_bf16 v[4:7], v[178:181], v[224:227], v[4:7]
	v_mfma_f32_16x16x32_bf16 v[0:3], v[186:189], v[224:227], v[0:3]
	v_mfma_f32_16x16x32_bf16 v[48:51], v[182:185], v[204:207], v[48:51]
	v_mfma_f32_16x16x32_bf16 v[44:47], v[196:199], v[204:207], v[44:47]
	v_mfma_f32_16x16x32_bf16 v[32:35], v[182:185], v[212:215], v[32:35]
	v_mfma_f32_16x16x32_bf16 v[28:31], v[196:199], v[212:215], v[28:31]
	v_mfma_f32_16x16x32_bf16 v[16:19], v[182:185], v[220:223], v[16:19]
	v_mfma_f32_16x16x32_bf16 v[12:15], v[196:199], v[220:223], v[12:15]
	v_mfma_f32_16x16x32_bf16 v[4:7], v[182:185], v[228:231], v[4:7]
	v_mfma_f32_16x16x32_bf16 v[0:3], v[196:199], v[228:231], v[0:3]
	s_barrier
; #define PG8_STAGE(bufoff, gbase, voff) do { _Pragma("unroll") for (int _i = 0; _i < 2; ++_i) \
;         __builtin_amdgcn_global_load_lds((const unsigned*)((const char*)(gbase) + (voff)[_i]), (PG8_LAS unsigned*)(lds + (bufoff) + ldsw + _i * 8192), 16, 0, 0); } while (0)
; #define PG8_LDA(dst, b, h) do { _Pragma("unroll") for (int m = 0; m < 4; ++m) _Pragma("unroll") for (int k = 0; k < 2; ++k) dst[m][k] = *(const PG8_LAS bf16x8*)(lds + PG8_SA(b, h) + aoff + m * 2048 + k * 1024); } while (0)
; #define PG8_LDB(dst, b, h) do { _Pragma("unroll") for (int n = 0; n < 2; ++n) _Pragma("unroll") for (int k = 0; k < 2; ++k) dst[n][k] = *(const PG8_LAS bf16x8*)(lds + PG8_SB(b, h) + boff + n * 2048 + k * 1024); } while (0)
; #define PG8_MMA(ai, bj, At, Bt) do { __builtin_amdgcn_s_setprio(1); _Pragma("unroll") for (int m = 0; m < 4; ++m) _Pragma("unroll") for (int n = 0; n < 2; ++n) _Pragma("unroll") for (int k = 0; k < 2; ++k) \
;         acc[ai][bj][m][n] = __builtin_amdgcn_mfma_f32_16x16x32_bf16(Bt[n][k], At[m][k], acc[ai][bj][m][n], 0, 0, 0); __builtin_amdgcn_s_setprio(0); } while (0)
; #define PG8_WAIT_V(n) asm volatile("s_waitcnt vmcnt(" #n ")" ::: "memory")
; #define PG8_WAIT_L(n) asm volatile("s_waitcnt lgkmcnt(" #n ")" ::: "memory")
; #define PG8_BAR __builtin_amdgcn_s_barrier()
; #define PG8_SCHED __builtin_amdgcn_sched_barrier(0)
; template <class Epi, class Sched, bool ALIGN_EPI = false, bool SP2 = false>
; __device__ __forceinline__ void gemm_phase(PG8_LAS unsigned char* lds, const Gemm g, const Sched& S, const Epi& E) {
;     ...
;             PG8_LDB(B0, 1, 0); PG8_LDB(B1, 1, 1); PG8_SCHED; PG8_LDA(At, 1, 0); PG8_STAGE(PG8_SA(0, 1), a2 + hstep, voffA);
;             PG8_WAIT_V(8); PG8_WAIT_L(0); PG8_BAR; PG8_MMA(0, 0, At, B0); PG8_MMA(0, 1, At, B1); PG8_BAR; PG8_SCHED;
;             PG8_LDA(At, 1, 1); PG8_STAGE(PG8_SB(1, 0), b3, voffB); PG8_STAGE(PG8_SB(1, 1), b3 + hstep, voffB); PG8_STAGE(PG8_SA(1, 0), a3, voffA);
;             PG8_WAIT_V(8); PG8_WAIT_L(0); PG8_BAR; PG8_MMA(1, 0, At, B0); PG8_MMA(1, 1, At, B1); PG8_BAR; PG8_SCHED;
;     ...
;         }
;         if constexpr (ALIGN_EPI) { if (wr == 0) PG8_BAR; }
	s_add_i32 s73, 0, 0x18000
	v_add_u32_e32 v163, s73, v149
	s_add_i32 s80, 0, 0x1c000
	ds_read_b128 v[144:147], v163
	ds_read_b128 v[166:169], v163 offset:1024
	ds_read_b128 v[170:173], v163 offset:2048
	ds_read_b128 v[174:177], v163 offset:3072
	v_add_u32_e32 v163, s80, v149
	ds_read_b128 v[178:181], v163
	ds_read_b128 v[182:185], v163 offset:1024
	ds_read_b128 v[186:189], v163 offset:2048
	ds_read_b128 v[196:199], v163 offset:3072
	s_add_u32 s6, s78, 0x40000
	s_addc_u32 s7, s79, 0
	s_mov_b32 m0, s42
	ds_read_b128 v[200:203], v159 offset:32768
	ds_read_b128 v[204:207], v159 offset:33792
	ds_read_b128 v[208:211], v159 offset:34816
	ds_read_b128 v[212:215], v159 offset:35840
	ds_read_b128 v[216:219], v159 offset:36864
	ds_read_b128 v[220:223], v159 offset:37888
	ds_read_b128 v[224:227], v159 offset:38912
	ds_read_b128 v[228:231], v159 offset:39936
	global_load_lds_dwordx4 v128, s[6:7]
	s_mov_b32 m0, s43
	s_nop 0
	global_load_lds_dwordx4 v132, s[6:7]
	s_waitcnt vmcnt(8)
	s_waitcnt lgkmcnt(0)
	s_barrier
	v_mfma_f32_16x16x32_bf16 v[124:127], v[144:147], v[200:203], v[124:127]
	v_mfma_f32_16x16x32_bf16 v[120:123], v[170:173], v[200:203], v[120:123]
	v_mfma_f32_16x16x32_bf16 v[112:115], v[144:147], v[208:211], v[112:115]
	v_mfma_f32_16x16x32_bf16 v[104:107], v[170:173], v[208:211], v[104:107]
	v_mfma_f32_16x16x32_bf16 v[96:99], v[144:147], v[216:219], v[96:99]
	v_mfma_f32_16x16x32_bf16 v[88:91], v[170:173], v[216:219], v[88:91]
	v_mfma_f32_16x16x32_bf16 v[80:83], v[144:147], v[224:227], v[80:83]
	v_mfma_f32_16x16x32_bf16 v[72:75], v[170:173], v[224:227], v[72:75]
	v_mfma_f32_16x16x32_bf16 v[124:127], v[166:169], v[204:207], v[124:127]
	v_mfma_f32_16x16x32_bf16 v[120:123], v[174:177], v[204:207], v[120:123]
	v_mfma_f32_16x16x32_bf16 v[112:115], v[166:169], v[212:215], v[112:115]
	v_mfma_f32_16x16x32_bf16 v[104:107], v[174:177], v[212:215], v[104:107]
	v_mfma_f32_16x16x32_bf16 v[96:99], v[166:169], v[220:223], v[96:99]
	v_mfma_f32_16x16x32_bf16 v[88:91], v[174:177], v[220:223], v[88:91]
	v_mfma_f32_16x16x32_bf16 v[80:83], v[166:169], v[228:231], v[80:83]
	v_mfma_f32_16x16x32_bf16 v[72:75], v[174:177], v[228:231], v[72:75]
	v_mfma_f32_16x16x32_bf16 v[116:119], v[178:181], v[200:203], v[116:119]
	v_mfma_f32_16x16x32_bf16 v[108:111], v[186:189], v[200:203], v[108:111]
	v_mfma_f32_16x16x32_bf16 v[100:103], v[178:181], v[208:211], v[100:103]
	v_mfma_f32_16x16x32_bf16 v[92:95], v[186:189], v[208:211], v[92:95]
	v_mfma_f32_16x16x32_bf16 v[84:87], v[178:181], v[216:219], v[84:87]
	v_mfma_f32_16x16x32_bf16 v[76:79], v[186:189], v[216:219], v[76:79]
	v_mfma_f32_16x16x32_bf16 v[68:71], v[178:181], v[224:227], v[68:71]
	v_mfma_f32_16x16x32_bf16 v[64:67], v[186:189], v[224:227], v[64:67]
	v_mfma_f32_16x16x32_bf16 v[116:119], v[182:185], v[204:207], v[116:119]
	v_mfma_f32_16x16x32_bf16 v[108:111], v[196:199], v[204:207], v[108:111]
	v_mfma_f32_16x16x32_bf16 v[100:103], v[182:185], v[212:215], v[100:103]
	v_mfma_f32_16x16x32_bf16 v[92:95], v[196:199], v[212:215], v[92:95]
	v_mfma_f32_16x16x32_bf16 v[84:87], v[182:185], v[220:223], v[84:87]
	v_mfma_f32_16x16x32_bf16 v[76:79], v[196:199], v[220:223], v[76:79]
	v_mfma_f32_16x16x32_bf16 v[68:71], v[182:185], v[228:231], v[68:71]
	v_mfma_f32_16x16x32_bf16 v[64:67], v[196:199], v[228:231], v[64:67]
	s_barrier
	s_add_i32 s6, s73, s27
	v_lshl_add_u64 v[190:191], v[190:191], 0, s[38:39]
	s_mov_b32 m0, s6
	ds_read_b128 v[200:203], v159 offset:49152
	ds_read_b128 v[204:207], v159 offset:50176
	ds_read_b128 v[208:211], v159 offset:51200
	ds_read_b128 v[212:215], v159 offset:52224
	ds_read_b128 v[216:219], v159 offset:53248
	ds_read_b128 v[220:223], v159 offset:54272
	ds_read_b128 v[224:227], v159 offset:55296
	ds_read_b128 v[228:231], v159 offset:56320
	global_load_lds_dwordx4 v[190:191], off
	s_add_i32 m0, s6, 0x2000
	s_add_u32 s6, s60, 0x40080
	v_lshl_add_u64 v[190:191], v[232:233], 0, s[38:39]
	s_addc_u32 s7, s61, 0
	s_add_i32 s60, s80, s27
	global_load_lds_dwordx4 v[190:191], off
	v_lshl_add_u64 v[190:191], s[6:7], 0, v[130:131]
	s_mov_b32 m0, s60
	s_nop 0
	global_load_lds_dwordx4 v[190:191], off
	v_lshl_add_u64 v[190:191], s[6:7], 0, v[134:135]
	s_add_i32 m0, s60, 0x2000
	s_nop 0
	global_load_lds_dwordx4 v[190:191], off
	v_lshl_add_u64 v[190:191], v[234:235], 0, s[38:39]
	s_mov_b32 m0, s44
	s_nop 0
	global_load_lds_dwordx4 v[190:191], off
	v_lshl_add_u64 v[190:191], v[236:237], 0, s[38:39]
	s_mov_b32 m0, s45
	s_nop 0
	global_load_lds_dwordx4 v[190:191], off
	s_waitcnt vmcnt(8)
	s_waitcnt lgkmcnt(0)
	s_barrier
	v_mfma_f32_16x16x32_bf16 v[60:63], v[144:147], v[200:203], v[60:63]
	v_mfma_f32_16x16x32_bf16 v[56:59], v[170:173], v[200:203], v[56:59]
	v_mfma_f32_16x16x32_bf16 v[52:55], v[144:147], v[208:211], v[52:55]
	v_mfma_f32_16x16x32_bf16 v[40:43], v[170:173], v[208:211], v[40:43]
	v_mfma_f32_16x16x32_bf16 v[36:39], v[144:147], v[216:219], v[36:39]
	v_mfma_f32_16x16x32_bf16 v[24:27], v[170:173], v[216:219], v[24:27]
	v_mfma_f32_16x16x32_bf16 v[20:23], v[144:147], v[224:227], v[20:23]
	v_mfma_f32_16x16x32_bf16 v[8:11], v[170:173], v[224:227], v[8:11]
	v_mfma_f32_16x16x32_bf16 v[60:63], v[166:169], v[204:207], v[60:63]
	v_mfma_f32_16x16x32_bf16 v[56:59], v[174:177], v[204:207], v[56:59]
	v_mfma_f32_16x16x32_bf16 v[52:55], v[166:169], v[212:215], v[52:55]
	v_mfma_f32_16x16x32_bf16 v[40:43], v[174:177], v[212:215], v[40:43]
	v_mfma_f32_16x16x32_bf16 v[36:39], v[166:169], v[220:223], v[36:39]
	v_mfma_f32_16x16x32_bf16 v[24:27], v[174:177], v[220:223], v[24:27]
	v_mfma_f32_16x16x32_bf16 v[20:23], v[166:169], v[228:231], v[20:23]
	v_mfma_f32_16x16x32_bf16 v[8:11], v[174:177], v[228:231], v[8:11]
	v_mfma_f32_16x16x32_bf16 v[48:51], v[178:181], v[200:203], v[48:51]
	v_mfma_f32_16x16x32_bf16 v[44:47], v[186:189], v[200:203], v[44:47]
	v_mfma_f32_16x16x32_bf16 v[32:35], v[178:181], v[208:211], v[32:35]
	v_mfma_f32_16x16x32_bf16 v[28:31], v[186:189], v[208:211], v[28:31]
	v_mfma_f32_16x16x32_bf16 v[16:19], v[178:181], v[216:219], v[16:19]
	v_mfma_f32_16x16x32_bf16 v[12:15], v[186:189], v[216:219], v[12:15]
	v_mfma_f32_16x16x32_bf16 v[4:7], v[178:181], v[224:227], v[4:7]
	v_mfma_f32_16x16x32_bf16 v[0:3], v[186:189], v[224:227], v[0:3]
	v_mfma_f32_16x16x32_bf16 v[48:51], v[182:185], v[204:207], v[48:51]
	v_mfma_f32_16x16x32_bf16 v[44:47], v[196:199], v[204:207], v[44:47]
	v_mfma_f32_16x16x32_bf16 v[32:35], v[182:185], v[212:215], v[32:35]
	v_mfma_f32_16x16x32_bf16 v[28:31], v[196:199], v[212:215], v[28:31]
	v_mfma_f32_16x16x32_bf16 v[16:19], v[182:185], v[220:223], v[16:19]
	v_mfma_f32_16x16x32_bf16 v[12:15], v[196:199], v[220:223], v[12:15]
	v_mfma_f32_16x16x32_bf16 v[4:7], v[182:185], v[228:231], v[4:7]
	v_mfma_f32_16x16x32_bf16 v[0:3], v[196:199], v[228:231], v[0:3]
	s_barrier
	s_add_i32 s72, s72, 2
	s_add_u32 s58, s58, 0x100
	s_addc_u32 s59, s59, 0
	s_add_u32 s77, s77, 0x100
	s_addc_u32 s33, s33, 0
	s_cmp_gt_u32 s72, 13
	s_cbranch_scc0 .LBB0_1392
	s_and_b64 vcc, exec, s[40:41]
	s_cbranch_vccz .LBB0_1395
	s_barrier

; #define PG8_STAGE(bufoff, gbase, voff) do { _Pragma("unroll") for (int _i = 0; _i < 2; ++_i) \
;         __builtin_amdgcn_global_load_lds((const unsigned*)((const char*)(gbase) + (voff)[_i]), (PG8_LAS unsigned*)(lds + (bufoff) + ldsw + _i * 8192), 16, 0, 0); } while (0)
; #define PG8_LDA(dst, b, h) do { _Pragma("unroll") for (int m = 0; m < 4; ++m) _Pragma("unroll") for (int k = 0; k < 2; ++k) dst[m][k] = *(const PG8_LAS bf16x8*)(lds + PG8_SA(b, h) + aoff + m * 2048 + k * 1024); } while (0)
; #define PG8_LDB(dst, b, h) do { _Pragma("unroll") for (int n = 0; n < 2; ++n) _Pragma("unroll") for (int k = 0; k < 2; ++k) dst[n][k] = *(const PG8_LAS bf16x8*)(lds + PG8_SB(b, h) + boff + n * 2048 + k * 1024); } while (0)
; #define PG8_MMA(ai, bj, At, Bt) do { __builtin_amdgcn_s_setprio(1); _Pragma("unroll") for (int m = 0; m < 4; ++m) _Pragma("unroll") for (int n = 0; n < 2; ++n) _Pragma("unroll") for (int k = 0; k < 2; ++k) \
;         acc[ai][bj][m][n] = __builtin_amdgcn_mfma_f32_16x16x32_bf16(Bt[n][k], At[m][k], acc[ai][bj][m][n], 0, 0, 0); __builtin_amdgcn_s_setprio(0); } while (0)
; #define PG8_WAIT_V(n) asm volatile("s_waitcnt vmcnt(" #n ")" ::: "memory")
; #define PG8_WAIT_L(n) asm volatile("s_waitcnt lgkmcnt(" #n ")" ::: "memory")
; template <class Epi, class Sched, bool ALIGN_EPI = false, bool SP2 = false>
; __device__ __forceinline__ void gemm_phase(PG8_LAS unsigned char* lds, const Gemm g, const Sched& S, const Epi& E) {
;     ...
;             const bool last = (t == nt - 2);
;             const char* a1 = cA + (size_t)(t + 1) * kstep;
;             const char* a2 = last ? nA : cA + (size_t)(t + 2) * kstep; const char* b2 = last ? nB : cB + (size_t)(t + 2) * kstep;
;             const char* a3 = a2 + kstep; const char* b3 = b2 + kstep;
;             if (last && has_next) S.a_ready(nxt);
;             if constexpr (SP2) {
;             PG8_LDB(B0, 0, 0); PG8_LDB(B1, 0, 1); PG8_SCHED; PG8_LDA(At, 0, 0); PG8_STAGE(PG8_SA(1, 1), a1 + hstep, voffA);
;             PG8_WAIT_V(8); PG8_WAIT_L(0); PG8_BAR; PG8_MMA(0, 0, At, B0); PG8_MMA(0, 1, At, B1); PG8_BAR; PG8_SCHED;
;             PG8_LDA(At, 0, 1); PG8_STAGE(PG8_SB(0, 0), b2, voffB); PG8_STAGE(PG8_SB(0, 1), b2 + hstep, voffB); PG8_STAGE(PG8_SA(0, 0), a2, voffA);
;             PG8_WAIT_V(8); PG8_WAIT_L(0); PG8_BAR; PG8_MMA(1, 0, At, B0); PG8_MMA(1, 1, At, B1); PG8_BAR; PG8_SCHED;
.LBB0_1617:
	ds_read_b128 v[32:35], v191
	ds_read_b128 v[36:39], v191 offset:1024
	ds_read_b128 v[48:51], v191 offset:2048
	ds_read_b128 v[52:55], v191 offset:3072
	ds_read_b128 v[128:131], v195
	ds_read_b128 v[148:151], v195 offset:1024
	ds_read_b128 v[152:155], v195 offset:2048
	ds_read_b128 v[180:183], v195 offset:3072
	s_add_u32 s6, s56, 0xfffc0080
	s_addc_u32 s7, s57, -1
	s_cmp_eq_u32 s69, 12
	s_cselect_b32 s61, s26, s7
	s_cselect_b32 s60, s29, s6
	s_cselect_b32 s59, s49, s33
	s_cselect_b32 s58, s51, s68
	s_add_i32 m0, s78, 0xc000
	ds_read_b128 v[184:187], v198
	ds_read_b128 v[200:203], v198 offset:1024
	ds_read_b128 v[204:207], v198 offset:2048
	ds_read_b128 v[208:211], v198 offset:3072
	ds_read_b128 v[212:215], v198 offset:4096
	ds_read_b128 v[216:219], v198 offset:5120
	ds_read_b128 v[220:223], v198 offset:6144
	ds_read_b128 v[224:227], v198 offset:7168
	global_load_lds_dwordx4 v172, s[56:57]
	s_add_i32 m0, s78, 0xe000
	s_nop 0
	global_load_lds_dwordx4 v174, s[56:57]
	s_waitcnt vmcnt(8)
	s_waitcnt lgkmcnt(0)
	s_barrier
	v_mfma_f32_16x16x32_bf16 v[144:147], v[32:35], v[184:187], v[144:147]
	v_mfma_f32_16x16x32_bf16 v[140:143], v[48:51], v[184:187], v[140:143]
	v_mfma_f32_16x16x32_bf16 v[124:127], v[32:35], v[204:207], v[124:127]
	v_mfma_f32_16x16x32_bf16 v[120:123], v[48:51], v[204:207], v[120:123]
	v_mfma_f32_16x16x32_bf16 v[108:111], v[32:35], v[212:215], v[108:111]
	v_mfma_f32_16x16x32_bf16 v[104:107], v[48:51], v[212:215], v[104:107]
	v_mfma_f32_16x16x32_bf16 v[92:95], v[32:35], v[220:223], v[92:95]
	v_mfma_f32_16x16x32_bf16 v[88:91], v[48:51], v[220:223], v[88:91]
	v_mfma_f32_16x16x32_bf16 v[144:147], v[36:39], v[200:203], v[144:147]
	v_mfma_f32_16x16x32_bf16 v[140:143], v[52:55], v[200:203], v[140:143]
	v_mfma_f32_16x16x32_bf16 v[124:127], v[36:39], v[208:211], v[124:127]
	v_mfma_f32_16x16x32_bf16 v[120:123], v[52:55], v[208:211], v[120:123]
	v_mfma_f32_16x16x32_bf16 v[108:111], v[36:39], v[216:219], v[108:111]
	v_mfma_f32_16x16x32_bf16 v[104:107], v[52:55], v[216:219], v[104:107]
	v_mfma_f32_16x16x32_bf16 v[92:95], v[36:39], v[224:227], v[92:95]
	v_mfma_f32_16x16x32_bf16 v[88:91], v[52:55], v[224:227], v[88:91]
	v_mfma_f32_16x16x32_bf16 v[136:139], v[128:131], v[184:187], v[136:139]
	v_mfma_f32_16x16x32_bf16 v[132:135], v[152:155], v[184:187], v[132:135]
	v_mfma_f32_16x16x32_bf16 v[116:119], v[128:131], v[204:207], v[116:119]
	v_mfma_f32_16x16x32_bf16 v[112:115], v[152:155], v[204:207], v[112:115]
	v_mfma_f32_16x16x32_bf16 v[100:103], v[128:131], v[212:215], v[100:103]
	v_mfma_f32_16x16x32_bf16 v[96:99], v[152:155], v[212:215], v[96:99]
	v_mfma_f32_16x16x32_bf16 v[84:87], v[128:131], v[220:223], v[84:87]
	v_mfma_f32_16x16x32_bf16 v[80:83], v[152:155], v[220:223], v[80:83]
	v_mfma_f32_16x16x32_bf16 v[136:139], v[148:151], v[200:203], v[136:139]
	v_mfma_f32_16x16x32_bf16 v[132:135], v[180:183], v[200:203], v[132:135]
	v_mfma_f32_16x16x32_bf16 v[116:119], v[148:151], v[208:211], v[116:119]
	v_mfma_f32_16x16x32_bf16 v[112:115], v[180:183], v[208:211], v[112:115]
	v_mfma_f32_16x16x32_bf16 v[100:103], v[148:151], v[216:219], v[100:103]
	v_mfma_f32_16x16x32_bf16 v[96:99], v[180:183], v[216:219], v[96:99]
	v_mfma_f32_16x16x32_bf16 v[84:87], v[148:151], v[224:227], v[84:87]
	v_mfma_f32_16x16x32_bf16 v[80:83], v[180:183], v[224:227], v[80:83]
	s_barrier
	s_add_i32 s6, s43, s67
	s_mov_b32 m0, s6
	ds_read_b128 v[184:187], v198 offset:16384
	ds_read_b128 v[200:203], v198 offset:17408
	ds_read_b128 v[204:207], v198 offset:18432
	ds_read_b128 v[208:211], v198 offset:19456
	ds_read_b128 v[212:215], v198 offset:20480
	ds_read_b128 v[216:219], v198 offset:21504
	ds_read_b128 v[220:223], v198 offset:22528
	ds_read_b128 v[224:227], v198 offset:23552
	global_load_lds_dwordx4 v158, s[58:59]
	s_add_i32 m0, s6, 0x2000
	s_add_u32 s6, s58, 0x40000
	s_addc_u32 s7, s59, 0
	s_add_i32 s72, s76, s67
	global_load_lds_dwordx4 v170, s[58:59]
	s_mov_b32 m0, s72
	s_nop 0
	global_load_lds_dwordx4 v158, s[6:7]
	s_add_i32 m0, s72, 0x2000
	s_nop 0
	global_load_lds_dwordx4 v170, s[6:7]
	s_mov_b32 m0, s78
	s_nop 0
	global_load_lds_dwordx4 v156, s[60:61]
	s_mov_b32 m0, s79
	s_nop 0
	global_load_lds_dwordx4 v164, s[60:61]
	s_waitcnt vmcnt(8)
	s_waitcnt lgkmcnt(0)
	s_barrier
	v_mfma_f32_16x16x32_bf16 v[76:79], v[32:35], v[184:187], v[76:79]
	v_mfma_f32_16x16x32_bf16 v[72:75], v[48:51], v[184:187], v[72:75]
	v_mfma_f32_16x16x32_bf16 v[60:63], v[32:35], v[204:207], v[60:63]
	v_mfma_f32_16x16x32_bf16 v[56:59], v[48:51], v[204:207], v[56:59]
	v_mfma_f32_16x16x32_bf16 v[28:31], v[32:35], v[212:215], v[28:31]
	v_mfma_f32_16x16x32_bf16 v[24:27], v[48:51], v[212:215], v[24:27]
	v_mfma_f32_16x16x32_bf16 v[12:15], v[32:35], v[220:223], v[12:15]
	v_mfma_f32_16x16x32_bf16 v[8:11], v[48:51], v[220:223], v[8:11]
	v_mfma_f32_16x16x32_bf16 v[76:79], v[36:39], v[200:203], v[76:79]
	v_mfma_f32_16x16x32_bf16 v[72:75], v[52:55], v[200:203], v[72:75]
	v_mfma_f32_16x16x32_bf16 v[60:63], v[36:39], v[208:211], v[60:63]
	v_mfma_f32_16x16x32_bf16 v[56:59], v[52:55], v[208:211], v[56:59]
	v_mfma_f32_16x16x32_bf16 v[28:31], v[36:39], v[216:219], v[28:31]
	v_mfma_f32_16x16x32_bf16 v[24:27], v[52:55], v[216:219], v[24:27]
	v_mfma_f32_16x16x32_bf16 v[12:15], v[36:39], v[224:227], v[12:15]
	v_mfma_f32_16x16x32_bf16 v[8:11], v[52:55], v[224:227], v[8:11]
	v_mfma_f32_16x16x32_bf16 v[44:47], v[128:131], v[204:207], v[44:47]
	v_mfma_f32_16x16x32_bf16 v[40:43], v[152:155], v[204:207], v[40:43]
	v_mfma_f32_16x16x32_bf16 v[20:23], v[128:131], v[212:215], v[20:23]
	v_mfma_f32_16x16x32_bf16 v[16:19], v[152:155], v[212:215], v[16:19]
	v_mfma_f32_16x16x32_bf16 v[4:7], v[128:131], v[220:223], v[4:7]
	v_mfma_f32_16x16x32_bf16 v[0:3], v[152:155], v[220:223], v[0:3]
	v_mfma_f32_16x16x32_bf16 v[32:35], v[128:131], v[184:187], v[68:71]
	v_mfma_f32_16x16x32_bf16 v[36:39], v[152:155], v[184:187], v[64:67]
	v_mfma_f32_16x16x32_bf16 v[44:47], v[148:151], v[208:211], v[44:47]
	v_mfma_f32_16x16x32_bf16 v[40:43], v[180:183], v[208:211], v[40:43]
	v_mfma_f32_16x16x32_bf16 v[20:23], v[148:151], v[216:219], v[20:23]
	v_mfma_f32_16x16x32_bf16 v[16:19], v[180:183], v[216:219], v[16:19]
	v_mfma_f32_16x16x32_bf16 v[4:7], v[148:151], v[224:227], v[4:7]
	v_mfma_f32_16x16x32_bf16 v[0:3], v[180:183], v[224:227], v[0:3]
	v_mfma_f32_16x16x32_bf16 v[32:35], v[148:151], v[200:203], v[32:35]
	v_mfma_f32_16x16x32_bf16 v[36:39], v[180:183], v[200:203], v[36:39]
	s_barrier
; #define PG8_STAGE(bufoff, gbase, voff) do { _Pragma("unroll") for (int _i = 0; _i < 2; ++_i) \
;         __builtin_amdgcn_global_load_lds((const unsigned*)((const char*)(gbase) + (voff)[_i]), (PG8_LAS unsigned*)(lds + (bufoff) + ldsw + _i * 8192), 16, 0, 0); } while (0)
; #define PG8_LDA(dst, b, h) do { _Pragma("unroll") for (int m = 0; m < 4; ++m) _Pragma("unroll") for (int k = 0; k < 2; ++k) dst[m][k] = *(const PG8_LAS bf16x8*)(lds + PG8_SA(b, h) + aoff + m * 2048 + k * 1024); } while (0)
; #define PG8_LDB(dst, b, h) do { _Pragma("unroll") for (int n = 0; n < 2; ++n) _Pragma("unroll") for (int k = 0; k < 2; ++k) dst[n][k] = *(const PG8_LAS bf16x8*)(lds + PG8_SB(b, h) + boff + n * 2048 + k * 1024); } while (0)
; #define PG8_MMA(ai, bj, At, Bt) do { __builtin_amdgcn_s_setprio(1); _Pragma("unroll") for (int m = 0; m < 4; ++m) _Pragma("unroll") for (int n = 0; n < 2; ++n) _Pragma("unroll") for (int k = 0; k < 2; ++k) \
;         acc[ai][bj][m][n] = __builtin_amdgcn_mfma_f32_16x16x32_bf16(Bt[n][k], At[m][k], acc[ai][bj][m][n], 0, 0, 0); __builtin_amdgcn_s_setprio(0); } while (0)
; #define PG8_WAIT_V(n) asm volatile("s_waitcnt vmcnt(" #n ")" ::: "memory")
; #define PG8_WAIT_L(n) asm volatile("s_waitcnt lgkmcnt(" #n ")" ::: "memory")
; #define PG8_BAR __builtin_amdgcn_s_barrier()
; #define PG8_SCHED __builtin_amdgcn_sched_barrier(0)
; template <class Epi, class Sched, bool ALIGN_EPI = false, bool SP2 = false>
; __device__ __forceinline__ void gemm_phase(PG8_LAS unsigned char* lds, const Gemm g, const Sched& S, const Epi& E) {
;     ...
;             PG8_LDB(B0, 1, 0); PG8_LDB(B1, 1, 1); PG8_SCHED; PG8_LDA(At, 1, 0); PG8_STAGE(PG8_SA(0, 1), a2 + hstep, voffA);
;             PG8_WAIT_V(8); PG8_WAIT_L(0); PG8_BAR; PG8_MMA(0, 0, At, B0); PG8_MMA(0, 1, At, B1); PG8_BAR; PG8_SCHED;
;             PG8_LDA(At, 1, 1); PG8_STAGE(PG8_SB(1, 0), b3, voffB); PG8_STAGE(PG8_SB(1, 1), b3 + hstep, voffB); PG8_STAGE(PG8_SA(1, 0), a3, voffA);
;             PG8_WAIT_V(8); PG8_WAIT_L(0); PG8_BAR; PG8_MMA(1, 0, At, B0); PG8_MMA(1, 1, At, B1); PG8_BAR; PG8_SCHED;
;     ...
;         }
;         if constexpr (ALIGN_EPI) { if (wr == 0) PG8_BAR; }
	s_add_i32 s72, 0, 0x18000
	s_add_i32 s73, 0, 0x1c000
	v_add_u32_e32 v68, s72, v169
	v_add_u32_e32 v180, s73, v169
	ds_read_b128 v[48:51], v68
	ds_read_b128 v[52:55], v68 offset:1024
	ds_read_b128 v[64:67], v68 offset:2048
	ds_read_b128 v[68:71], v68 offset:3072
	ds_read_b128 v[128:131], v180
	ds_read_b128 v[148:151], v180 offset:1024
	ds_read_b128 v[152:155], v180 offset:2048
	ds_read_b128 v[180:183], v180 offset:3072
	s_add_u32 s6, s60, 0x40000
	s_addc_u32 s7, s61, 0
	s_mov_b32 m0, s80
	ds_read_b128 v[184:187], v198 offset:32768
	ds_read_b128 v[200:203], v198 offset:33792
	ds_read_b128 v[204:207], v198 offset:34816
	ds_read_b128 v[208:211], v198 offset:35840
	ds_read_b128 v[212:215], v198 offset:36864
	ds_read_b128 v[216:219], v198 offset:37888
	ds_read_b128 v[220:223], v198 offset:38912
	ds_read_b128 v[224:227], v198 offset:39936
	global_load_lds_dwordx4 v156, s[6:7]
	s_mov_b32 m0, s81
	s_nop 0
	global_load_lds_dwordx4 v164, s[6:7]
	s_waitcnt vmcnt(8)
	s_waitcnt lgkmcnt(0)
	s_barrier
	v_mfma_f32_16x16x32_bf16 v[144:147], v[48:51], v[184:187], v[144:147]
	v_mfma_f32_16x16x32_bf16 v[140:143], v[64:67], v[184:187], v[140:143]
	v_mfma_f32_16x16x32_bf16 v[124:127], v[48:51], v[204:207], v[124:127]
	v_mfma_f32_16x16x32_bf16 v[120:123], v[64:67], v[204:207], v[120:123]
	v_mfma_f32_16x16x32_bf16 v[108:111], v[48:51], v[212:215], v[108:111]
	v_mfma_f32_16x16x32_bf16 v[104:107], v[64:67], v[212:215], v[104:107]
	v_mfma_f32_16x16x32_bf16 v[92:95], v[48:51], v[220:223], v[92:95]
	v_mfma_f32_16x16x32_bf16 v[88:91], v[64:67], v[220:223], v[88:91]
	v_mfma_f32_16x16x32_bf16 v[144:147], v[52:55], v[200:203], v[144:147]
	v_mfma_f32_16x16x32_bf16 v[140:143], v[68:71], v[200:203], v[140:143]
	v_mfma_f32_16x16x32_bf16 v[124:127], v[52:55], v[208:211], v[124:127]
	v_mfma_f32_16x16x32_bf16 v[120:123], v[68:71], v[208:211], v[120:123]
	v_mfma_f32_16x16x32_bf16 v[108:111], v[52:55], v[216:219], v[108:111]
	v_mfma_f32_16x16x32_bf16 v[104:107], v[68:71], v[216:219], v[104:107]
	v_mfma_f32_16x16x32_bf16 v[92:95], v[52:55], v[224:227], v[92:95]
	v_mfma_f32_16x16x32_bf16 v[88:91], v[68:71], v[224:227], v[88:91]
	v_mfma_f32_16x16x32_bf16 v[136:139], v[128:131], v[184:187], v[136:139]
	v_mfma_f32_16x16x32_bf16 v[132:135], v[152:155], v[184:187], v[132:135]
	v_mfma_f32_16x16x32_bf16 v[116:119], v[128:131], v[204:207], v[116:119]
	v_mfma_f32_16x16x32_bf16 v[112:115], v[152:155], v[204:207], v[112:115]
	v_mfma_f32_16x16x32_bf16 v[100:103], v[128:131], v[212:215], v[100:103]
	v_mfma_f32_16x16x32_bf16 v[96:99], v[152:155], v[212:215], v[96:99]
	v_mfma_f32_16x16x32_bf16 v[84:87], v[128:131], v[220:223], v[84:87]
	v_mfma_f32_16x16x32_bf16 v[80:83], v[152:155], v[220:223], v[80:83]
	v_mfma_f32_16x16x32_bf16 v[136:139], v[148:151], v[200:203], v[136:139]
	v_mfma_f32_16x16x32_bf16 v[132:135], v[180:183], v[200:203], v[132:135]
	v_mfma_f32_16x16x32_bf16 v[116:119], v[148:151], v[208:211], v[116:119]
	v_mfma_f32_16x16x32_bf16 v[112:115], v[180:183], v[208:211], v[112:115]
	v_mfma_f32_16x16x32_bf16 v[100:103], v[148:151], v[216:219], v[100:103]
	v_mfma_f32_16x16x32_bf16 v[96:99], v[180:183], v[216:219], v[96:99]
	v_mfma_f32_16x16x32_bf16 v[84:87], v[148:151], v[224:227], v[84:87]
	v_mfma_f32_16x16x32_bf16 v[80:83], v[180:183], v[224:227], v[80:83]
	s_barrier
	s_add_i32 s6, s72, s67
	s_add_u32 s98, s58, 0x80
	s_addc_u32 s99, s59, 0
	s_add_u32 s100, s60, 0x80
	s_addc_u32 s101, s61, 0
	s_mov_b32 m0, s6
	ds_read_b128 v[184:187], v198 offset:49152
	ds_read_b128 v[200:203], v198 offset:50176
	ds_read_b128 v[204:207], v198 offset:51200
	ds_read_b128 v[208:211], v198 offset:52224
	ds_read_b128 v[212:215], v198 offset:53248
	ds_read_b128 v[216:219], v198 offset:54272
	ds_read_b128 v[220:223], v198 offset:55296
	ds_read_b128 v[224:227], v198 offset:56320
	global_load_lds_dwordx4 v158, s[98:99]
	s_add_i32 m0, s6, 0x2000
	s_add_u32 s6, s58, 0x40080
	s_addc_u32 s7, s59, 0
	s_add_i32 s58, s73, s67
	global_load_lds_dwordx4 v170, s[98:99]
	s_mov_b32 m0, s58
	s_nop 0
	global_load_lds_dwordx4 v158, s[6:7]
	s_add_i32 m0, s58, 0x2000
	s_nop 0
	global_load_lds_dwordx4 v170, s[6:7]
	s_mov_b32 m0, s45
	s_nop 0
	global_load_lds_dwordx4 v156, s[100:101]
	s_mov_b32 m0, s42
	s_nop 0
	global_load_lds_dwordx4 v164, s[100:101]
	s_waitcnt vmcnt(8)
	s_waitcnt lgkmcnt(0)
	s_barrier
	v_mfma_f32_16x16x32_bf16 v[76:79], v[48:51], v[184:187], v[76:79]
	v_mfma_f32_16x16x32_bf16 v[72:75], v[64:67], v[184:187], v[72:75]
	v_mfma_f32_16x16x32_bf16 v[60:63], v[48:51], v[204:207], v[60:63]
	v_mfma_f32_16x16x32_bf16 v[56:59], v[64:67], v[204:207], v[56:59]
	v_mfma_f32_16x16x32_bf16 v[28:31], v[48:51], v[212:215], v[28:31]
	v_mfma_f32_16x16x32_bf16 v[24:27], v[64:67], v[212:215], v[24:27]
	v_mfma_f32_16x16x32_bf16 v[12:15], v[48:51], v[220:223], v[12:15]
	v_mfma_f32_16x16x32_bf16 v[8:11], v[64:67], v[220:223], v[8:11]
	v_mfma_f32_16x16x32_bf16 v[76:79], v[52:55], v[200:203], v[76:79]
	v_mfma_f32_16x16x32_bf16 v[72:75], v[68:71], v[200:203], v[72:75]
	v_mfma_f32_16x16x32_bf16 v[60:63], v[52:55], v[208:211], v[60:63]
	v_mfma_f32_16x16x32_bf16 v[56:59], v[68:71], v[208:211], v[56:59]
	v_mfma_f32_16x16x32_bf16 v[28:31], v[52:55], v[216:219], v[28:31]
	v_mfma_f32_16x16x32_bf16 v[24:27], v[68:71], v[216:219], v[24:27]
	v_mfma_f32_16x16x32_bf16 v[12:15], v[52:55], v[224:227], v[12:15]
	v_mfma_f32_16x16x32_bf16 v[8:11], v[68:71], v[224:227], v[8:11]
	v_mfma_f32_16x16x32_bf16 v[32:35], v[128:131], v[184:187], v[32:35]
	v_mfma_f32_16x16x32_bf16 v[68:71], v[148:151], v[200:203], v[32:35]
	v_mfma_f32_16x16x32_bf16 v[32:35], v[152:155], v[184:187], v[36:39]
	v_mfma_f32_16x16x32_bf16 v[64:67], v[180:183], v[200:203], v[32:35]
	v_mfma_f32_16x16x32_bf16 v[32:35], v[128:131], v[204:207], v[44:47]
	v_mfma_f32_16x16x32_bf16 v[44:47], v[148:151], v[208:211], v[32:35]
	v_mfma_f32_16x16x32_bf16 v[32:35], v[152:155], v[204:207], v[40:43]
	v_mfma_f32_16x16x32_bf16 v[20:23], v[128:131], v[212:215], v[20:23]
	v_mfma_f32_16x16x32_bf16 v[16:19], v[152:155], v[212:215], v[16:19]
	v_mfma_f32_16x16x32_bf16 v[4:7], v[128:131], v[220:223], v[4:7]
	v_mfma_f32_16x16x32_bf16 v[0:3], v[152:155], v[220:223], v[0:3]
	v_mfma_f32_16x16x32_bf16 v[40:43], v[180:183], v[208:211], v[32:35]
	v_mfma_f32_16x16x32_bf16 v[20:23], v[148:151], v[216:219], v[20:23]
	v_mfma_f32_16x16x32_bf16 v[16:19], v[180:183], v[216:219], v[16:19]
	v_mfma_f32_16x16x32_bf16 v[4:7], v[148:151], v[224:227], v[4:7]
	v_mfma_f32_16x16x32_bf16 v[0:3], v[180:183], v[224:227], v[0:3]
	s_barrier
	s_add_i32 s69, s69, 2
	s_add_u32 s56, s56, 0x100
	s_addc_u32 s57, s57, 0
	s_add_u32 s68, s68, 0x100
	s_addc_u32 s33, s33, 0
	s_cmp_gt_u32 s69, 13
	s_cbranch_scc0 .LBB0_1617
	v_readlane_b32 s68, v243, 59
	s_and_b64 vcc, exec, s[40:41]
	v_readlane_b32 s69, v243, 60
	s_cbranch_vccz .LBB0_1620
	s_barrier

; #define PG8_STAGE(bufoff, gbase, voff) do { _Pragma("unroll") for (int _i = 0; _i < 2; ++_i) \
;         __builtin_amdgcn_global_load_lds((const unsigned*)((const char*)(gbase) + (voff)[_i]), (PG8_LAS unsigned*)(lds + (bufoff) + ldsw + _i * 8192), 16, 0, 0); } while (0)
; #define PG8_LDA(dst, b, h) do { _Pragma("unroll") for (int m = 0; m < 4; ++m) _Pragma("unroll") for (int k = 0; k < 2; ++k) dst[m][k] = *(const PG8_LAS bf16x8*)(lds + PG8_SA(b, h) + aoff + m * 2048 + k * 1024); } while (0)
; #define PG8_LDB(dst, b, h) do { _Pragma("unroll") for (int n = 0; n < 2; ++n) _Pragma("unroll") for (int k = 0; k < 2; ++k) dst[n][k] = *(const PG8_LAS bf16x8*)(lds + PG8_SB(b, h) + boff + n * 2048 + k * 1024); } while (0)
; #define PG8_MMA(ai, bj, At, Bt) do { __builtin_amdgcn_s_setprio(1); _Pragma("unroll") for (int m = 0; m < 4; ++m) _Pragma("unroll") for (int n = 0; n < 2; ++n) _Pragma("unroll") for (int k = 0; k < 2; ++k) \
;         acc[ai][bj][m][n] = __builtin_amdgcn_mfma_f32_16x16x32_bf16(Bt[n][k], At[m][k], acc[ai][bj][m][n], 0, 0, 0); __builtin_amdgcn_s_setprio(0); } while (0)
; #define PG8_WAIT_V(n) asm volatile("s_waitcnt vmcnt(" #n ")" ::: "memory")
; #define PG8_WAIT_L(n) asm volatile("s_waitcnt lgkmcnt(" #n ")" ::: "memory")
; template <class Epi, class Sched, bool ALIGN_EPI = false, bool SP2 = false>
; __device__ __forceinline__ void gemm_phase(PG8_LAS unsigned char* lds, const Gemm g, const Sched& S, const Epi& E) {
;     ...
;             const bool last = (t == nt - 2);
;             const char* a1 = cA + (size_t)(t + 1) * kstep;
;             const char* a2 = last ? nA : cA + (size_t)(t + 2) * kstep; const char* b2 = last ? nB : cB + (size_t)(t + 2) * kstep;
;             const char* a3 = a2 + kstep; const char* b3 = b2 + kstep;
;             if (last && has_next) S.a_ready(nxt);
;             if constexpr (SP2) {
;             PG8_LDB(B0, 0, 0); PG8_LDB(B1, 0, 1); PG8_SCHED; PG8_LDA(At, 0, 0); PG8_STAGE(PG8_SA(1, 1), a1 + hstep, voffA);
;             PG8_WAIT_V(8); PG8_WAIT_L(0); PG8_BAR; PG8_MMA(0, 0, At, B0); PG8_MMA(0, 1, At, B1); PG8_BAR; PG8_SCHED;
;             PG8_LDA(At, 0, 1); PG8_STAGE(PG8_SB(0, 0), b2, voffB); PG8_STAGE(PG8_SB(0, 1), b2 + hstep, voffB); PG8_STAGE(PG8_SA(0, 0), a2, voffA);
;             PG8_WAIT_V(8); PG8_WAIT_L(0); PG8_BAR; PG8_MMA(1, 0, At, B0); PG8_MMA(1, 1, At, B1); PG8_BAR; PG8_SCHED;
.LBB0_1698:
	ds_read_b128 v[144:147], v153
	ds_read_b128 v[170:173], v153 offset:1024
	ds_read_b128 v[174:177], v153 offset:2048
	ds_read_b128 v[178:181], v153 offset:3072
	ds_read_b128 v[182:185], v154
	ds_read_b128 v[186:189], v154 offset:1024
	ds_read_b128 v[198:201], v154 offset:2048
	ds_read_b128 v[202:205], v154 offset:3072
	s_add_u32 s6, s60, 0xfffc0080
	s_addc_u32 s7, s61, -1
	s_cmp_eq_u32 s72, 12
	s_cselect_b32 s81, s29, s7
	s_cselect_b32 s80, s55, s6
	s_cselect_b32 s79, s53, s33
	s_cselect_b32 s78, s68, s69
	s_add_i32 m0, s43, 0xc000
	ds_read_b128 v[206:209], v155
	ds_read_b128 v[210:213], v155 offset:1024
	ds_read_b128 v[214:217], v155 offset:2048
	ds_read_b128 v[218:221], v155 offset:3072
	ds_read_b128 v[222:225], v155 offset:4096
	ds_read_b128 v[226:229], v155 offset:5120
	ds_read_b128 v[230:233], v155 offset:6144
	ds_read_b128 v[234:237], v155 offset:7168
	global_load_lds_dwordx4 v136, s[60:61]
	s_add_i32 m0, s43, 0xe000
	s_nop 0
	global_load_lds_dwordx4 v138, s[60:61]
	s_waitcnt vmcnt(8)
	s_waitcnt lgkmcnt(0)
	s_barrier
	v_mfma_f32_16x16x32_bf16 v[124:127], v[144:147], v[206:209], v[124:127]
	v_mfma_f32_16x16x32_bf16 v[120:123], v[174:177], v[206:209], v[120:123]
	v_mfma_f32_16x16x32_bf16 v[108:111], v[144:147], v[214:217], v[108:111]
	v_mfma_f32_16x16x32_bf16 v[104:107], v[174:177], v[214:217], v[104:107]
	v_mfma_f32_16x16x32_bf16 v[92:95], v[144:147], v[222:225], v[92:95]
	v_mfma_f32_16x16x32_bf16 v[88:91], v[174:177], v[222:225], v[88:91]
	v_mfma_f32_16x16x32_bf16 v[76:79], v[144:147], v[230:233], v[76:79]
	v_mfma_f32_16x16x32_bf16 v[72:75], v[174:177], v[230:233], v[72:75]
	v_mfma_f32_16x16x32_bf16 v[124:127], v[170:173], v[210:213], v[124:127]
	v_mfma_f32_16x16x32_bf16 v[120:123], v[178:181], v[210:213], v[120:123]
	v_mfma_f32_16x16x32_bf16 v[108:111], v[170:173], v[218:221], v[108:111]
	v_mfma_f32_16x16x32_bf16 v[104:107], v[178:181], v[218:221], v[104:107]
	v_mfma_f32_16x16x32_bf16 v[92:95], v[170:173], v[226:229], v[92:95]
	v_mfma_f32_16x16x32_bf16 v[88:91], v[178:181], v[226:229], v[88:91]
	v_mfma_f32_16x16x32_bf16 v[76:79], v[170:173], v[234:237], v[76:79]
	v_mfma_f32_16x16x32_bf16 v[72:75], v[178:181], v[234:237], v[72:75]
	v_mfma_f32_16x16x32_bf16 v[116:119], v[182:185], v[206:209], v[116:119]
	v_mfma_f32_16x16x32_bf16 v[112:115], v[198:201], v[206:209], v[112:115]
	v_mfma_f32_16x16x32_bf16 v[100:103], v[182:185], v[214:217], v[100:103]
	v_mfma_f32_16x16x32_bf16 v[96:99], v[198:201], v[214:217], v[96:99]
	v_mfma_f32_16x16x32_bf16 v[84:87], v[182:185], v[222:225], v[84:87]
	v_mfma_f32_16x16x32_bf16 v[80:83], v[198:201], v[222:225], v[80:83]
	v_mfma_f32_16x16x32_bf16 v[68:71], v[182:185], v[230:233], v[68:71]
	v_mfma_f32_16x16x32_bf16 v[64:67], v[198:201], v[230:233], v[64:67]
	v_mfma_f32_16x16x32_bf16 v[116:119], v[186:189], v[210:213], v[116:119]
	v_mfma_f32_16x16x32_bf16 v[112:115], v[202:205], v[210:213], v[112:115]
	v_mfma_f32_16x16x32_bf16 v[100:103], v[186:189], v[218:221], v[100:103]
	v_mfma_f32_16x16x32_bf16 v[96:99], v[202:205], v[218:221], v[96:99]
	v_mfma_f32_16x16x32_bf16 v[84:87], v[186:189], v[226:229], v[84:87]
	v_mfma_f32_16x16x32_bf16 v[80:83], v[202:205], v[226:229], v[80:83]
	v_mfma_f32_16x16x32_bf16 v[68:71], v[186:189], v[234:237], v[68:71]
	v_mfma_f32_16x16x32_bf16 v[64:67], v[202:205], v[234:237], v[64:67]
	s_barrier
	s_add_i32 s6, s26, s42
	s_mov_b32 m0, s6
	ds_read_b128 v[206:209], v155 offset:16384
	ds_read_b128 v[210:213], v155 offset:17408
	ds_read_b128 v[214:217], v155 offset:18432
	ds_read_b128 v[218:221], v155 offset:19456
	ds_read_b128 v[222:225], v155 offset:20480
	ds_read_b128 v[226:229], v155 offset:21504
	ds_read_b128 v[230:233], v155 offset:22528
	ds_read_b128 v[234:237], v155 offset:23552
	global_load_lds_dwordx4 v130, s[78:79]
	s_add_i32 m0, s6, 0x2000
	s_add_u32 s6, s78, 0x40000
	s_addc_u32 s7, s79, 0
	s_add_i32 s73, s74, s42
	global_load_lds_dwordx4 v134, s[78:79]
	s_mov_b32 m0, s73
	s_nop 0
	global_load_lds_dwordx4 v130, s[6:7]
	s_add_i32 m0, s73, 0x2000
	s_nop 0
	global_load_lds_dwordx4 v134, s[6:7]
	s_mov_b32 m0, s43
	s_nop 0
	global_load_lds_dwordx4 v128, s[80:81]
	s_mov_b32 m0, s44
	s_nop 0
	global_load_lds_dwordx4 v132, s[80:81]
	s_waitcnt vmcnt(8)
	s_waitcnt lgkmcnt(0)
	s_barrier
	v_mfma_f32_16x16x32_bf16 v[60:63], v[144:147], v[206:209], v[60:63]
	v_mfma_f32_16x16x32_bf16 v[56:59], v[174:177], v[206:209], v[56:59]
	v_mfma_f32_16x16x32_bf16 v[44:47], v[144:147], v[214:217], v[44:47]
	v_mfma_f32_16x16x32_bf16 v[40:43], v[174:177], v[214:217], v[40:43]
	v_mfma_f32_16x16x32_bf16 v[28:31], v[144:147], v[222:225], v[28:31]
	v_mfma_f32_16x16x32_bf16 v[24:27], v[174:177], v[222:225], v[24:27]
	v_mfma_f32_16x16x32_bf16 v[12:15], v[144:147], v[230:233], v[12:15]
	v_mfma_f32_16x16x32_bf16 v[8:11], v[174:177], v[230:233], v[8:11]
	v_mfma_f32_16x16x32_bf16 v[60:63], v[170:173], v[210:213], v[60:63]
	v_mfma_f32_16x16x32_bf16 v[56:59], v[178:181], v[210:213], v[56:59]
	v_mfma_f32_16x16x32_bf16 v[44:47], v[170:173], v[218:221], v[44:47]
	v_mfma_f32_16x16x32_bf16 v[40:43], v[178:181], v[218:221], v[40:43]
	v_mfma_f32_16x16x32_bf16 v[28:31], v[170:173], v[226:229], v[28:31]
	v_mfma_f32_16x16x32_bf16 v[24:27], v[178:181], v[226:229], v[24:27]
	v_mfma_f32_16x16x32_bf16 v[12:15], v[170:173], v[234:237], v[12:15]
	v_mfma_f32_16x16x32_bf16 v[8:11], v[178:181], v[234:237], v[8:11]
	v_mfma_f32_16x16x32_bf16 v[52:55], v[182:185], v[206:209], v[52:55]
	v_mfma_f32_16x16x32_bf16 v[48:51], v[198:201], v[206:209], v[48:51]
	v_mfma_f32_16x16x32_bf16 v[36:39], v[182:185], v[214:217], v[36:39]
	v_mfma_f32_16x16x32_bf16 v[32:35], v[198:201], v[214:217], v[32:35]
	v_mfma_f32_16x16x32_bf16 v[20:23], v[182:185], v[222:225], v[20:23]
	v_mfma_f32_16x16x32_bf16 v[16:19], v[198:201], v[222:225], v[16:19]
	v_mfma_f32_16x16x32_bf16 v[4:7], v[182:185], v[230:233], v[4:7]
	v_mfma_f32_16x16x32_bf16 v[0:3], v[198:201], v[230:233], v[0:3]
	v_mfma_f32_16x16x32_bf16 v[52:55], v[186:189], v[210:213], v[52:55]
	v_mfma_f32_16x16x32_bf16 v[48:51], v[202:205], v[210:213], v[48:51]
	v_mfma_f32_16x16x32_bf16 v[36:39], v[186:189], v[218:221], v[36:39]
	v_mfma_f32_16x16x32_bf16 v[32:35], v[202:205], v[218:221], v[32:35]
	v_mfma_f32_16x16x32_bf16 v[20:23], v[186:189], v[226:229], v[20:23]
	v_mfma_f32_16x16x32_bf16 v[16:19], v[202:205], v[226:229], v[16:19]
	v_mfma_f32_16x16x32_bf16 v[4:7], v[186:189], v[234:237], v[4:7]
	v_mfma_f32_16x16x32_bf16 v[0:3], v[202:205], v[234:237], v[0:3]
	s_barrier
; #define PG8_STAGE(bufoff, gbase, voff) do { _Pragma("unroll") for (int _i = 0; _i < 2; ++_i) \
;         __builtin_amdgcn_global_load_lds((const unsigned*)((const char*)(gbase) + (voff)[_i]), (PG8_LAS unsigned*)(lds + (bufoff) + ldsw + _i * 8192), 16, 0, 0); } while (0)
; #define PG8_LDA(dst, b, h) do { _Pragma("unroll") for (int m = 0; m < 4; ++m) _Pragma("unroll") for (int k = 0; k < 2; ++k) dst[m][k] = *(const PG8_LAS bf16x8*)(lds + PG8_SA(b, h) + aoff + m * 2048 + k * 1024); } while (0)
; #define PG8_LDB(dst, b, h) do { _Pragma("unroll") for (int n = 0; n < 2; ++n) _Pragma("unroll") for (int k = 0; k < 2; ++k) dst[n][k] = *(const PG8_LAS bf16x8*)(lds + PG8_SB(b, h) + boff + n * 2048 + k * 1024); } while (0)
; #define PG8_MMA(ai, bj, At, Bt) do { __builtin_amdgcn_s_setprio(1); _Pragma("unroll") for (int m = 0; m < 4; ++m) _Pragma("unroll") for (int n = 0; n < 2; ++n) _Pragma("unroll") for (int k = 0; k < 2; ++k) \
;         acc[ai][bj][m][n] = __builtin_amdgcn_mfma_f32_16x16x32_bf16(Bt[n][k], At[m][k], acc[ai][bj][m][n], 0, 0, 0); __builtin_amdgcn_s_setprio(0); } while (0)
; #define PG8_WAIT_V(n) asm volatile("s_waitcnt vmcnt(" #n ")" ::: "memory")
; #define PG8_WAIT_L(n) asm volatile("s_waitcnt lgkmcnt(" #n ")" ::: "memory")
; #define PG8_BAR __builtin_amdgcn_s_barrier()
; #define PG8_SCHED __builtin_amdgcn_sched_barrier(0)
; template <class Epi, class Sched, bool ALIGN_EPI = false, bool SP2 = false>
; __device__ __forceinline__ void gemm_phase(PG8_LAS unsigned char* lds, const Gemm g, const Sched& S, const Epi& E) {
;     ...
;             PG8_LDB(B0, 1, 0); PG8_LDB(B1, 1, 1); PG8_SCHED; PG8_LDA(At, 1, 0); PG8_STAGE(PG8_SA(0, 1), a2 + hstep, voffA);
;             PG8_WAIT_V(8); PG8_WAIT_L(0); PG8_BAR; PG8_MMA(0, 0, At, B0); PG8_MMA(0, 1, At, B1); PG8_BAR; PG8_SCHED;
;             PG8_LDA(At, 1, 1); PG8_STAGE(PG8_SB(1, 0), b3, voffB); PG8_STAGE(PG8_SB(1, 1), b3 + hstep, voffB); PG8_STAGE(PG8_SA(1, 0), a3, voffA);
;             PG8_WAIT_V(8); PG8_WAIT_L(0); PG8_BAR; PG8_MMA(1, 0, At, B0); PG8_MMA(1, 1, At, B1); PG8_BAR; PG8_SCHED;
;     ...
;         }
;         if constexpr (ALIGN_EPI) { if (wr == 0) PG8_BAR; }
	s_add_i32 s73, 0, 0x18000
	v_add_u32_e32 v157, s73, v151
	s_add_i32 s82, 0, 0x1c000
	ds_read_b128 v[144:147], v157
	ds_read_b128 v[170:173], v157 offset:1024
	ds_read_b128 v[174:177], v157 offset:2048
	ds_read_b128 v[178:181], v157 offset:3072
	v_add_u32_e32 v157, s82, v151
	ds_read_b128 v[182:185], v157
	ds_read_b128 v[186:189], v157 offset:1024
	ds_read_b128 v[198:201], v157 offset:2048
	ds_read_b128 v[202:205], v157 offset:3072
	s_add_u32 s6, s80, 0x40000
	s_addc_u32 s7, s81, 0
	s_mov_b32 m0, s45
	ds_read_b128 v[206:209], v155 offset:32768
	ds_read_b128 v[210:213], v155 offset:33792
	ds_read_b128 v[214:217], v155 offset:34816
	ds_read_b128 v[218:221], v155 offset:35840
	ds_read_b128 v[222:225], v155 offset:36864
	ds_read_b128 v[226:229], v155 offset:37888
	ds_read_b128 v[230:233], v155 offset:38912
	ds_read_b128 v[234:237], v155 offset:39936
	global_load_lds_dwordx4 v128, s[6:7]
	s_mov_b32 m0, s67
	s_nop 0
	global_load_lds_dwordx4 v132, s[6:7]
	s_waitcnt vmcnt(8)
	s_waitcnt lgkmcnt(0)
	s_barrier
	v_mfma_f32_16x16x32_bf16 v[124:127], v[144:147], v[206:209], v[124:127]
	v_mfma_f32_16x16x32_bf16 v[120:123], v[174:177], v[206:209], v[120:123]
	v_mfma_f32_16x16x32_bf16 v[108:111], v[144:147], v[214:217], v[108:111]
	v_mfma_f32_16x16x32_bf16 v[104:107], v[174:177], v[214:217], v[104:107]
	v_mfma_f32_16x16x32_bf16 v[92:95], v[144:147], v[222:225], v[92:95]
	v_mfma_f32_16x16x32_bf16 v[88:91], v[174:177], v[222:225], v[88:91]
	v_mfma_f32_16x16x32_bf16 v[76:79], v[144:147], v[230:233], v[76:79]
	v_mfma_f32_16x16x32_bf16 v[72:75], v[174:177], v[230:233], v[72:75]
	v_mfma_f32_16x16x32_bf16 v[124:127], v[170:173], v[210:213], v[124:127]
	v_mfma_f32_16x16x32_bf16 v[120:123], v[178:181], v[210:213], v[120:123]
	v_mfma_f32_16x16x32_bf16 v[108:111], v[170:173], v[218:221], v[108:111]
	v_mfma_f32_16x16x32_bf16 v[104:107], v[178:181], v[218:221], v[104:107]
	v_mfma_f32_16x16x32_bf16 v[92:95], v[170:173], v[226:229], v[92:95]
	v_mfma_f32_16x16x32_bf16 v[88:91], v[178:181], v[226:229], v[88:91]
	v_mfma_f32_16x16x32_bf16 v[76:79], v[170:173], v[234:237], v[76:79]
	v_mfma_f32_16x16x32_bf16 v[72:75], v[178:181], v[234:237], v[72:75]
	v_mfma_f32_16x16x32_bf16 v[116:119], v[182:185], v[206:209], v[116:119]
	v_mfma_f32_16x16x32_bf16 v[112:115], v[198:201], v[206:209], v[112:115]
	v_mfma_f32_16x16x32_bf16 v[100:103], v[182:185], v[214:217], v[100:103]
	v_mfma_f32_16x16x32_bf16 v[96:99], v[198:201], v[214:217], v[96:99]
	v_mfma_f32_16x16x32_bf16 v[84:87], v[182:185], v[222:225], v[84:87]
	v_mfma_f32_16x16x32_bf16 v[80:83], v[198:201], v[222:225], v[80:83]
	v_mfma_f32_16x16x32_bf16 v[68:71], v[182:185], v[230:233], v[68:71]
	v_mfma_f32_16x16x32_bf16 v[64:67], v[198:201], v[230:233], v[64:67]
	v_mfma_f32_16x16x32_bf16 v[116:119], v[186:189], v[210:213], v[116:119]
	v_mfma_f32_16x16x32_bf16 v[112:115], v[202:205], v[210:213], v[112:115]
	v_mfma_f32_16x16x32_bf16 v[100:103], v[186:189], v[218:221], v[100:103]
	v_mfma_f32_16x16x32_bf16 v[96:99], v[202:205], v[218:221], v[96:99]
	v_mfma_f32_16x16x32_bf16 v[84:87], v[186:189], v[226:229], v[84:87]
	v_mfma_f32_16x16x32_bf16 v[80:83], v[202:205], v[226:229], v[80:83]
	v_mfma_f32_16x16x32_bf16 v[68:71], v[186:189], v[234:237], v[68:71]
	v_mfma_f32_16x16x32_bf16 v[64:67], v[202:205], v[234:237], v[64:67]
	s_barrier
	s_add_i32 s6, s73, s42
	s_add_u32 s98, s78, 0x80
	s_addc_u32 s99, s79, 0
	s_add_u32 s100, s80, 0x80
	s_addc_u32 s101, s81, 0
	s_mov_b32 m0, s6
	ds_read_b128 v[206:209], v155 offset:49152
	ds_read_b128 v[210:213], v155 offset:50176
	ds_read_b128 v[214:217], v155 offset:51200
	ds_read_b128 v[218:221], v155 offset:52224
	ds_read_b128 v[222:225], v155 offset:53248
	ds_read_b128 v[226:229], v155 offset:54272
	ds_read_b128 v[230:233], v155 offset:55296
	ds_read_b128 v[234:237], v155 offset:56320
	global_load_lds_dwordx4 v130, s[98:99]
	s_add_i32 m0, s6, 0x2000
	s_add_u32 s6, s78, 0x40080
	s_addc_u32 s7, s79, 0
	s_add_i32 s73, s82, s42
	global_load_lds_dwordx4 v134, s[98:99]
	s_mov_b32 m0, s73
	s_nop 0
	global_load_lds_dwordx4 v130, s[6:7]
	s_add_i32 m0, s73, 0x2000
	s_nop 0
	global_load_lds_dwordx4 v134, s[6:7]
	s_mov_b32 m0, s4
	s_nop 0
	global_load_lds_dwordx4 v128, s[100:101]
	s_mov_b32 m0, s77
	s_nop 0
	global_load_lds_dwordx4 v132, s[100:101]
	s_waitcnt vmcnt(8)
	s_waitcnt lgkmcnt(0)
	s_barrier
	v_mfma_f32_16x16x32_bf16 v[60:63], v[144:147], v[206:209], v[60:63]
	v_mfma_f32_16x16x32_bf16 v[56:59], v[174:177], v[206:209], v[56:59]
	v_mfma_f32_16x16x32_bf16 v[44:47], v[144:147], v[214:217], v[44:47]
	v_mfma_f32_16x16x32_bf16 v[40:43], v[174:177], v[214:217], v[40:43]
	v_mfma_f32_16x16x32_bf16 v[28:31], v[144:147], v[222:225], v[28:31]
	v_mfma_f32_16x16x32_bf16 v[24:27], v[174:177], v[222:225], v[24:27]
	v_mfma_f32_16x16x32_bf16 v[12:15], v[144:147], v[230:233], v[12:15]
	v_mfma_f32_16x16x32_bf16 v[8:11], v[174:177], v[230:233], v[8:11]
	v_mfma_f32_16x16x32_bf16 v[60:63], v[170:173], v[210:213], v[60:63]
	v_mfma_f32_16x16x32_bf16 v[56:59], v[178:181], v[210:213], v[56:59]
	v_mfma_f32_16x16x32_bf16 v[44:47], v[170:173], v[218:221], v[44:47]
	v_mfma_f32_16x16x32_bf16 v[40:43], v[178:181], v[218:221], v[40:43]
	v_mfma_f32_16x16x32_bf16 v[28:31], v[170:173], v[226:229], v[28:31]
	v_mfma_f32_16x16x32_bf16 v[24:27], v[178:181], v[226:229], v[24:27]
	v_mfma_f32_16x16x32_bf16 v[12:15], v[170:173], v[234:237], v[12:15]
	v_mfma_f32_16x16x32_bf16 v[8:11], v[178:181], v[234:237], v[8:11]
	v_mfma_f32_16x16x32_bf16 v[52:55], v[182:185], v[206:209], v[52:55]
	v_mfma_f32_16x16x32_bf16 v[48:51], v[198:201], v[206:209], v[48:51]
	v_mfma_f32_16x16x32_bf16 v[36:39], v[182:185], v[214:217], v[36:39]
	v_mfma_f32_16x16x32_bf16 v[32:35], v[198:201], v[214:217], v[32:35]
	v_mfma_f32_16x16x32_bf16 v[20:23], v[182:185], v[222:225], v[20:23]
	v_mfma_f32_16x16x32_bf16 v[16:19], v[198:201], v[222:225], v[16:19]
	v_mfma_f32_16x16x32_bf16 v[4:7], v[182:185], v[230:233], v[4:7]
	v_mfma_f32_16x16x32_bf16 v[0:3], v[198:201], v[230:233], v[0:3]
	v_mfma_f32_16x16x32_bf16 v[52:55], v[186:189], v[210:213], v[52:55]
	v_mfma_f32_16x16x32_bf16 v[48:51], v[202:205], v[210:213], v[48:51]
	v_mfma_f32_16x16x32_bf16 v[36:39], v[186:189], v[218:221], v[36:39]
	v_mfma_f32_16x16x32_bf16 v[32:35], v[202:205], v[218:221], v[32:35]
	v_mfma_f32_16x16x32_bf16 v[20:23], v[186:189], v[226:229], v[20:23]
	v_mfma_f32_16x16x32_bf16 v[16:19], v[202:205], v[226:229], v[16:19]
	v_mfma_f32_16x16x32_bf16 v[4:7], v[186:189], v[234:237], v[4:7]
	v_mfma_f32_16x16x32_bf16 v[0:3], v[202:205], v[234:237], v[0:3]
	s_barrier
	s_add_i32 s72, s72, 2
	s_add_u32 s60, s60, 0x100
	s_addc_u32 s61, s61, 0
	s_add_u32 s69, s69, 0x100
	s_addc_u32 s33, s33, 0
	s_cmp_gt_u32 s72, 13
	s_cbranch_scc0 .LBB0_1698
	s_and_b64 vcc, exec, s[50:51]
	s_cbranch_vccz .LBB0_1701
	s_barrier

; #define PG8_STAGE(bufoff, gbase, voff) do { _Pragma("unroll") for (int _i = 0; _i < 2; ++_i) \
;         __builtin_amdgcn_global_load_lds((const unsigned*)((const char*)(gbase) + (voff)[_i]), (PG8_LAS unsigned*)(lds + (bufoff) + ldsw + _i * 8192), 16, 0, 0); } while (0)
; #define PG8_LDA(dst, b, h) do { _Pragma("unroll") for (int m = 0; m < 4; ++m) _Pragma("unroll") for (int k = 0; k < 2; ++k) dst[m][k] = *(const PG8_LAS bf16x8*)(lds + PG8_SA(b, h) + aoff + m * 2048 + k * 1024); } while (0)
; #define PG8_LDB(dst, b, h) do { _Pragma("unroll") for (int n = 0; n < 2; ++n) _Pragma("unroll") for (int k = 0; k < 2; ++k) dst[n][k] = *(const PG8_LAS bf16x8*)(lds + PG8_SB(b, h) + boff + n * 2048 + k * 1024); } while (0)
; #define PG8_MMA(ai, bj, At, Bt) do { __builtin_amdgcn_s_setprio(1); _Pragma("unroll") for (int m = 0; m < 4; ++m) _Pragma("unroll") for (int n = 0; n < 2; ++n) _Pragma("unroll") for (int k = 0; k < 2; ++k) \
;         acc[ai][bj][m][n] = __builtin_amdgcn_mfma_f32_16x16x32_bf16(Bt[n][k], At[m][k], acc[ai][bj][m][n], 0, 0, 0); __builtin_amdgcn_s_setprio(0); } while (0)
; #define PG8_WAIT_V(n) asm volatile("s_waitcnt vmcnt(" #n ")" ::: "memory")
; #define PG8_WAIT_L(n) asm volatile("s_waitcnt lgkmcnt(" #n ")" ::: "memory")
; template <class Epi, class Sched, bool ALIGN_EPI = false, bool SP2 = false>
; __device__ __forceinline__ void gemm_phase(PG8_LAS unsigned char* lds, const Gemm g, const Sched& S, const Epi& E) {
;     ...
;             const bool last = (t == nt - 2);
;             const char* a1 = cA + (size_t)(t + 1) * kstep;
;             const char* a2 = last ? nA : cA + (size_t)(t + 2) * kstep; const char* b2 = last ? nB : cB + (size_t)(t + 2) * kstep;
;             const char* a3 = a2 + kstep; const char* b3 = b2 + kstep;
;             if (last && has_next) S.a_ready(nxt);
;             if constexpr (SP2) {
;             PG8_LDB(B0, 0, 0); PG8_LDB(B1, 0, 1); PG8_SCHED; PG8_LDA(At, 0, 0); PG8_STAGE(PG8_SA(1, 1), a1 + hstep, voffA);
;             PG8_WAIT_V(8); PG8_WAIT_L(0); PG8_BAR; PG8_MMA(0, 0, At, B0); PG8_MMA(0, 1, At, B1); PG8_BAR; PG8_SCHED;
;             PG8_LDA(At, 0, 1); PG8_STAGE(PG8_SB(0, 0), b2, voffB); PG8_STAGE(PG8_SB(0, 1), b2 + hstep, voffB); PG8_STAGE(PG8_SA(0, 0), a2, voffA);
;             PG8_WAIT_V(8); PG8_WAIT_L(0); PG8_BAR; PG8_MMA(1, 0, At, B0); PG8_MMA(1, 1, At, B1); PG8_BAR; PG8_SCHED;
.LBB0_1822:
	ds_read_b128 v[144:147], v154
	ds_read_b128 v[168:171], v154 offset:1024
	ds_read_b128 v[172:175], v154 offset:2048
	ds_read_b128 v[176:179], v154 offset:3072
	ds_read_b128 v[180:183], v155
	ds_read_b128 v[184:187], v155 offset:1024
	ds_read_b128 v[188:191], v155 offset:2048
	ds_read_b128 v[198:201], v155 offset:3072
	s_add_u32 s6, s50, 0xfffc0080
	s_addc_u32 s7, s51, -1
	s_cmp_eq_u32 s72, 12
	s_cselect_b32 s55, s39, s7
	s_cselect_b32 s54, s69, s6
	s_cselect_b32 s53, s37, s33
	s_cselect_b32 s52, s74, s75
	s_add_i32 m0, s27, 0xc000
	ds_read_b128 v[202:205], v156
	ds_read_b128 v[206:209], v156 offset:1024
	ds_read_b128 v[210:213], v156 offset:2048
	ds_read_b128 v[214:217], v156 offset:3072
	ds_read_b128 v[218:221], v156 offset:4096
	ds_read_b128 v[222:225], v156 offset:5120
	ds_read_b128 v[226:229], v156 offset:6144
	ds_read_b128 v[230:233], v156 offset:7168
	global_load_lds_dwordx4 v136, s[50:51]
	s_add_i32 m0, s27, 0xe000
	s_nop 0
	global_load_lds_dwordx4 v138, s[50:51]
	s_waitcnt vmcnt(8)
	s_waitcnt lgkmcnt(0)
	s_barrier
	v_mfma_f32_16x16x32_bf16 v[124:127], v[144:147], v[202:205], v[124:127]
	v_mfma_f32_16x16x32_bf16 v[116:119], v[172:175], v[202:205], v[116:119]
	v_mfma_f32_16x16x32_bf16 v[108:111], v[144:147], v[210:213], v[108:111]
	v_mfma_f32_16x16x32_bf16 v[100:103], v[172:175], v[210:213], v[100:103]
	v_mfma_f32_16x16x32_bf16 v[92:95], v[144:147], v[218:221], v[92:95]
	v_mfma_f32_16x16x32_bf16 v[84:87], v[172:175], v[218:221], v[84:87]
	v_mfma_f32_16x16x32_bf16 v[76:79], v[144:147], v[226:229], v[76:79]
	v_mfma_f32_16x16x32_bf16 v[68:71], v[172:175], v[226:229], v[68:71]
	v_mfma_f32_16x16x32_bf16 v[124:127], v[168:171], v[206:209], v[124:127]
	v_mfma_f32_16x16x32_bf16 v[116:119], v[176:179], v[206:209], v[116:119]
	v_mfma_f32_16x16x32_bf16 v[108:111], v[168:171], v[214:217], v[108:111]
	v_mfma_f32_16x16x32_bf16 v[100:103], v[176:179], v[214:217], v[100:103]
	v_mfma_f32_16x16x32_bf16 v[92:95], v[168:171], v[222:225], v[92:95]
	v_mfma_f32_16x16x32_bf16 v[84:87], v[176:179], v[222:225], v[84:87]
	v_mfma_f32_16x16x32_bf16 v[76:79], v[168:171], v[230:233], v[76:79]
	v_mfma_f32_16x16x32_bf16 v[68:71], v[176:179], v[230:233], v[68:71]
	v_mfma_f32_16x16x32_bf16 v[120:123], v[180:183], v[202:205], v[120:123]
	v_mfma_f32_16x16x32_bf16 v[112:115], v[188:191], v[202:205], v[112:115]
	v_mfma_f32_16x16x32_bf16 v[104:107], v[180:183], v[210:213], v[104:107]
	v_mfma_f32_16x16x32_bf16 v[96:99], v[188:191], v[210:213], v[96:99]
	v_mfma_f32_16x16x32_bf16 v[88:91], v[180:183], v[218:221], v[88:91]
	v_mfma_f32_16x16x32_bf16 v[80:83], v[188:191], v[218:221], v[80:83]
	v_mfma_f32_16x16x32_bf16 v[72:75], v[180:183], v[226:229], v[72:75]
	v_mfma_f32_16x16x32_bf16 v[64:67], v[188:191], v[226:229], v[64:67]
	v_mfma_f32_16x16x32_bf16 v[120:123], v[184:187], v[206:209], v[120:123]
	v_mfma_f32_16x16x32_bf16 v[112:115], v[198:201], v[206:209], v[112:115]
	v_mfma_f32_16x16x32_bf16 v[104:107], v[184:187], v[214:217], v[104:107]
	v_mfma_f32_16x16x32_bf16 v[96:99], v[198:201], v[214:217], v[96:99]
	v_mfma_f32_16x16x32_bf16 v[88:91], v[184:187], v[222:225], v[88:91]
	v_mfma_f32_16x16x32_bf16 v[80:83], v[198:201], v[222:225], v[80:83]
	v_mfma_f32_16x16x32_bf16 v[72:75], v[184:187], v[230:233], v[72:75]
	v_mfma_f32_16x16x32_bf16 v[64:67], v[198:201], v[230:233], v[64:67]
	s_barrier
	s_add_i32 s6, s59, s26
	s_mov_b32 m0, s6
	ds_read_b128 v[202:205], v156 offset:16384
	ds_read_b128 v[206:209], v156 offset:17408
	ds_read_b128 v[210:213], v156 offset:18432
	ds_read_b128 v[214:217], v156 offset:19456
	ds_read_b128 v[218:221], v156 offset:20480
	ds_read_b128 v[222:225], v156 offset:21504
	ds_read_b128 v[226:229], v156 offset:22528
	ds_read_b128 v[230:233], v156 offset:23552
	global_load_lds_dwordx4 v132, s[52:53]
	s_add_i32 m0, s6, 0x2000
	s_add_u32 s6, s52, 0x40000
	s_addc_u32 s7, s53, 0
	s_add_i32 s73, s60, s26
	global_load_lds_dwordx4 v128, s[52:53]
	s_mov_b32 m0, s73
	s_nop 0
	global_load_lds_dwordx4 v132, s[6:7]
	s_add_i32 m0, s73, 0x2000
	s_nop 0
	global_load_lds_dwordx4 v128, s[6:7]
	s_mov_b32 m0, s27
	s_nop 0
	global_load_lds_dwordx4 v134, s[54:55]
	s_mov_b32 m0, s42
	s_nop 0
	global_load_lds_dwordx4 v130, s[54:55]
	s_waitcnt vmcnt(8)
	s_waitcnt lgkmcnt(0)
	s_barrier
	v_mfma_f32_16x16x32_bf16 v[60:63], v[144:147], v[202:205], v[60:63]
	v_mfma_f32_16x16x32_bf16 v[52:55], v[172:175], v[202:205], v[52:55]
	v_mfma_f32_16x16x32_bf16 v[44:47], v[144:147], v[210:213], v[44:47]
	v_mfma_f32_16x16x32_bf16 v[36:39], v[172:175], v[210:213], v[36:39]
	v_mfma_f32_16x16x32_bf16 v[28:31], v[144:147], v[218:221], v[28:31]
	v_mfma_f32_16x16x32_bf16 v[20:23], v[172:175], v[218:221], v[20:23]
	v_mfma_f32_16x16x32_bf16 v[12:15], v[144:147], v[226:229], v[12:15]
	v_mfma_f32_16x16x32_bf16 v[4:7], v[172:175], v[226:229], v[4:7]
	v_mfma_f32_16x16x32_bf16 v[60:63], v[168:171], v[206:209], v[60:63]
	v_mfma_f32_16x16x32_bf16 v[52:55], v[176:179], v[206:209], v[52:55]
	v_mfma_f32_16x16x32_bf16 v[44:47], v[168:171], v[214:217], v[44:47]
	v_mfma_f32_16x16x32_bf16 v[36:39], v[176:179], v[214:217], v[36:39]
	v_mfma_f32_16x16x32_bf16 v[28:31], v[168:171], v[222:225], v[28:31]
	v_mfma_f32_16x16x32_bf16 v[20:23], v[176:179], v[222:225], v[20:23]
	v_mfma_f32_16x16x32_bf16 v[12:15], v[168:171], v[230:233], v[12:15]
	v_mfma_f32_16x16x32_bf16 v[4:7], v[176:179], v[230:233], v[4:7]
	v_mfma_f32_16x16x32_bf16 v[56:59], v[180:183], v[202:205], v[56:59]
	v_mfma_f32_16x16x32_bf16 v[48:51], v[188:191], v[202:205], v[48:51]
	v_mfma_f32_16x16x32_bf16 v[40:43], v[180:183], v[210:213], v[40:43]
	v_mfma_f32_16x16x32_bf16 v[32:35], v[188:191], v[210:213], v[32:35]
	v_mfma_f32_16x16x32_bf16 v[24:27], v[180:183], v[218:221], v[24:27]
	v_mfma_f32_16x16x32_bf16 v[16:19], v[188:191], v[218:221], v[16:19]
	v_mfma_f32_16x16x32_bf16 v[8:11], v[180:183], v[226:229], v[8:11]
	v_mfma_f32_16x16x32_bf16 v[0:3], v[188:191], v[226:229], v[0:3]
	v_mfma_f32_16x16x32_bf16 v[56:59], v[184:187], v[206:209], v[56:59]
	v_mfma_f32_16x16x32_bf16 v[48:51], v[198:201], v[206:209], v[48:51]
	v_mfma_f32_16x16x32_bf16 v[40:43], v[184:187], v[214:217], v[40:43]
	v_mfma_f32_16x16x32_bf16 v[32:35], v[198:201], v[214:217], v[32:35]
	v_mfma_f32_16x16x32_bf16 v[24:27], v[184:187], v[222:225], v[24:27]
	v_mfma_f32_16x16x32_bf16 v[16:19], v[198:201], v[222:225], v[16:19]
	v_mfma_f32_16x16x32_bf16 v[8:11], v[184:187], v[230:233], v[8:11]
	v_mfma_f32_16x16x32_bf16 v[0:3], v[198:201], v[230:233], v[0:3]
	s_barrier
; #define PG8_STAGE(bufoff, gbase, voff) do { _Pragma("unroll") for (int _i = 0; _i < 2; ++_i) \
;         __builtin_amdgcn_global_load_lds((const unsigned*)((const char*)(gbase) + (voff)[_i]), (PG8_LAS unsigned*)(lds + (bufoff) + ldsw + _i * 8192), 16, 0, 0); } while (0)
; #define PG8_LDA(dst, b, h) do { _Pragma("unroll") for (int m = 0; m < 4; ++m) _Pragma("unroll") for (int k = 0; k < 2; ++k) dst[m][k] = *(const PG8_LAS bf16x8*)(lds + PG8_SA(b, h) + aoff + m * 2048 + k * 1024); } while (0)
; #define PG8_LDB(dst, b, h) do { _Pragma("unroll") for (int n = 0; n < 2; ++n) _Pragma("unroll") for (int k = 0; k < 2; ++k) dst[n][k] = *(const PG8_LAS bf16x8*)(lds + PG8_SB(b, h) + boff + n * 2048 + k * 1024); } while (0)
; #define PG8_MMA(ai, bj, At, Bt) do { __builtin_amdgcn_s_setprio(1); _Pragma("unroll") for (int m = 0; m < 4; ++m) _Pragma("unroll") for (int n = 0; n < 2; ++n) _Pragma("unroll") for (int k = 0; k < 2; ++k) \
;         acc[ai][bj][m][n] = __builtin_amdgcn_mfma_f32_16x16x32_bf16(Bt[n][k], At[m][k], acc[ai][bj][m][n], 0, 0, 0); __builtin_amdgcn_s_setprio(0); } while (0)
; #define PG8_WAIT_V(n) asm volatile("s_waitcnt vmcnt(" #n ")" ::: "memory")
; #define PG8_WAIT_L(n) asm volatile("s_waitcnt lgkmcnt(" #n ")" ::: "memory")
; #define PG8_BAR __builtin_amdgcn_s_barrier()
; #define PG8_SCHED __builtin_amdgcn_sched_barrier(0)
; template <class Epi, class Sched, bool ALIGN_EPI = false, bool SP2 = false>
; __device__ __forceinline__ void gemm_phase(PG8_LAS unsigned char* lds, const Gemm g, const Sched& S, const Epi& E) {
;     ...
;             PG8_LDB(B0, 1, 0); PG8_LDB(B1, 1, 1); PG8_SCHED; PG8_LDA(At, 1, 0); PG8_STAGE(PG8_SA(0, 1), a2 + hstep, voffA);
;             PG8_WAIT_V(8); PG8_WAIT_L(0); PG8_BAR; PG8_MMA(0, 0, At, B0); PG8_MMA(0, 1, At, B1); PG8_BAR; PG8_SCHED;
;             PG8_LDA(At, 1, 1); PG8_STAGE(PG8_SB(1, 0), b3, voffB); PG8_STAGE(PG8_SB(1, 1), b3 + hstep, voffB); PG8_STAGE(PG8_SA(1, 0), a3, voffA);
;             PG8_WAIT_V(8); PG8_WAIT_L(0); PG8_BAR; PG8_MMA(1, 0, At, B0); PG8_MMA(1, 1, At, B1); PG8_BAR; PG8_SCHED;
;     ...
;         }
;         if constexpr (ALIGN_EPI) { if (wr == 0) PG8_BAR; }
	s_add_i32 s73, 0, 0x18000
	v_add_u32_e32 v157, s73, v151
	s_add_i32 s76, 0, 0x1c000
	ds_read_b128 v[144:147], v157
	ds_read_b128 v[168:171], v157 offset:1024
	ds_read_b128 v[172:175], v157 offset:2048
	ds_read_b128 v[176:179], v157 offset:3072
	v_add_u32_e32 v157, s76, v151
	ds_read_b128 v[180:183], v157
	ds_read_b128 v[184:187], v157 offset:1024
	ds_read_b128 v[188:191], v157 offset:2048
	ds_read_b128 v[198:201], v157 offset:3072
	s_add_u32 s6, s54, 0x40000
	s_addc_u32 s7, s55, 0
	s_mov_b32 m0, s43
	ds_read_b128 v[202:205], v156 offset:32768
	ds_read_b128 v[206:209], v156 offset:33792
	ds_read_b128 v[210:213], v156 offset:34816
	ds_read_b128 v[214:217], v156 offset:35840
	ds_read_b128 v[218:221], v156 offset:36864
	ds_read_b128 v[222:225], v156 offset:37888
	ds_read_b128 v[226:229], v156 offset:38912
	ds_read_b128 v[230:233], v156 offset:39936
	global_load_lds_dwordx4 v134, s[6:7]
	s_mov_b32 m0, s56
	s_nop 0
	global_load_lds_dwordx4 v130, s[6:7]
	s_waitcnt vmcnt(8)
	s_waitcnt lgkmcnt(0)
	s_barrier
	v_mfma_f32_16x16x32_bf16 v[124:127], v[144:147], v[202:205], v[124:127]
	v_mfma_f32_16x16x32_bf16 v[116:119], v[172:175], v[202:205], v[116:119]
	v_mfma_f32_16x16x32_bf16 v[108:111], v[144:147], v[210:213], v[108:111]
	v_mfma_f32_16x16x32_bf16 v[100:103], v[172:175], v[210:213], v[100:103]
	v_mfma_f32_16x16x32_bf16 v[92:95], v[144:147], v[218:221], v[92:95]
	v_mfma_f32_16x16x32_bf16 v[84:87], v[172:175], v[218:221], v[84:87]
	v_mfma_f32_16x16x32_bf16 v[76:79], v[144:147], v[226:229], v[76:79]
	v_mfma_f32_16x16x32_bf16 v[68:71], v[172:175], v[226:229], v[68:71]
	v_mfma_f32_16x16x32_bf16 v[124:127], v[168:171], v[206:209], v[124:127]
	v_mfma_f32_16x16x32_bf16 v[116:119], v[176:179], v[206:209], v[116:119]
	v_mfma_f32_16x16x32_bf16 v[108:111], v[168:171], v[214:217], v[108:111]
	v_mfma_f32_16x16x32_bf16 v[100:103], v[176:179], v[214:217], v[100:103]
	v_mfma_f32_16x16x32_bf16 v[92:95], v[168:171], v[222:225], v[92:95]
	v_mfma_f32_16x16x32_bf16 v[84:87], v[176:179], v[222:225], v[84:87]
	v_mfma_f32_16x16x32_bf16 v[76:79], v[168:171], v[230:233], v[76:79]
	v_mfma_f32_16x16x32_bf16 v[68:71], v[176:179], v[230:233], v[68:71]
	v_mfma_f32_16x16x32_bf16 v[120:123], v[180:183], v[202:205], v[120:123]
	v_mfma_f32_16x16x32_bf16 v[112:115], v[188:191], v[202:205], v[112:115]
	v_mfma_f32_16x16x32_bf16 v[104:107], v[180:183], v[210:213], v[104:107]
	v_mfma_f32_16x16x32_bf16 v[96:99], v[188:191], v[210:213], v[96:99]
	v_mfma_f32_16x16x32_bf16 v[88:91], v[180:183], v[218:221], v[88:91]
	v_mfma_f32_16x16x32_bf16 v[80:83], v[188:191], v[218:221], v[80:83]
	v_mfma_f32_16x16x32_bf16 v[72:75], v[180:183], v[226:229], v[72:75]
	v_mfma_f32_16x16x32_bf16 v[64:67], v[188:191], v[226:229], v[64:67]
	v_mfma_f32_16x16x32_bf16 v[120:123], v[184:187], v[206:209], v[120:123]
	v_mfma_f32_16x16x32_bf16 v[112:115], v[198:201], v[206:209], v[112:115]
	v_mfma_f32_16x16x32_bf16 v[104:107], v[184:187], v[214:217], v[104:107]
	v_mfma_f32_16x16x32_bf16 v[96:99], v[198:201], v[214:217], v[96:99]
	v_mfma_f32_16x16x32_bf16 v[88:91], v[184:187], v[222:225], v[88:91]
	v_mfma_f32_16x16x32_bf16 v[80:83], v[198:201], v[222:225], v[80:83]
	v_mfma_f32_16x16x32_bf16 v[72:75], v[184:187], v[230:233], v[72:75]
	v_mfma_f32_16x16x32_bf16 v[64:67], v[198:201], v[230:233], v[64:67]
	s_barrier
	s_add_i32 s6, s73, s26
	s_add_u32 s98, s52, 0x80
	s_addc_u32 s99, s53, 0
	s_add_u32 s100, s54, 0x80
	s_addc_u32 s101, s55, 0
	s_mov_b32 m0, s6
	ds_read_b128 v[202:205], v156 offset:49152
	ds_read_b128 v[206:209], v156 offset:50176
	ds_read_b128 v[210:213], v156 offset:51200
	ds_read_b128 v[214:217], v156 offset:52224
	ds_read_b128 v[218:221], v156 offset:53248
	ds_read_b128 v[222:225], v156 offset:54272
	ds_read_b128 v[226:229], v156 offset:55296
	ds_read_b128 v[230:233], v156 offset:56320
	global_load_lds_dwordx4 v132, s[98:99]
	s_add_i32 m0, s6, 0x2000
	s_add_u32 s6, s52, 0x40080
	s_addc_u32 s7, s53, 0
	s_add_i32 s52, s76, s26
	global_load_lds_dwordx4 v128, s[98:99]
	s_mov_b32 m0, s52
	s_nop 0
	global_load_lds_dwordx4 v132, s[6:7]
	s_add_i32 m0, s52, 0x2000
	s_nop 0
	global_load_lds_dwordx4 v128, s[6:7]
	s_mov_b32 m0, s57
	s_nop 0
	global_load_lds_dwordx4 v134, s[100:101]
	s_mov_b32 m0, s58
	s_nop 0
	global_load_lds_dwordx4 v130, s[100:101]
	s_waitcnt vmcnt(8)
	s_waitcnt lgkmcnt(0)
	s_barrier
	v_mfma_f32_16x16x32_bf16 v[60:63], v[144:147], v[202:205], v[60:63]
	v_mfma_f32_16x16x32_bf16 v[52:55], v[172:175], v[202:205], v[52:55]
	v_mfma_f32_16x16x32_bf16 v[44:47], v[144:147], v[210:213], v[44:47]
	v_mfma_f32_16x16x32_bf16 v[36:39], v[172:175], v[210:213], v[36:39]
	v_mfma_f32_16x16x32_bf16 v[28:31], v[144:147], v[218:221], v[28:31]
	v_mfma_f32_16x16x32_bf16 v[20:23], v[172:175], v[218:221], v[20:23]
	v_mfma_f32_16x16x32_bf16 v[12:15], v[144:147], v[226:229], v[12:15]
	v_mfma_f32_16x16x32_bf16 v[4:7], v[172:175], v[226:229], v[4:7]
	v_mfma_f32_16x16x32_bf16 v[60:63], v[168:171], v[206:209], v[60:63]
	v_mfma_f32_16x16x32_bf16 v[52:55], v[176:179], v[206:209], v[52:55]
	v_mfma_f32_16x16x32_bf16 v[44:47], v[168:171], v[214:217], v[44:47]
	v_mfma_f32_16x16x32_bf16 v[36:39], v[176:179], v[214:217], v[36:39]
	v_mfma_f32_16x16x32_bf16 v[28:31], v[168:171], v[222:225], v[28:31]
	v_mfma_f32_16x16x32_bf16 v[20:23], v[176:179], v[222:225], v[20:23]
	v_mfma_f32_16x16x32_bf16 v[12:15], v[168:171], v[230:233], v[12:15]
	v_mfma_f32_16x16x32_bf16 v[4:7], v[176:179], v[230:233], v[4:7]
	v_mfma_f32_16x16x32_bf16 v[56:59], v[180:183], v[202:205], v[56:59]
	v_mfma_f32_16x16x32_bf16 v[48:51], v[188:191], v[202:205], v[48:51]
	v_mfma_f32_16x16x32_bf16 v[40:43], v[180:183], v[210:213], v[40:43]
	v_mfma_f32_16x16x32_bf16 v[32:35], v[188:191], v[210:213], v[32:35]
	v_mfma_f32_16x16x32_bf16 v[24:27], v[180:183], v[218:221], v[24:27]
	v_mfma_f32_16x16x32_bf16 v[16:19], v[188:191], v[218:221], v[16:19]
	v_mfma_f32_16x16x32_bf16 v[8:11], v[180:183], v[226:229], v[8:11]
	v_mfma_f32_16x16x32_bf16 v[0:3], v[188:191], v[226:229], v[0:3]
	v_mfma_f32_16x16x32_bf16 v[56:59], v[184:187], v[206:209], v[56:59]
	v_mfma_f32_16x16x32_bf16 v[48:51], v[198:201], v[206:209], v[48:51]
	v_mfma_f32_16x16x32_bf16 v[40:43], v[184:187], v[214:217], v[40:43]
	v_mfma_f32_16x16x32_bf16 v[32:35], v[198:201], v[214:217], v[32:35]
	v_mfma_f32_16x16x32_bf16 v[24:27], v[184:187], v[222:225], v[24:27]
	v_mfma_f32_16x16x32_bf16 v[16:19], v[198:201], v[222:225], v[16:19]
	v_mfma_f32_16x16x32_bf16 v[8:11], v[184:187], v[230:233], v[8:11]
	v_mfma_f32_16x16x32_bf16 v[0:3], v[198:201], v[230:233], v[0:3]
	s_barrier
	s_add_i32 s72, s72, 2
	s_add_u32 s50, s50, 0x100
	s_addc_u32 s51, s51, 0
	s_add_u32 s75, s75, 0x100
	s_addc_u32 s33, s33, 0
	s_cmp_gt_u32 s72, 13
	s_cbranch_scc0 .LBB0_1822
	v_readlane_b32 s74, v243, 57
	s_and_b64 vcc, exec, s[34:35]
	v_readlane_b32 s75, v243, 58
	s_cbranch_vccz .LBB0_1825
	s_barrier

; #define PG8_STAGE(bufoff, gbase, voff) do { _Pragma("unroll") for (int _i = 0; _i < 2; ++_i) \
;         __builtin_amdgcn_global_load_lds((const unsigned*)((const char*)(gbase) + (voff)[_i]), (PG8_LAS unsigned*)(lds + (bufoff) + ldsw + _i * 8192), 16, 0, 0); } while (0)
; #define PG8_LDA(dst, b, h) do { _Pragma("unroll") for (int m = 0; m < 4; ++m) _Pragma("unroll") for (int k = 0; k < 2; ++k) dst[m][k] = *(const PG8_LAS bf16x8*)(lds + PG8_SA(b, h) + aoff + m * 2048 + k * 1024); } while (0)
; #define PG8_LDB(dst, b, h) do { _Pragma("unroll") for (int n = 0; n < 2; ++n) _Pragma("unroll") for (int k = 0; k < 2; ++k) dst[n][k] = *(const PG8_LAS bf16x8*)(lds + PG8_SB(b, h) + boff + n * 2048 + k * 1024); } while (0)
; #define PG8_MMA(ai, bj, At, Bt) do { __builtin_amdgcn_s_setprio(1); _Pragma("unroll") for (int m = 0; m < 4; ++m) _Pragma("unroll") for (int n = 0; n < 2; ++n) _Pragma("unroll") for (int k = 0; k < 2; ++k) \
;         acc[ai][bj][m][n] = __builtin_amdgcn_mfma_f32_16x16x32_bf16(Bt[n][k], At[m][k], acc[ai][bj][m][n], 0, 0, 0); __builtin_amdgcn_s_setprio(0); } while (0)
; #define PG8_WAIT_V(n) asm volatile("s_waitcnt vmcnt(" #n ")" ::: "memory")
; #define PG8_WAIT_L(n) asm volatile("s_waitcnt lgkmcnt(" #n ")" ::: "memory")
; template <class Epi, class Sched, bool ALIGN_EPI = false, bool SP2 = false>
; __device__ __forceinline__ void gemm_phase(PG8_LAS unsigned char* lds, const Gemm g, const Sched& S, const Epi& E) {
;     ...
;             const bool last = (t == nt - 2);
;             const char* a1 = cA + (size_t)(t + 1) * kstep;
;             const char* a2 = last ? nA : cA + (size_t)(t + 2) * kstep; const char* b2 = last ? nB : cB + (size_t)(t + 2) * kstep;
;             const char* a3 = a2 + kstep; const char* b3 = b2 + kstep;
;             if (last && has_next) S.a_ready(nxt);
;             if constexpr (SP2) {
;             PG8_LDB(B0, 0, 0); PG8_LDB(B1, 0, 1); PG8_SCHED; PG8_LDA(At, 0, 0); PG8_STAGE(PG8_SA(1, 1), a1 + hstep, voffA);
;             PG8_WAIT_V(8); PG8_WAIT_L(0); PG8_BAR; PG8_MMA(0, 0, At, B0); PG8_MMA(0, 1, At, B1); PG8_BAR; PG8_SCHED;
;             PG8_LDA(At, 0, 1); PG8_STAGE(PG8_SB(0, 0), b2, voffB); PG8_STAGE(PG8_SB(0, 1), b2 + hstep, voffB); PG8_STAGE(PG8_SA(0, 0), a2, voffA);
;             PG8_WAIT_V(8); PG8_WAIT_L(0); PG8_BAR; PG8_MMA(1, 0, At, B0); PG8_MMA(1, 1, At, B1); PG8_BAR; PG8_SCHED;
.LBB0_1935:
	ds_read_b128 v[144:147], v153
	ds_read_b128 v[168:171], v153 offset:1024
	ds_read_b128 v[172:175], v153 offset:2048
	ds_read_b128 v[176:179], v153 offset:3072
	ds_read_b128 v[180:183], v154
	ds_read_b128 v[184:187], v154 offset:1024
	ds_read_b128 v[188:191], v154 offset:2048
	ds_read_b128 v[198:201], v154 offset:3072
	s_add_u32 s50, s48, 0x100
	s_addc_u32 s51, s49, 0
	s_cmp_eq_u32 s72, 40
	s_cselect_b32 s55, s41, s51
	s_cselect_b32 s54, s40, s50
	s_cselect_b32 s53, s47, s77
	s_cselect_b32 s52, s46, s33
	s_add_i32 m0, s58, 0xc000
	ds_read_b128 v[202:205], v155
	ds_read_b128 v[206:209], v155 offset:1024
	ds_read_b128 v[210:213], v155 offset:2048
	ds_read_b128 v[214:217], v155 offset:3072
	ds_read_b128 v[218:221], v155 offset:4096
	ds_read_b128 v[222:225], v155 offset:5120
	ds_read_b128 v[226:229], v155 offset:6144
	ds_read_b128 v[230:233], v155 offset:7168
	global_load_lds_dwordx4 v136, s[48:49]
	s_add_i32 m0, s58, 0xe000
	s_nop 0
	global_load_lds_dwordx4 v138, s[48:49]
	s_waitcnt vmcnt(8)
	s_waitcnt lgkmcnt(0)
	s_barrier
	v_mfma_f32_16x16x32_bf16 v[124:127], v[144:147], v[202:205], v[124:127]
	v_mfma_f32_16x16x32_bf16 v[120:123], v[172:175], v[202:205], v[120:123]
	v_mfma_f32_16x16x32_bf16 v[108:111], v[144:147], v[210:213], v[108:111]
	v_mfma_f32_16x16x32_bf16 v[104:107], v[172:175], v[210:213], v[104:107]
	v_mfma_f32_16x16x32_bf16 v[92:95], v[144:147], v[218:221], v[92:95]
	v_mfma_f32_16x16x32_bf16 v[88:91], v[172:175], v[218:221], v[88:91]
	v_mfma_f32_16x16x32_bf16 v[76:79], v[144:147], v[226:229], v[76:79]
	v_mfma_f32_16x16x32_bf16 v[72:75], v[172:175], v[226:229], v[72:75]
	v_mfma_f32_16x16x32_bf16 v[124:127], v[168:171], v[206:209], v[124:127]
	v_mfma_f32_16x16x32_bf16 v[120:123], v[176:179], v[206:209], v[120:123]
	v_mfma_f32_16x16x32_bf16 v[108:111], v[168:171], v[214:217], v[108:111]
	v_mfma_f32_16x16x32_bf16 v[104:107], v[176:179], v[214:217], v[104:107]
	v_mfma_f32_16x16x32_bf16 v[92:95], v[168:171], v[222:225], v[92:95]
	v_mfma_f32_16x16x32_bf16 v[88:91], v[176:179], v[222:225], v[88:91]
	v_mfma_f32_16x16x32_bf16 v[76:79], v[168:171], v[230:233], v[76:79]
	v_mfma_f32_16x16x32_bf16 v[72:75], v[176:179], v[230:233], v[72:75]
	v_mfma_f32_16x16x32_bf16 v[116:119], v[180:183], v[202:205], v[116:119]
	v_mfma_f32_16x16x32_bf16 v[112:115], v[188:191], v[202:205], v[112:115]
	v_mfma_f32_16x16x32_bf16 v[100:103], v[180:183], v[210:213], v[100:103]
	v_mfma_f32_16x16x32_bf16 v[96:99], v[188:191], v[210:213], v[96:99]
	v_mfma_f32_16x16x32_bf16 v[84:87], v[180:183], v[218:221], v[84:87]
	v_mfma_f32_16x16x32_bf16 v[80:83], v[188:191], v[218:221], v[80:83]
	v_mfma_f32_16x16x32_bf16 v[68:71], v[180:183], v[226:229], v[68:71]
	v_mfma_f32_16x16x32_bf16 v[64:67], v[188:191], v[226:229], v[64:67]
	v_mfma_f32_16x16x32_bf16 v[116:119], v[184:187], v[206:209], v[116:119]
	v_mfma_f32_16x16x32_bf16 v[112:115], v[198:201], v[206:209], v[112:115]
	v_mfma_f32_16x16x32_bf16 v[100:103], v[184:187], v[214:217], v[100:103]
	v_mfma_f32_16x16x32_bf16 v[96:99], v[198:201], v[214:217], v[96:99]
	v_mfma_f32_16x16x32_bf16 v[84:87], v[184:187], v[222:225], v[84:87]
	v_mfma_f32_16x16x32_bf16 v[80:83], v[198:201], v[222:225], v[80:83]
	v_mfma_f32_16x16x32_bf16 v[68:71], v[184:187], v[230:233], v[68:71]
	v_mfma_f32_16x16x32_bf16 v[64:67], v[198:201], v[230:233], v[64:67]
	s_barrier
	s_add_i32 s6, s26, s57
	s_mov_b32 m0, s6
	ds_read_b128 v[202:205], v155 offset:16384
	ds_read_b128 v[206:209], v155 offset:17408
	ds_read_b128 v[210:213], v155 offset:18432
	ds_read_b128 v[214:217], v155 offset:19456
	ds_read_b128 v[218:221], v155 offset:20480
	ds_read_b128 v[222:225], v155 offset:21504
	ds_read_b128 v[226:229], v155 offset:22528
	ds_read_b128 v[230:233], v155 offset:23552
	global_load_lds_dwordx4 v130, s[52:53]
	s_add_i32 m0, s6, 0x2000
	s_add_u32 s6, s52, 0xb0000
	s_addc_u32 s7, s53, 0
	s_add_i32 s48, s74, s57
	global_load_lds_dwordx4 v134, s[52:53]
	s_mov_b32 m0, s48
	s_nop 0
	global_load_lds_dwordx4 v130, s[6:7]
	s_add_i32 m0, s48, 0x2000
	s_nop 0
	global_load_lds_dwordx4 v134, s[6:7]
	s_mov_b32 m0, s58
	s_nop 0
	global_load_lds_dwordx4 v128, s[54:55]
	s_mov_b32 m0, s59
	s_nop 0
	global_load_lds_dwordx4 v132, s[54:55]
	s_waitcnt vmcnt(8)
	s_waitcnt lgkmcnt(0)
	s_barrier
	v_mfma_f32_16x16x32_bf16 v[60:63], v[144:147], v[202:205], v[60:63]
	v_mfma_f32_16x16x32_bf16 v[56:59], v[172:175], v[202:205], v[56:59]
	v_mfma_f32_16x16x32_bf16 v[44:47], v[144:147], v[210:213], v[44:47]
	v_mfma_f32_16x16x32_bf16 v[40:43], v[172:175], v[210:213], v[40:43]
	v_mfma_f32_16x16x32_bf16 v[28:31], v[144:147], v[218:221], v[28:31]
	v_mfma_f32_16x16x32_bf16 v[24:27], v[172:175], v[218:221], v[24:27]
	v_mfma_f32_16x16x32_bf16 v[12:15], v[144:147], v[226:229], v[12:15]
	v_mfma_f32_16x16x32_bf16 v[8:11], v[172:175], v[226:229], v[8:11]
	v_mfma_f32_16x16x32_bf16 v[60:63], v[168:171], v[206:209], v[60:63]
	v_mfma_f32_16x16x32_bf16 v[56:59], v[176:179], v[206:209], v[56:59]
	v_mfma_f32_16x16x32_bf16 v[44:47], v[168:171], v[214:217], v[44:47]
	v_mfma_f32_16x16x32_bf16 v[40:43], v[176:179], v[214:217], v[40:43]
	v_mfma_f32_16x16x32_bf16 v[28:31], v[168:171], v[222:225], v[28:31]
	v_mfma_f32_16x16x32_bf16 v[24:27], v[176:179], v[222:225], v[24:27]
	v_mfma_f32_16x16x32_bf16 v[12:15], v[168:171], v[230:233], v[12:15]
	v_mfma_f32_16x16x32_bf16 v[8:11], v[176:179], v[230:233], v[8:11]
	v_mfma_f32_16x16x32_bf16 v[52:55], v[180:183], v[202:205], v[52:55]
	v_mfma_f32_16x16x32_bf16 v[48:51], v[188:191], v[202:205], v[48:51]
	v_mfma_f32_16x16x32_bf16 v[36:39], v[180:183], v[210:213], v[36:39]
	v_mfma_f32_16x16x32_bf16 v[32:35], v[188:191], v[210:213], v[32:35]
	v_mfma_f32_16x16x32_bf16 v[20:23], v[180:183], v[218:221], v[20:23]
	v_mfma_f32_16x16x32_bf16 v[16:19], v[188:191], v[218:221], v[16:19]
	v_mfma_f32_16x16x32_bf16 v[4:7], v[180:183], v[226:229], v[4:7]
	v_mfma_f32_16x16x32_bf16 v[0:3], v[188:191], v[226:229], v[0:3]
	v_mfma_f32_16x16x32_bf16 v[52:55], v[184:187], v[206:209], v[52:55]
	v_mfma_f32_16x16x32_bf16 v[48:51], v[198:201], v[206:209], v[48:51]
	v_mfma_f32_16x16x32_bf16 v[36:39], v[184:187], v[214:217], v[36:39]
	v_mfma_f32_16x16x32_bf16 v[32:35], v[198:201], v[214:217], v[32:35]
	v_mfma_f32_16x16x32_bf16 v[20:23], v[184:187], v[222:225], v[20:23]
	v_mfma_f32_16x16x32_bf16 v[16:19], v[198:201], v[222:225], v[16:19]
	v_mfma_f32_16x16x32_bf16 v[4:7], v[184:187], v[230:233], v[4:7]
	v_mfma_f32_16x16x32_bf16 v[0:3], v[198:201], v[230:233], v[0:3]
	s_barrier
; #define PG8_STAGE(bufoff, gbase, voff) do { _Pragma("unroll") for (int _i = 0; _i < 2; ++_i) \
;         __builtin_amdgcn_global_load_lds((const unsigned*)((const char*)(gbase) + (voff)[_i]), (PG8_LAS unsigned*)(lds + (bufoff) + ldsw + _i * 8192), 16, 0, 0); } while (0)
; #define PG8_LDA(dst, b, h) do { _Pragma("unroll") for (int m = 0; m < 4; ++m) _Pragma("unroll") for (int k = 0; k < 2; ++k) dst[m][k] = *(const PG8_LAS bf16x8*)(lds + PG8_SA(b, h) + aoff + m * 2048 + k * 1024); } while (0)
; #define PG8_LDB(dst, b, h) do { _Pragma("unroll") for (int n = 0; n < 2; ++n) _Pragma("unroll") for (int k = 0; k < 2; ++k) dst[n][k] = *(const PG8_LAS bf16x8*)(lds + PG8_SB(b, h) + boff + n * 2048 + k * 1024); } while (0)
; #define PG8_MMA(ai, bj, At, Bt) do { __builtin_amdgcn_s_setprio(1); _Pragma("unroll") for (int m = 0; m < 4; ++m) _Pragma("unroll") for (int n = 0; n < 2; ++n) _Pragma("unroll") for (int k = 0; k < 2; ++k) \
;         acc[ai][bj][m][n] = __builtin_amdgcn_mfma_f32_16x16x32_bf16(Bt[n][k], At[m][k], acc[ai][bj][m][n], 0, 0, 0); __builtin_amdgcn_s_setprio(0); } while (0)
; #define PG8_WAIT_V(n) asm volatile("s_waitcnt vmcnt(" #n ")" ::: "memory")
; #define PG8_WAIT_L(n) asm volatile("s_waitcnt lgkmcnt(" #n ")" ::: "memory")
; #define PG8_BAR __builtin_amdgcn_s_barrier()
; #define PG8_SCHED __builtin_amdgcn_sched_barrier(0)
; template <class Epi, class Sched, bool ALIGN_EPI = false, bool SP2 = false>
; __device__ __forceinline__ void gemm_phase(PG8_LAS unsigned char* lds, const Gemm g, const Sched& S, const Epi& E) {
;     ...
;             PG8_LDB(B0, 1, 0); PG8_LDB(B1, 1, 1); PG8_SCHED; PG8_LDA(At, 1, 0); PG8_STAGE(PG8_SA(0, 1), a2 + hstep, voffA);
;             PG8_WAIT_V(8); PG8_WAIT_L(0); PG8_BAR; PG8_MMA(0, 0, At, B0); PG8_MMA(0, 1, At, B1); PG8_BAR; PG8_SCHED;
;             PG8_LDA(At, 1, 1); PG8_STAGE(PG8_SB(1, 0), b3, voffB); PG8_STAGE(PG8_SB(1, 1), b3 + hstep, voffB); PG8_STAGE(PG8_SA(1, 0), a3, voffA);
;             PG8_WAIT_V(8); PG8_WAIT_L(0); PG8_BAR; PG8_MMA(1, 0, At, B0); PG8_MMA(1, 1, At, B1); PG8_BAR; PG8_SCHED;
;     ...
;         }
;         if constexpr (ALIGN_EPI) { if (wr == 0) PG8_BAR; }
	s_add_i32 s48, 0, 0x18000
	v_add_u32_e32 v157, s48, v151
	s_add_i32 s49, 0, 0x1c000
	ds_read_b128 v[144:147], v157
	ds_read_b128 v[168:171], v157 offset:1024
	ds_read_b128 v[172:175], v157 offset:2048
	ds_read_b128 v[176:179], v157 offset:3072
	v_add_u32_e32 v157, s49, v151
	ds_read_b128 v[180:183], v157
	ds_read_b128 v[184:187], v157 offset:1024
	ds_read_b128 v[188:191], v157 offset:2048
	ds_read_b128 v[198:201], v157 offset:3072
	s_add_u32 s6, s54, 0xb0000
	s_addc_u32 s7, s55, 0
	s_mov_b32 m0, s60
	ds_read_b128 v[202:205], v155 offset:32768
	ds_read_b128 v[206:209], v155 offset:33792
	ds_read_b128 v[210:213], v155 offset:34816
	ds_read_b128 v[214:217], v155 offset:35840
	ds_read_b128 v[218:221], v155 offset:36864
	ds_read_b128 v[222:225], v155 offset:37888
	ds_read_b128 v[226:229], v155 offset:38912
	ds_read_b128 v[230:233], v155 offset:39936
	global_load_lds_dwordx4 v128, s[6:7]
	s_mov_b32 m0, s61
	s_nop 0
	global_load_lds_dwordx4 v132, s[6:7]
	s_waitcnt vmcnt(8)
	s_waitcnt lgkmcnt(0)
	s_barrier
	v_mfma_f32_16x16x32_bf16 v[124:127], v[144:147], v[202:205], v[124:127]
	v_mfma_f32_16x16x32_bf16 v[120:123], v[172:175], v[202:205], v[120:123]
	v_mfma_f32_16x16x32_bf16 v[108:111], v[144:147], v[210:213], v[108:111]
	v_mfma_f32_16x16x32_bf16 v[104:107], v[172:175], v[210:213], v[104:107]
	v_mfma_f32_16x16x32_bf16 v[92:95], v[144:147], v[218:221], v[92:95]
	v_mfma_f32_16x16x32_bf16 v[88:91], v[172:175], v[218:221], v[88:91]
	v_mfma_f32_16x16x32_bf16 v[76:79], v[144:147], v[226:229], v[76:79]
	v_mfma_f32_16x16x32_bf16 v[72:75], v[172:175], v[226:229], v[72:75]
	v_mfma_f32_16x16x32_bf16 v[124:127], v[168:171], v[206:209], v[124:127]
	v_mfma_f32_16x16x32_bf16 v[120:123], v[176:179], v[206:209], v[120:123]
	v_mfma_f32_16x16x32_bf16 v[108:111], v[168:171], v[214:217], v[108:111]
	v_mfma_f32_16x16x32_bf16 v[104:107], v[176:179], v[214:217], v[104:107]
	v_mfma_f32_16x16x32_bf16 v[92:95], v[168:171], v[222:225], v[92:95]
	v_mfma_f32_16x16x32_bf16 v[88:91], v[176:179], v[222:225], v[88:91]
	v_mfma_f32_16x16x32_bf16 v[76:79], v[168:171], v[230:233], v[76:79]
	v_mfma_f32_16x16x32_bf16 v[72:75], v[176:179], v[230:233], v[72:75]
	v_mfma_f32_16x16x32_bf16 v[116:119], v[180:183], v[202:205], v[116:119]
	v_mfma_f32_16x16x32_bf16 v[112:115], v[188:191], v[202:205], v[112:115]
	v_mfma_f32_16x16x32_bf16 v[100:103], v[180:183], v[210:213], v[100:103]
	v_mfma_f32_16x16x32_bf16 v[96:99], v[188:191], v[210:213], v[96:99]
	v_mfma_f32_16x16x32_bf16 v[84:87], v[180:183], v[218:221], v[84:87]
	v_mfma_f32_16x16x32_bf16 v[80:83], v[188:191], v[218:221], v[80:83]
	v_mfma_f32_16x16x32_bf16 v[68:71], v[180:183], v[226:229], v[68:71]
	v_mfma_f32_16x16x32_bf16 v[64:67], v[188:191], v[226:229], v[64:67]
	v_mfma_f32_16x16x32_bf16 v[116:119], v[184:187], v[206:209], v[116:119]
	v_mfma_f32_16x16x32_bf16 v[112:115], v[198:201], v[206:209], v[112:115]
	v_mfma_f32_16x16x32_bf16 v[100:103], v[184:187], v[214:217], v[100:103]
	v_mfma_f32_16x16x32_bf16 v[96:99], v[198:201], v[214:217], v[96:99]
	v_mfma_f32_16x16x32_bf16 v[84:87], v[184:187], v[222:225], v[84:87]
	v_mfma_f32_16x16x32_bf16 v[80:83], v[198:201], v[222:225], v[80:83]
	v_mfma_f32_16x16x32_bf16 v[68:71], v[184:187], v[230:233], v[68:71]
	v_mfma_f32_16x16x32_bf16 v[64:67], v[198:201], v[230:233], v[64:67]
	s_barrier
	s_add_i32 s6, s48, s57
	s_add_u32 s98, s52, 0x80
	s_addc_u32 s99, s53, 0
	s_add_u32 s100, s54, 0x80
	s_addc_u32 s101, s55, 0
	s_mov_b32 m0, s6
	ds_read_b128 v[202:205], v155 offset:49152
	ds_read_b128 v[206:209], v155 offset:50176
	ds_read_b128 v[210:213], v155 offset:51200
	ds_read_b128 v[214:217], v155 offset:52224
	ds_read_b128 v[218:221], v155 offset:53248
	ds_read_b128 v[222:225], v155 offset:54272
	ds_read_b128 v[226:229], v155 offset:55296
	ds_read_b128 v[230:233], v155 offset:56320
	global_load_lds_dwordx4 v130, s[98:99]
	s_add_i32 m0, s6, 0x2000
	s_add_u32 s6, s52, 0xb0080
	s_addc_u32 s7, s53, 0
	s_add_i32 s48, s49, s57
	global_load_lds_dwordx4 v134, s[98:99]
	s_mov_b32 m0, s48
	s_nop 0
	global_load_lds_dwordx4 v130, s[6:7]
	s_add_i32 m0, s48, 0x2000
	s_nop 0
	global_load_lds_dwordx4 v134, s[6:7]
	s_mov_b32 m0, s76
	s_nop 0
	global_load_lds_dwordx4 v128, s[100:101]
	s_mov_b32 m0, s4
	s_nop 0
	global_load_lds_dwordx4 v132, s[100:101]
	s_waitcnt vmcnt(8)
	s_waitcnt lgkmcnt(0)
	s_barrier
	v_mfma_f32_16x16x32_bf16 v[60:63], v[144:147], v[202:205], v[60:63]
	v_mfma_f32_16x16x32_bf16 v[56:59], v[172:175], v[202:205], v[56:59]
	v_mfma_f32_16x16x32_bf16 v[44:47], v[144:147], v[210:213], v[44:47]
	v_mfma_f32_16x16x32_bf16 v[40:43], v[172:175], v[210:213], v[40:43]
	v_mfma_f32_16x16x32_bf16 v[28:31], v[144:147], v[218:221], v[28:31]
	v_mfma_f32_16x16x32_bf16 v[24:27], v[172:175], v[218:221], v[24:27]
	v_mfma_f32_16x16x32_bf16 v[12:15], v[144:147], v[226:229], v[12:15]
	v_mfma_f32_16x16x32_bf16 v[8:11], v[172:175], v[226:229], v[8:11]
	v_mfma_f32_16x16x32_bf16 v[60:63], v[168:171], v[206:209], v[60:63]
	v_mfma_f32_16x16x32_bf16 v[56:59], v[176:179], v[206:209], v[56:59]
	v_mfma_f32_16x16x32_bf16 v[44:47], v[168:171], v[214:217], v[44:47]
	v_mfma_f32_16x16x32_bf16 v[40:43], v[176:179], v[214:217], v[40:43]
	v_mfma_f32_16x16x32_bf16 v[28:31], v[168:171], v[222:225], v[28:31]
	v_mfma_f32_16x16x32_bf16 v[24:27], v[176:179], v[222:225], v[24:27]
	v_mfma_f32_16x16x32_bf16 v[12:15], v[168:171], v[230:233], v[12:15]
	v_mfma_f32_16x16x32_bf16 v[8:11], v[176:179], v[230:233], v[8:11]
	v_mfma_f32_16x16x32_bf16 v[52:55], v[180:183], v[202:205], v[52:55]
	v_mfma_f32_16x16x32_bf16 v[48:51], v[188:191], v[202:205], v[48:51]
	v_mfma_f32_16x16x32_bf16 v[36:39], v[180:183], v[210:213], v[36:39]
	v_mfma_f32_16x16x32_bf16 v[32:35], v[188:191], v[210:213], v[32:35]
	v_mfma_f32_16x16x32_bf16 v[20:23], v[180:183], v[218:221], v[20:23]
	v_mfma_f32_16x16x32_bf16 v[16:19], v[188:191], v[218:221], v[16:19]
	v_mfma_f32_16x16x32_bf16 v[4:7], v[180:183], v[226:229], v[4:7]
	v_mfma_f32_16x16x32_bf16 v[0:3], v[188:191], v[226:229], v[0:3]
	v_mfma_f32_16x16x32_bf16 v[52:55], v[184:187], v[206:209], v[52:55]
	v_mfma_f32_16x16x32_bf16 v[48:51], v[198:201], v[206:209], v[48:51]
	v_mfma_f32_16x16x32_bf16 v[36:39], v[184:187], v[214:217], v[36:39]
	v_mfma_f32_16x16x32_bf16 v[32:35], v[198:201], v[214:217], v[32:35]
	v_mfma_f32_16x16x32_bf16 v[20:23], v[184:187], v[222:225], v[20:23]
	v_mfma_f32_16x16x32_bf16 v[16:19], v[198:201], v[222:225], v[16:19]
	v_mfma_f32_16x16x32_bf16 v[4:7], v[184:187], v[230:233], v[4:7]
	v_mfma_f32_16x16x32_bf16 v[0:3], v[198:201], v[230:233], v[0:3]
	s_barrier
	s_add_i32 s72, s72, 2
	s_add_u32 s33, s33, 0x100
	s_addc_u32 s77, s77, 0
	s_cmp_gt_u32 s72, 41
	s_mov_b64 s[48:49], s[50:51]
	s_cbranch_scc0 .LBB0_1935
	s_and_b64 vcc, exec, s[38:39]
	s_cbranch_vccz .LBB0_1938
	s_barrier
